# phase-5 narrow-GEMM epilogue stores (decay, a/dir records, gate) also widened to dwordx4 via permlane32_swap pairs; counted vmcnt waits re-derived
# speedup vs baseline: 1.0374x; 1.0125x over previous
; __device__ __forceinline__ float sigm(float x) { return __builtin_amdgcn_rcpf(1.f + __builtin_amdgcn_exp2f(-LOG2E * x)); }
; __device__ __forceinline__ void epi_decay(const f32x16 (&acc)[2][2], int nbase, int tbase, int M, const float* w0, u16* DIR) {
;     ...
; #pragma unroll
;   for (int tb = 0; tb < 2; ++tb) {
;     const int tok = tbase + tb * 32 + l32;
;     if (tok < M) {
;       u16* dst = DIR + ((size_t)tok * 16 + head) * 192;
; #pragma unroll
;       for (int nb = 0; nb < 2; ++nb)
; #pragma unroll
;         for (int i = 0; i < 4; ++i) {
;           const int c = nb * 32 + 8 * i + 4 * h;
;           const f32x4 w = *(const f32x4*)(w0 + nbase + c);
;           float o[4];
; #pragma unroll
;           for (int j = 0; j < 4; ++j) o[j] = 0.6065306597126334f * sigm(w[j] + acc[nb][tb][4 * i + j]);
;           *(u32x2*)(dst + c) = (u32x2){pk_f16(o[0], o[1]), pk_f16(o[2], o[3])};
;         }
;     }
;   }
.LBB0_466:
	s_or_b64 exec, exec, s[6:7]
	v_mov_b32_e32 v70, v204
	s_load_dwordx2 s[0:1], s[64:65], 0x90
	v_lshl_add_u32 v69, v69, 7, v78
	v_lshl_or_b32 v68, v68, 7, v85
	v_and_or_b32 v74, v70, 31, v69
	v_lshrrev_b32_e32 v69, 3, v70
	v_ashrrev_i32_e32 v72, 6, v68
	v_and_b32_e32 v75, 4, v69
	v_ashrrev_i32_e32 v69, 31, v68
	v_ashrrev_i32_e32 v73, 31, v72
	s_waitcnt lgkmcnt(0)
	v_lshl_add_u64 v[70:71], v[68:69], 2, s[0:1]
	v_cmp_gt_i32_e64 s[40:41], s72, v74
	v_lshlrev_b32_e32 v160, 2, v75
	v_lshlrev_b32_e32 v68, 1, v75
	s_and_saveexec_b64 s[46:47], s[40:41]
	s_cbranch_execz .LBB0_468
	v_ashrrev_i32_e32 v75, 31, v74
	v_lshl_add_u64 v[76:77], v[74:75], 4, v[72:73]
	v_mov_b64_e32 v[88:89], s[42:43]
	v_mad_u64_u32 v[92:93], s[0:1], v76, s75, v[88:89]
	v_mad_i32_i24 v93, v77, s75, v93
	v_lshl_add_u64 v[76:77], v[70:71], 0, v[160:161]
	global_load_dwordx4 v[118:121], v[76:77], off
	global_load_dwordx4 v[122:125], v[76:77], off offset:32
	global_load_dwordx4 v[126:129], v[76:77], off offset:64
	global_load_dwordx4 v[130:133], v[76:77], off offset:96
	global_load_dwordx4 v[134:137], v[76:77], off offset:128
	global_load_dwordx4 v[138:141], v[76:77], off offset:160
	global_load_dwordx4 v[142:145], v[76:77], off offset:192
	global_load_dwordx4 v[146:149], v[76:77], off offset:224
	v_mov_b32_e32 v69, v161
	s_waitcnt vmcnt(7)
	v_add_f32_e32 v48, v48, v118
	v_add_f32_e32 v49, v49, v119
	v_add_f32_e32 v50, v50, v120
	v_add_f32_e32 v51, v51, v121
	v_mul_f32_e32 v48, 0xbfb8aa3b, v48
	v_mul_f32_e32 v49, 0xbfb8aa3b, v49
	v_mul_f32_e32 v50, 0xbfb8aa3b, v50
	v_mul_f32_e32 v51, 0xbfb8aa3b, v51
	v_exp_f32_e32 v48, v48
	v_exp_f32_e32 v49, v49
	v_exp_f32_e32 v50, v50
	v_exp_f32_e32 v51, v51
	v_add_f32_e32 v48, 1.0, v48
	v_add_f32_e32 v49, 1.0, v49
	v_add_f32_e32 v50, 1.0, v50
	v_add_f32_e32 v51, 1.0, v51
	v_rcp_f32_e32 v48, v48
	v_rcp_f32_e32 v49, v49
	v_rcp_f32_e32 v50, v50
	v_rcp_f32_e32 v51, v51
	v_pk_mul_f32 v[48:49], v[48:49], s[22:23] op_sel_hi:[1,0]
	s_nop 0
	v_cvt_pk_f16_f32 v88, v48, v49
	v_pk_mul_f32 v[50:51], v[50:51], s[22:23] op_sel_hi:[1,0]
	v_lshl_add_u64 v[48:49], v[92:93], 0, v[68:69]
	v_cvt_pk_f16_f32 v89, v50, v51
	v_mbcnt_lo_u32_b32 v238, -1, 0
	v_mbcnt_hi_u32_b32 v238, -1, v238
	v_lshrrev_b32_e32 v238, 2, v238
	v_and_b32_e32 v238, 8, v238
	v_mov_b32_e32 v239, 0
	v_lshl_add_u64 v[238:239], v[48:49], 0, v[238:239]
	v_mov_b32_e32 v222, v88
	v_mov_b32_e32 v223, v89
	s_nop 0
	s_waitcnt vmcnt(6)
	v_add_f32_e32 v50, v52, v122
	v_add_f32_e32 v51, v53, v123
	v_add_f32_e32 v52, v54, v124
	v_add_f32_e32 v53, v55, v125
	v_mul_f32_e32 v50, 0xbfb8aa3b, v50
	v_mul_f32_e32 v51, 0xbfb8aa3b, v51
	v_mul_f32_e32 v52, 0xbfb8aa3b, v52
	v_mul_f32_e32 v53, 0xbfb8aa3b, v53
	v_exp_f32_e32 v50, v50
	v_exp_f32_e32 v51, v51
	v_exp_f32_e32 v52, v52
	v_exp_f32_e32 v53, v53
	v_add_f32_e32 v50, 1.0, v50
	v_add_f32_e32 v51, 1.0, v51
	v_add_f32_e32 v52, 1.0, v52
	v_add_f32_e32 v53, 1.0, v53
	v_rcp_f32_e32 v50, v50
	v_rcp_f32_e32 v51, v51
	v_rcp_f32_e32 v52, v52
	v_rcp_f32_e32 v53, v53
	v_pk_mul_f32 v[50:51], v[50:51], s[22:23] op_sel_hi:[1,0]
	s_nop 0
	v_cvt_pk_f16_f32 v50, v50, v51
	v_pk_mul_f32 v[52:53], v[52:53], s[22:23] op_sel_hi:[1,0]
	s_nop 0
	v_cvt_pk_f16_f32 v51, v52, v53
	v_mov_b32_e32 v224, v50
	v_mov_b32_e32 v225, v51
	s_nop 1
	v_permlane32_swap_b32_e32 v222, v224
	v_permlane32_swap_b32_e32 v223, v225
	global_store_dwordx4 v[238:239], v[222:225], off
	s_nop 0
	s_waitcnt vmcnt(6)
	v_add_f32_e32 v50, v56, v126
	v_add_f32_e32 v51, v57, v127
	v_add_f32_e32 v52, v58, v128
	v_add_f32_e32 v53, v59, v129
	v_mul_f32_e32 v50, 0xbfb8aa3b, v50
	v_mul_f32_e32 v51, 0xbfb8aa3b, v51
	v_mul_f32_e32 v52, 0xbfb8aa3b, v52
	v_mul_f32_e32 v53, 0xbfb8aa3b, v53
	v_exp_f32_e32 v50, v50
	v_exp_f32_e32 v51, v51
	v_exp_f32_e32 v52, v52
	v_exp_f32_e32 v53, v53
	v_add_f32_e32 v50, 1.0, v50
	v_add_f32_e32 v51, 1.0, v51
	v_add_f32_e32 v52, 1.0, v52
	v_add_f32_e32 v53, 1.0, v53
	v_rcp_f32_e32 v50, v50
	v_rcp_f32_e32 v51, v51
	v_rcp_f32_e32 v52, v52
	v_rcp_f32_e32 v53, v53
	v_pk_mul_f32 v[50:51], v[50:51], s[22:23] op_sel_hi:[1,0]
	s_nop 0
	v_cvt_pk_f16_f32 v50, v50, v51
	v_pk_mul_f32 v[52:53], v[52:53], s[22:23] op_sel_hi:[1,0]
	s_nop 0
	v_cvt_pk_f16_f32 v51, v52, v53
	v_mov_b32_e32 v226, v50
	v_mov_b32_e32 v227, v51
	s_nop 0
	s_waitcnt vmcnt(5)
	v_add_f32_e32 v50, v60, v130
	v_add_f32_e32 v51, v61, v131
	v_add_f32_e32 v52, v62, v132
	v_add_f32_e32 v53, v63, v133
	v_mul_f32_e32 v50, 0xbfb8aa3b, v50
	v_mul_f32_e32 v51, 0xbfb8aa3b, v51
	v_mul_f32_e32 v52, 0xbfb8aa3b, v52
	v_mul_f32_e32 v53, 0xbfb8aa3b, v53
	v_exp_f32_e32 v50, v50
	v_exp_f32_e32 v51, v51
	v_exp_f32_e32 v52, v52
	v_exp_f32_e32 v53, v53
	v_add_f32_e32 v50, 1.0, v50
	v_add_f32_e32 v51, 1.0, v51
	v_add_f32_e32 v52, 1.0, v52
	v_add_f32_e32 v53, 1.0, v53
	v_rcp_f32_e32 v50, v50
	v_rcp_f32_e32 v51, v51
	v_rcp_f32_e32 v52, v52
	v_rcp_f32_e32 v53, v53
	v_pk_mul_f32 v[50:51], v[50:51], s[22:23] op_sel_hi:[1,0]
	s_nop 0
	v_cvt_pk_f16_f32 v50, v50, v51
	v_pk_mul_f32 v[52:53], v[52:53], s[22:23] op_sel_hi:[1,0]
	s_nop 0
	v_cvt_pk_f16_f32 v51, v52, v53
	v_mov_b32_e32 v228, v50
	v_mov_b32_e32 v229, v51
	s_nop 1
	v_permlane32_swap_b32_e32 v226, v228
	v_permlane32_swap_b32_e32 v227, v229
	global_store_dwordx4 v[238:239], v[226:229], off offset:32
	s_nop 0
	s_waitcnt vmcnt(5)
; __device__ __forceinline__ float sigm(float x) { return __builtin_amdgcn_rcpf(1.f + __builtin_amdgcn_exp2f(-LOG2E * x)); }
; __device__ __forceinline__ void epi_decay(const f32x16 (&acc)[2][2], int nbase, int tbase, int M, const float* w0, u16* DIR) {
;     ...
; #pragma unroll
;   for (int tb = 0; tb < 2; ++tb) {
;     const int tok = tbase + tb * 32 + l32;
;     if (tok < M) {
;       u16* dst = DIR + ((size_t)tok * 16 + head) * 192;
; #pragma unroll
;       for (int nb = 0; nb < 2; ++nb)
; #pragma unroll
;         for (int i = 0; i < 4; ++i) {
;           const int c = nb * 32 + 8 * i + 4 * h;
;           const f32x4 w = *(const f32x4*)(w0 + nbase + c);
;           float o[4];
; #pragma unroll
;           for (int j = 0; j < 4; ++j) o[j] = 0.6065306597126334f * sigm(w[j] + acc[nb][tb][4 * i + j]);
;           *(u32x2*)(dst + c) = (u32x2){pk_f16(o[0], o[1]), pk_f16(o[2], o[3])};
;         }
;     }
;   }
	v_add_f32_e32 v32, v32, v134
	v_add_f32_e32 v33, v33, v135
	v_add_f32_e32 v34, v34, v136
	v_add_f32_e32 v35, v35, v137
	v_mul_f32_e32 v32, 0xbfb8aa3b, v32
	v_mul_f32_e32 v33, 0xbfb8aa3b, v33
	v_mul_f32_e32 v34, 0xbfb8aa3b, v34
	v_mul_f32_e32 v35, 0xbfb8aa3b, v35
	v_exp_f32_e32 v32, v32
	v_exp_f32_e32 v33, v33
	v_exp_f32_e32 v34, v34
	v_exp_f32_e32 v35, v35
	v_add_f32_e32 v32, 1.0, v32
	v_add_f32_e32 v33, 1.0, v33
	v_add_f32_e32 v34, 1.0, v34
	v_add_f32_e32 v35, 1.0, v35
	v_rcp_f32_e32 v32, v32
	v_rcp_f32_e32 v33, v33
	v_rcp_f32_e32 v34, v34
	v_rcp_f32_e32 v35, v35
	v_pk_mul_f32 v[32:33], v[32:33], s[22:23] op_sel_hi:[1,0]
	s_nop 0
	v_cvt_pk_f16_f32 v32, v32, v33
	v_pk_mul_f32 v[34:35], v[34:35], s[22:23] op_sel_hi:[1,0]
	s_nop 0
	v_cvt_pk_f16_f32 v33, v34, v35
	v_mov_b32_e32 v230, v32
	v_mov_b32_e32 v231, v33
	s_nop 0
	s_waitcnt vmcnt(4)
	v_add_f32_e32 v32, v36, v138
	v_add_f32_e32 v33, v37, v139
	v_add_f32_e32 v34, v38, v140
	v_add_f32_e32 v35, v39, v141
	v_mul_f32_e32 v32, 0xbfb8aa3b, v32
	v_mul_f32_e32 v33, 0xbfb8aa3b, v33
	v_mul_f32_e32 v34, 0xbfb8aa3b, v34
	v_mul_f32_e32 v35, 0xbfb8aa3b, v35
	v_exp_f32_e32 v32, v32
	v_exp_f32_e32 v33, v33
	v_exp_f32_e32 v34, v34
	v_exp_f32_e32 v35, v35
	v_add_f32_e32 v32, 1.0, v32
	v_add_f32_e32 v33, 1.0, v33
	v_add_f32_e32 v34, 1.0, v34
	v_add_f32_e32 v35, 1.0, v35
	v_rcp_f32_e32 v32, v32
	v_rcp_f32_e32 v33, v33
	v_rcp_f32_e32 v34, v34
	v_rcp_f32_e32 v35, v35
	v_pk_mul_f32 v[32:33], v[32:33], s[22:23] op_sel_hi:[1,0]
	s_nop 0
	v_cvt_pk_f16_f32 v32, v32, v33
	v_pk_mul_f32 v[34:35], v[34:35], s[22:23] op_sel_hi:[1,0]
	s_nop 0
	v_cvt_pk_f16_f32 v33, v34, v35
	v_mov_b32_e32 v232, v32
	v_mov_b32_e32 v233, v33
	s_nop 1
	v_permlane32_swap_b32_e32 v230, v232
	v_permlane32_swap_b32_e32 v231, v233
	global_store_dwordx4 v[238:239], v[230:233], off offset:64
	s_nop 0
	s_waitcnt vmcnt(4)
	v_add_f32_e32 v32, v40, v142
	v_add_f32_e32 v33, v41, v143
	v_add_f32_e32 v34, v42, v144
	v_add_f32_e32 v35, v43, v145
	v_mul_f32_e32 v32, 0xbfb8aa3b, v32
	v_mul_f32_e32 v33, 0xbfb8aa3b, v33
	v_mul_f32_e32 v34, 0xbfb8aa3b, v34
	v_mul_f32_e32 v35, 0xbfb8aa3b, v35
	v_exp_f32_e32 v32, v32
	v_exp_f32_e32 v33, v33
	v_exp_f32_e32 v34, v34
	v_exp_f32_e32 v35, v35
	v_add_f32_e32 v32, 1.0, v32
	v_add_f32_e32 v33, 1.0, v33
	v_add_f32_e32 v34, 1.0, v34
	v_add_f32_e32 v35, 1.0, v35
	v_rcp_f32_e32 v32, v32
	v_rcp_f32_e32 v33, v33
	v_rcp_f32_e32 v34, v34
	v_rcp_f32_e32 v35, v35
	v_pk_mul_f32 v[32:33], v[32:33], s[22:23] op_sel_hi:[1,0]
	s_nop 0
	v_cvt_pk_f16_f32 v32, v32, v33
	v_pk_mul_f32 v[34:35], v[34:35], s[22:23] op_sel_hi:[1,0]
	s_nop 0
	v_cvt_pk_f16_f32 v33, v34, v35
	v_mov_b32_e32 v234, v32
	v_mov_b32_e32 v235, v33
	s_nop 0
	s_waitcnt vmcnt(3)
	v_add_f32_e32 v32, v44, v146
	v_add_f32_e32 v33, v45, v147
	v_add_f32_e32 v34, v46, v148
	v_add_f32_e32 v35, v47, v149
	v_mul_f32_e32 v32, 0xbfb8aa3b, v32
	v_mul_f32_e32 v33, 0xbfb8aa3b, v33
	v_mul_f32_e32 v34, 0xbfb8aa3b, v34
	v_mul_f32_e32 v35, 0xbfb8aa3b, v35
	v_exp_f32_e32 v32, v32
	v_exp_f32_e32 v33, v33
	v_exp_f32_e32 v34, v34
	v_exp_f32_e32 v35, v35
	v_add_f32_e32 v32, 1.0, v32
	v_add_f32_e32 v33, 1.0, v33
	v_add_f32_e32 v34, 1.0, v34
	v_add_f32_e32 v35, 1.0, v35
	v_rcp_f32_e32 v32, v32
	v_rcp_f32_e32 v33, v33
	v_rcp_f32_e32 v34, v34
	v_rcp_f32_e32 v35, v35
	v_pk_mul_f32 v[32:33], v[32:33], s[22:23] op_sel_hi:[1,0]
	s_nop 0
	v_cvt_pk_f16_f32 v32, v32, v33
	v_pk_mul_f32 v[34:35], v[34:35], s[22:23] op_sel_hi:[1,0]
	s_nop 0
	v_cvt_pk_f16_f32 v33, v34, v35
	v_mov_b32_e32 v236, v32
	v_mov_b32_e32 v237, v33
	s_nop 1
	v_permlane32_swap_b32_e32 v234, v236
	v_permlane32_swap_b32_e32 v235, v237
	global_store_dwordx4 v[238:239], v[234:237], off offset:96
.LBB0_468:
	s_or_b64 exec, exec, s[46:47]
	v_or_b32_e32 v32, 32, v74
	v_cmp_gt_i32_e64 s[40:41], s72, v32
	s_and_saveexec_b64 s[46:47], s[40:41]
	s_cbranch_execz .LBB0_459
	v_ashrrev_i32_e32 v33, 31, v32
	v_lshl_add_u64 v[32:33], v[32:33], 4, v[72:73]
	v_mov_b64_e32 v[34:35], s[42:43]
	v_mad_u64_u32 v[38:39], s[0:1], v32, s75, v[34:35]
	v_mad_i32_i24 v39, v33, s75, v39
	v_lshl_add_u64 v[32:33], v[70:71], 0, v[160:161]
	global_load_dwordx4 v[118:121], v[32:33], off
	global_load_dwordx4 v[122:125], v[32:33], off offset:32
	global_load_dwordx4 v[126:129], v[32:33], off offset:64
	global_load_dwordx4 v[130:133], v[32:33], off offset:96
	global_load_dwordx4 v[134:137], v[32:33], off offset:128
	global_load_dwordx4 v[138:141], v[32:33], off offset:160
	global_load_dwordx4 v[142:145], v[32:33], off offset:192
	global_load_dwordx4 v[146:149], v[32:33], off offset:224
	v_mov_b32_e32 v69, v161
	s_waitcnt vmcnt(7)
	v_add_f32_e32 v16, v16, v118
	v_add_f32_e32 v17, v17, v119
	v_add_f32_e32 v18, v18, v120
	v_add_f32_e32 v19, v19, v121
	v_mul_f32_e32 v16, 0xbfb8aa3b, v16
	v_mul_f32_e32 v17, 0xbfb8aa3b, v17
	v_mul_f32_e32 v18, 0xbfb8aa3b, v18
	v_mul_f32_e32 v19, 0xbfb8aa3b, v19
	v_exp_f32_e32 v16, v16
	v_exp_f32_e32 v17, v17
	v_exp_f32_e32 v18, v18
	v_exp_f32_e32 v19, v19
	v_add_f32_e32 v16, 1.0, v16
	v_add_f32_e32 v17, 1.0, v17
	v_add_f32_e32 v18, 1.0, v18
	v_add_f32_e32 v19, 1.0, v19
	v_rcp_f32_e32 v16, v16
	v_rcp_f32_e32 v17, v17
	v_rcp_f32_e32 v18, v18
	v_rcp_f32_e32 v19, v19
	v_pk_mul_f32 v[16:17], v[16:17], s[22:23] op_sel_hi:[1,0]
	s_nop 0
	v_cvt_pk_f16_f32 v34, v16, v17
	v_pk_mul_f32 v[18:19], v[18:19], s[22:23] op_sel_hi:[1,0]
	v_lshl_add_u64 v[16:17], v[38:39], 0, v[68:69]
	v_cvt_pk_f16_f32 v35, v18, v19
	v_mbcnt_lo_u32_b32 v238, -1, 0
	v_mbcnt_hi_u32_b32 v238, -1, v238
	v_lshrrev_b32_e32 v238, 2, v238
	v_and_b32_e32 v238, 8, v238
	v_mov_b32_e32 v239, 0
	v_lshl_add_u64 v[238:239], v[16:17], 0, v[238:239]
	v_mov_b32_e32 v242, v34
	v_mov_b32_e32 v243, v35
	s_nop 0
	s_waitcnt vmcnt(6)
; __device__ __forceinline__ float sigm(float x) { return __builtin_amdgcn_rcpf(1.f + __builtin_amdgcn_exp2f(-LOG2E * x)); }
; __device__ __forceinline__ void epi_decay(const f32x16 (&acc)[2][2], int nbase, int tbase, int M, const float* w0, u16* DIR) {
;     ...
; #pragma unroll
;   for (int tb = 0; tb < 2; ++tb) {
;     const int tok = tbase + tb * 32 + l32;
;     if (tok < M) {
;       u16* dst = DIR + ((size_t)tok * 16 + head) * 192;
; #pragma unroll
;       for (int nb = 0; nb < 2; ++nb)
; #pragma unroll
;         for (int i = 0; i < 4; ++i) {
;           const int c = nb * 32 + 8 * i + 4 * h;
;           const f32x4 w = *(const f32x4*)(w0 + nbase + c);
;           float o[4];
; #pragma unroll
;           for (int j = 0; j < 4; ++j) o[j] = 0.6065306597126334f * sigm(w[j] + acc[nb][tb][4 * i + j]);
;           *(u32x2*)(dst + c) = (u32x2){pk_f16(o[0], o[1]), pk_f16(o[2], o[3])};
;         }
;     }
;   }
	v_add_f32_e32 v18, v20, v122
	v_add_f32_e32 v19, v21, v123
	v_add_f32_e32 v20, v22, v124
	v_add_f32_e32 v21, v23, v125
	v_mul_f32_e32 v18, 0xbfb8aa3b, v18
	v_mul_f32_e32 v19, 0xbfb8aa3b, v19
	v_mul_f32_e32 v20, 0xbfb8aa3b, v20
	v_mul_f32_e32 v21, 0xbfb8aa3b, v21
	v_exp_f32_e32 v18, v18
	v_exp_f32_e32 v19, v19
	v_exp_f32_e32 v20, v20
	v_exp_f32_e32 v21, v21
	v_add_f32_e32 v18, 1.0, v18
	v_add_f32_e32 v19, 1.0, v19
	v_add_f32_e32 v20, 1.0, v20
	v_add_f32_e32 v21, 1.0, v21
	v_rcp_f32_e32 v18, v18
	v_rcp_f32_e32 v19, v19
	v_rcp_f32_e32 v20, v20
	v_rcp_f32_e32 v21, v21
	v_pk_mul_f32 v[18:19], v[18:19], s[22:23] op_sel_hi:[1,0]
	s_nop 0
	v_cvt_pk_f16_f32 v18, v18, v19
	v_pk_mul_f32 v[20:21], v[20:21], s[22:23] op_sel_hi:[1,0]
	s_nop 0
	v_cvt_pk_f16_f32 v19, v20, v21
	v_mov_b32_e32 v244, v18
	v_mov_b32_e32 v245, v19
	s_nop 1
	v_permlane32_swap_b32_e32 v242, v244
	v_permlane32_swap_b32_e32 v243, v245
	global_store_dwordx4 v[238:239], v[242:245], off
	s_nop 0
	s_waitcnt vmcnt(6)
	v_add_f32_e32 v18, v24, v126
	v_add_f32_e32 v19, v25, v127
	v_add_f32_e32 v20, v26, v128
	v_add_f32_e32 v21, v27, v129
	v_mul_f32_e32 v18, 0xbfb8aa3b, v18
	v_mul_f32_e32 v19, 0xbfb8aa3b, v19
	v_mul_f32_e32 v20, 0xbfb8aa3b, v20
	v_mul_f32_e32 v21, 0xbfb8aa3b, v21
	v_exp_f32_e32 v18, v18
	v_exp_f32_e32 v19, v19
	v_exp_f32_e32 v20, v20
	v_exp_f32_e32 v21, v21
	v_add_f32_e32 v18, 1.0, v18
	v_add_f32_e32 v19, 1.0, v19
	v_add_f32_e32 v20, 1.0, v20
	v_add_f32_e32 v21, 1.0, v21
	v_rcp_f32_e32 v18, v18
	v_rcp_f32_e32 v19, v19
	v_rcp_f32_e32 v20, v20
	v_rcp_f32_e32 v21, v21
	v_pk_mul_f32 v[18:19], v[18:19], s[22:23] op_sel_hi:[1,0]
	s_nop 0
	v_cvt_pk_f16_f32 v18, v18, v19
	v_pk_mul_f32 v[20:21], v[20:21], s[22:23] op_sel_hi:[1,0]
	s_nop 0
	v_cvt_pk_f16_f32 v19, v20, v21
	v_mov_b32_e32 v246, v18
	v_mov_b32_e32 v247, v19
	s_nop 0
	s_waitcnt vmcnt(5)
	v_add_f32_e32 v18, v28, v130
	v_add_f32_e32 v19, v29, v131
	v_add_f32_e32 v20, v30, v132
	v_add_f32_e32 v21, v31, v133
	v_mul_f32_e32 v18, 0xbfb8aa3b, v18
	v_mul_f32_e32 v19, 0xbfb8aa3b, v19
	v_mul_f32_e32 v20, 0xbfb8aa3b, v20
	v_mul_f32_e32 v21, 0xbfb8aa3b, v21
	v_exp_f32_e32 v18, v18
	v_exp_f32_e32 v19, v19
	v_exp_f32_e32 v20, v20
	v_exp_f32_e32 v21, v21
	v_add_f32_e32 v18, 1.0, v18
	v_add_f32_e32 v19, 1.0, v19
	v_add_f32_e32 v20, 1.0, v20
	v_add_f32_e32 v21, 1.0, v21
	v_rcp_f32_e32 v18, v18
	v_rcp_f32_e32 v19, v19
	v_rcp_f32_e32 v20, v20
	v_rcp_f32_e32 v21, v21
	v_pk_mul_f32 v[18:19], v[18:19], s[22:23] op_sel_hi:[1,0]
	s_nop 0
	v_cvt_pk_f16_f32 v18, v18, v19
	v_pk_mul_f32 v[20:21], v[20:21], s[22:23] op_sel_hi:[1,0]
	s_nop 0
	v_cvt_pk_f16_f32 v19, v20, v21
	v_mov_b32_e32 v248, v18
	v_mov_b32_e32 v249, v19
	s_nop 1
	v_permlane32_swap_b32_e32 v246, v248
	v_permlane32_swap_b32_e32 v247, v249
	global_store_dwordx4 v[238:239], v[246:249], off offset:32
	s_nop 0
	s_waitcnt vmcnt(5)
	v_add_f32_e32 v0, v0, v134
	v_add_f32_e32 v1, v1, v135
	v_add_f32_e32 v2, v2, v136
	v_add_f32_e32 v3, v3, v137
	v_mul_f32_e32 v0, 0xbfb8aa3b, v0
	v_mul_f32_e32 v1, 0xbfb8aa3b, v1
	v_mul_f32_e32 v2, 0xbfb8aa3b, v2
	v_mul_f32_e32 v3, 0xbfb8aa3b, v3
	v_exp_f32_e32 v0, v0
	v_exp_f32_e32 v1, v1
	v_exp_f32_e32 v2, v2
	v_exp_f32_e32 v3, v3
	v_add_f32_e32 v0, 1.0, v0
	v_add_f32_e32 v1, 1.0, v1
	v_add_f32_e32 v2, 1.0, v2
	v_add_f32_e32 v3, 1.0, v3
	v_rcp_f32_e32 v0, v0
	v_rcp_f32_e32 v1, v1
	v_rcp_f32_e32 v2, v2
	v_rcp_f32_e32 v3, v3
	v_pk_mul_f32 v[0:1], v[0:1], s[22:23] op_sel_hi:[1,0]
	s_nop 0
	v_cvt_pk_f16_f32 v0, v0, v1
	v_pk_mul_f32 v[2:3], v[2:3], s[22:23] op_sel_hi:[1,0]
	s_nop 0
	v_cvt_pk_f16_f32 v1, v2, v3
	v_mov_b32_e32 v222, v0
	v_mov_b32_e32 v223, v1
	s_nop 0
	s_waitcnt vmcnt(4)
	v_add_f32_e32 v0, v4, v138
	v_add_f32_e32 v1, v5, v139
	v_add_f32_e32 v2, v6, v140
	v_add_f32_e32 v3, v7, v141
	v_mul_f32_e32 v0, 0xbfb8aa3b, v0
	v_mul_f32_e32 v1, 0xbfb8aa3b, v1
	v_mul_f32_e32 v2, 0xbfb8aa3b, v2
	v_mul_f32_e32 v3, 0xbfb8aa3b, v3
	v_exp_f32_e32 v0, v0
	v_exp_f32_e32 v1, v1
	v_exp_f32_e32 v2, v2
	v_exp_f32_e32 v3, v3
	v_add_f32_e32 v0, 1.0, v0
	v_add_f32_e32 v1, 1.0, v1
	v_add_f32_e32 v2, 1.0, v2
	v_add_f32_e32 v3, 1.0, v3
	v_rcp_f32_e32 v0, v0
	v_rcp_f32_e32 v1, v1
	v_rcp_f32_e32 v2, v2
	v_rcp_f32_e32 v3, v3
	v_pk_mul_f32 v[0:1], v[0:1], s[22:23] op_sel_hi:[1,0]
	s_nop 0
	v_cvt_pk_f16_f32 v0, v0, v1
	v_pk_mul_f32 v[2:3], v[2:3], s[22:23] op_sel_hi:[1,0]
	s_nop 0
	v_cvt_pk_f16_f32 v1, v2, v3
	v_mov_b32_e32 v224, v0
	v_mov_b32_e32 v225, v1
	s_nop 1
	v_permlane32_swap_b32_e32 v222, v224
	v_permlane32_swap_b32_e32 v223, v225
	global_store_dwordx4 v[238:239], v[222:225], off offset:64
	s_nop 0
	s_waitcnt vmcnt(4)
	v_add_f32_e32 v0, v8, v142
	v_add_f32_e32 v1, v9, v143
	v_add_f32_e32 v2, v10, v144
	v_add_f32_e32 v3, v11, v145
	v_mul_f32_e32 v0, 0xbfb8aa3b, v0
	v_mul_f32_e32 v1, 0xbfb8aa3b, v1
	v_mul_f32_e32 v2, 0xbfb8aa3b, v2
	v_mul_f32_e32 v3, 0xbfb8aa3b, v3
	v_exp_f32_e32 v0, v0
	v_exp_f32_e32 v1, v1
	v_exp_f32_e32 v2, v2
	v_exp_f32_e32 v3, v3
	v_add_f32_e32 v0, 1.0, v0
	v_add_f32_e32 v1, 1.0, v1
	v_add_f32_e32 v2, 1.0, v2
	v_add_f32_e32 v3, 1.0, v3
	v_rcp_f32_e32 v0, v0
	v_rcp_f32_e32 v1, v1
	v_rcp_f32_e32 v2, v2
	v_rcp_f32_e32 v3, v3
	v_pk_mul_f32 v[0:1], v[0:1], s[22:23] op_sel_hi:[1,0]
	s_nop 0
	v_cvt_pk_f16_f32 v0, v0, v1
	v_pk_mul_f32 v[2:3], v[2:3], s[22:23] op_sel_hi:[1,0]
	s_nop 0
	v_cvt_pk_f16_f32 v1, v2, v3
	v_mov_b32_e32 v226, v0
	v_mov_b32_e32 v227, v1
	s_nop 0
	s_waitcnt vmcnt(3)
	v_add_f32_e32 v0, v12, v146
	v_add_f32_e32 v1, v13, v147
	v_add_f32_e32 v2, v14, v148
	v_add_f32_e32 v3, v15, v149
	v_mul_f32_e32 v0, 0xbfb8aa3b, v0
	v_mul_f32_e32 v1, 0xbfb8aa3b, v1
	v_mul_f32_e32 v2, 0xbfb8aa3b, v2
	v_mul_f32_e32 v3, 0xbfb8aa3b, v3
	v_exp_f32_e32 v0, v0
	v_exp_f32_e32 v1, v1
	v_exp_f32_e32 v2, v2
	v_exp_f32_e32 v3, v3
	v_add_f32_e32 v0, 1.0, v0
	v_add_f32_e32 v1, 1.0, v1
	v_add_f32_e32 v2, 1.0, v2
	v_add_f32_e32 v3, 1.0, v3
	v_rcp_f32_e32 v0, v0
	v_rcp_f32_e32 v1, v1
	v_rcp_f32_e32 v2, v2
	v_rcp_f32_e32 v3, v3
	v_pk_mul_f32 v[0:1], v[0:1], s[22:23] op_sel_hi:[1,0]
	s_nop 0
	v_cvt_pk_f16_f32 v0, v0, v1
	v_pk_mul_f32 v[2:3], v[2:3], s[22:23] op_sel_hi:[1,0]
	s_nop 0
	v_cvt_pk_f16_f32 v1, v2, v3
	v_mov_b32_e32 v228, v0
	v_mov_b32_e32 v229, v1
	s_nop 1
	v_permlane32_swap_b32_e32 v226, v228
	v_permlane32_swap_b32_e32 v227, v229
	global_store_dwordx4 v[238:239], v[226:229], off offset:96
	s_branch .LBB0_459

; __device__ __forceinline__ float sigm(float x) { return __builtin_amdgcn_rcpf(1.f + __builtin_amdgcn_exp2f(-LOG2E * x)); }
; __device__ __forceinline__ void epi_decay(const f32x16 (&acc)[2][2], int nbase, int tbase, int M, const float* w0, u16* DIR) {
;     ...
; #pragma unroll
;   for (int tb = 0; tb < 2; ++tb) {
;     const int tok = tbase + tb * 32 + l32;
;     if (tok < M) {
;       u16* dst = DIR + ((size_t)tok * 16 + head) * 192;
; #pragma unroll
;       for (int nb = 0; nb < 2; ++nb)
; #pragma unroll
;         for (int i = 0; i < 4; ++i) {
;           const int c = nb * 32 + 8 * i + 4 * h;
;           const f32x4 w = *(const f32x4*)(w0 + nbase + c);
;           float o[4];
; #pragma unroll
;           for (int j = 0; j < 4; ++j) o[j] = 0.6065306597126334f * sigm(w[j] + acc[nb][tb][4 * i + j]);
;           *(u32x2*)(dst + c) = (u32x2){pk_f16(o[0], o[1]), pk_f16(o[2], o[3])};
;         }
;     }
;   }
.LBB0_483:
	s_or_b64 exec, exec, s[6:7]
	v_lshl_add_u32 v69, v69, 7, v78
	v_mov_b32_e32 v70, v204
	v_lshl_or_b32 v68, v68, 7, v85
	v_ashrrev_i32_e32 v72, 6, v68
	v_and_or_b32 v74, v70, 31, v69
	v_lshrrev_b32_e32 v69, 3, v70
	v_and_b32_e32 v75, 4, v69
	v_ashrrev_i32_e32 v69, 31, v68
	v_ashrrev_i32_e32 v73, 31, v72
	v_lshl_add_u64 v[70:71], v[68:69], 2, s[44:45]
	v_cmp_gt_i32_e64 s[40:41], s72, v74
	v_lshlrev_b32_e32 v160, 2, v75
	v_lshlrev_b32_e32 v68, 1, v75
	s_and_saveexec_b64 s[48:49], s[40:41]
	s_cbranch_execz .LBB0_485
	v_ashrrev_i32_e32 v75, 31, v74
	v_lshl_add_u64 v[76:77], v[74:75], 4, v[72:73]
	v_mov_b64_e32 v[88:89], s[42:43]
	v_mad_u64_u32 v[92:93], s[0:1], v76, s75, v[88:89]
	v_mad_i32_i24 v93, v77, s75, v93
	v_lshl_add_u64 v[76:77], v[70:71], 0, v[160:161]
	global_load_dwordx4 v[118:121], v[76:77], off
	global_load_dwordx4 v[122:125], v[76:77], off offset:32
	global_load_dwordx4 v[126:129], v[76:77], off offset:64
	global_load_dwordx4 v[130:133], v[76:77], off offset:96
	global_load_dwordx4 v[134:137], v[76:77], off offset:128
	global_load_dwordx4 v[138:141], v[76:77], off offset:160
	global_load_dwordx4 v[142:145], v[76:77], off offset:192
	global_load_dwordx4 v[146:149], v[76:77], off offset:224
	v_mov_b32_e32 v69, v161
	s_waitcnt vmcnt(7)
	v_add_f32_e32 v48, v48, v118
	v_add_f32_e32 v49, v49, v119
	v_add_f32_e32 v50, v50, v120
	v_add_f32_e32 v51, v51, v121
	v_mul_f32_e32 v48, 0xbfb8aa3b, v48
	v_mul_f32_e32 v49, 0xbfb8aa3b, v49
	v_mul_f32_e32 v50, 0xbfb8aa3b, v50
	v_mul_f32_e32 v51, 0xbfb8aa3b, v51
	v_exp_f32_e32 v48, v48
	v_exp_f32_e32 v49, v49
	v_exp_f32_e32 v50, v50
	v_exp_f32_e32 v51, v51
	v_add_f32_e32 v48, 1.0, v48
	v_add_f32_e32 v49, 1.0, v49
	v_add_f32_e32 v50, 1.0, v50
	v_add_f32_e32 v51, 1.0, v51
	v_rcp_f32_e32 v48, v48
	v_rcp_f32_e32 v49, v49
	v_rcp_f32_e32 v50, v50
	v_rcp_f32_e32 v51, v51
	v_pk_mul_f32 v[48:49], v[48:49], s[22:23] op_sel_hi:[1,0]
	s_nop 0
	v_cvt_pk_f16_f32 v88, v48, v49
	v_pk_mul_f32 v[50:51], v[50:51], s[22:23] op_sel_hi:[1,0]
	v_lshl_add_u64 v[48:49], v[92:93], 0, v[68:69]
	v_cvt_pk_f16_f32 v89, v50, v51
	v_mbcnt_lo_u32_b32 v238, -1, 0
	v_mbcnt_hi_u32_b32 v238, -1, v238
	v_lshrrev_b32_e32 v238, 2, v238
	v_and_b32_e32 v238, 8, v238
	v_mov_b32_e32 v239, 0
	v_lshl_add_u64 v[238:239], v[48:49], 0, v[238:239]
	v_mov_b32_e32 v230, v88
	v_mov_b32_e32 v231, v89
	s_nop 0
	s_waitcnt vmcnt(6)
	v_add_f32_e32 v50, v52, v122
	v_add_f32_e32 v51, v53, v123
	v_add_f32_e32 v52, v54, v124
	v_add_f32_e32 v53, v55, v125
	v_mul_f32_e32 v50, 0xbfb8aa3b, v50
	v_mul_f32_e32 v51, 0xbfb8aa3b, v51
	v_mul_f32_e32 v52, 0xbfb8aa3b, v52
	v_mul_f32_e32 v53, 0xbfb8aa3b, v53
	v_exp_f32_e32 v50, v50
	v_exp_f32_e32 v51, v51
	v_exp_f32_e32 v52, v52
	v_exp_f32_e32 v53, v53
	v_add_f32_e32 v50, 1.0, v50
	v_add_f32_e32 v51, 1.0, v51
	v_add_f32_e32 v52, 1.0, v52
	v_add_f32_e32 v53, 1.0, v53
	v_rcp_f32_e32 v50, v50
	v_rcp_f32_e32 v51, v51
	v_rcp_f32_e32 v52, v52
	v_rcp_f32_e32 v53, v53
	v_pk_mul_f32 v[50:51], v[50:51], s[22:23] op_sel_hi:[1,0]
	s_nop 0
	v_cvt_pk_f16_f32 v50, v50, v51
	v_pk_mul_f32 v[52:53], v[52:53], s[22:23] op_sel_hi:[1,0]
	s_nop 0
	v_cvt_pk_f16_f32 v51, v52, v53
	v_mov_b32_e32 v232, v50
	v_mov_b32_e32 v233, v51
	s_nop 1
	v_permlane32_swap_b32_e32 v230, v232
	v_permlane32_swap_b32_e32 v231, v233
	global_store_dwordx4 v[238:239], v[230:233], off
	s_nop 0
	s_waitcnt vmcnt(6)
	v_add_f32_e32 v50, v56, v126
	v_add_f32_e32 v51, v57, v127
	v_add_f32_e32 v52, v58, v128
	v_add_f32_e32 v53, v59, v129
	v_mul_f32_e32 v50, 0xbfb8aa3b, v50
	v_mul_f32_e32 v51, 0xbfb8aa3b, v51
	v_mul_f32_e32 v52, 0xbfb8aa3b, v52
	v_mul_f32_e32 v53, 0xbfb8aa3b, v53
	v_exp_f32_e32 v50, v50
	v_exp_f32_e32 v51, v51
	v_exp_f32_e32 v52, v52
	v_exp_f32_e32 v53, v53
	v_add_f32_e32 v50, 1.0, v50
	v_add_f32_e32 v51, 1.0, v51
	v_add_f32_e32 v52, 1.0, v52
	v_add_f32_e32 v53, 1.0, v53
	v_rcp_f32_e32 v50, v50
	v_rcp_f32_e32 v51, v51
	v_rcp_f32_e32 v52, v52
	v_rcp_f32_e32 v53, v53
	v_pk_mul_f32 v[50:51], v[50:51], s[22:23] op_sel_hi:[1,0]
	s_nop 0
	v_cvt_pk_f16_f32 v50, v50, v51
	v_pk_mul_f32 v[52:53], v[52:53], s[22:23] op_sel_hi:[1,0]
	s_nop 0
	v_cvt_pk_f16_f32 v51, v52, v53
	v_mov_b32_e32 v234, v50
	v_mov_b32_e32 v235, v51
	s_nop 0
	s_waitcnt vmcnt(5)
	v_add_f32_e32 v50, v60, v130
	v_add_f32_e32 v51, v61, v131
	v_add_f32_e32 v52, v62, v132
	v_add_f32_e32 v53, v63, v133
	v_mul_f32_e32 v50, 0xbfb8aa3b, v50
	v_mul_f32_e32 v51, 0xbfb8aa3b, v51
	v_mul_f32_e32 v52, 0xbfb8aa3b, v52
	v_mul_f32_e32 v53, 0xbfb8aa3b, v53
	v_exp_f32_e32 v50, v50
	v_exp_f32_e32 v51, v51
	v_exp_f32_e32 v52, v52
	v_exp_f32_e32 v53, v53
	v_add_f32_e32 v50, 1.0, v50
	v_add_f32_e32 v51, 1.0, v51
	v_add_f32_e32 v52, 1.0, v52
	v_add_f32_e32 v53, 1.0, v53
	v_rcp_f32_e32 v50, v50
	v_rcp_f32_e32 v51, v51
	v_rcp_f32_e32 v52, v52
	v_rcp_f32_e32 v53, v53
	v_pk_mul_f32 v[50:51], v[50:51], s[22:23] op_sel_hi:[1,0]
	s_nop 0
	v_cvt_pk_f16_f32 v50, v50, v51
	v_pk_mul_f32 v[52:53], v[52:53], s[22:23] op_sel_hi:[1,0]
	s_nop 0
	v_cvt_pk_f16_f32 v51, v52, v53
	v_mov_b32_e32 v236, v50
	v_mov_b32_e32 v237, v51
	s_nop 1
	v_permlane32_swap_b32_e32 v234, v236
	v_permlane32_swap_b32_e32 v235, v237
	global_store_dwordx4 v[238:239], v[234:237], off offset:32
	s_nop 0
	s_waitcnt vmcnt(5)
	v_add_f32_e32 v32, v32, v134
	v_add_f32_e32 v33, v33, v135
	v_add_f32_e32 v34, v34, v136
	v_add_f32_e32 v35, v35, v137
	v_mul_f32_e32 v32, 0xbfb8aa3b, v32
	v_mul_f32_e32 v33, 0xbfb8aa3b, v33
	v_mul_f32_e32 v34, 0xbfb8aa3b, v34
	v_mul_f32_e32 v35, 0xbfb8aa3b, v35
	v_exp_f32_e32 v32, v32
	v_exp_f32_e32 v33, v33
	v_exp_f32_e32 v34, v34
	v_exp_f32_e32 v35, v35
	v_add_f32_e32 v32, 1.0, v32
	v_add_f32_e32 v33, 1.0, v33
	v_add_f32_e32 v34, 1.0, v34
	v_add_f32_e32 v35, 1.0, v35
	v_rcp_f32_e32 v32, v32
	v_rcp_f32_e32 v33, v33
	v_rcp_f32_e32 v34, v34
	v_rcp_f32_e32 v35, v35
	v_pk_mul_f32 v[32:33], v[32:33], s[22:23] op_sel_hi:[1,0]
	s_nop 0
	v_cvt_pk_f16_f32 v32, v32, v33
	v_pk_mul_f32 v[34:35], v[34:35], s[22:23] op_sel_hi:[1,0]
	s_nop 0
	v_cvt_pk_f16_f32 v33, v34, v35
	v_mov_b32_e32 v242, v32
	v_mov_b32_e32 v243, v33
	s_nop 0
	s_waitcnt vmcnt(4)
; __device__ __forceinline__ float sigm(float x) { return __builtin_amdgcn_rcpf(1.f + __builtin_amdgcn_exp2f(-LOG2E * x)); }
; __device__ __forceinline__ void epi_decay(const f32x16 (&acc)[2][2], int nbase, int tbase, int M, const float* w0, u16* DIR) {
;     ...
; #pragma unroll
;   for (int tb = 0; tb < 2; ++tb) {
;     const int tok = tbase + tb * 32 + l32;
;     if (tok < M) {
;       u16* dst = DIR + ((size_t)tok * 16 + head) * 192;
; #pragma unroll
;       for (int nb = 0; nb < 2; ++nb)
; #pragma unroll
;         for (int i = 0; i < 4; ++i) {
;           const int c = nb * 32 + 8 * i + 4 * h;
;           const f32x4 w = *(const f32x4*)(w0 + nbase + c);
;           float o[4];
; #pragma unroll
;           for (int j = 0; j < 4; ++j) o[j] = 0.6065306597126334f * sigm(w[j] + acc[nb][tb][4 * i + j]);
;           *(u32x2*)(dst + c) = (u32x2){pk_f16(o[0], o[1]), pk_f16(o[2], o[3])};
;         }
;     }
;   }
	v_add_f32_e32 v32, v36, v138
	v_add_f32_e32 v33, v37, v139
	v_add_f32_e32 v34, v38, v140
	v_add_f32_e32 v35, v39, v141
	v_mul_f32_e32 v32, 0xbfb8aa3b, v32
	v_mul_f32_e32 v33, 0xbfb8aa3b, v33
	v_mul_f32_e32 v34, 0xbfb8aa3b, v34
	v_mul_f32_e32 v35, 0xbfb8aa3b, v35
	v_exp_f32_e32 v32, v32
	v_exp_f32_e32 v33, v33
	v_exp_f32_e32 v34, v34
	v_exp_f32_e32 v35, v35
	v_add_f32_e32 v32, 1.0, v32
	v_add_f32_e32 v33, 1.0, v33
	v_add_f32_e32 v34, 1.0, v34
	v_add_f32_e32 v35, 1.0, v35
	v_rcp_f32_e32 v32, v32
	v_rcp_f32_e32 v33, v33
	v_rcp_f32_e32 v34, v34
	v_rcp_f32_e32 v35, v35
	v_pk_mul_f32 v[32:33], v[32:33], s[22:23] op_sel_hi:[1,0]
	s_nop 0
	v_cvt_pk_f16_f32 v32, v32, v33
	v_pk_mul_f32 v[34:35], v[34:35], s[22:23] op_sel_hi:[1,0]
	s_nop 0
	v_cvt_pk_f16_f32 v33, v34, v35
	v_mov_b32_e32 v244, v32
	v_mov_b32_e32 v245, v33
	s_nop 1
	v_permlane32_swap_b32_e32 v242, v244
	v_permlane32_swap_b32_e32 v243, v245
	global_store_dwordx4 v[238:239], v[242:245], off offset:64
	s_nop 0
	s_waitcnt vmcnt(4)
	v_add_f32_e32 v32, v40, v142
	v_add_f32_e32 v33, v41, v143
	v_add_f32_e32 v34, v42, v144
	v_add_f32_e32 v35, v43, v145
	v_mul_f32_e32 v32, 0xbfb8aa3b, v32
	v_mul_f32_e32 v33, 0xbfb8aa3b, v33
	v_mul_f32_e32 v34, 0xbfb8aa3b, v34
	v_mul_f32_e32 v35, 0xbfb8aa3b, v35
	v_exp_f32_e32 v32, v32
	v_exp_f32_e32 v33, v33
	v_exp_f32_e32 v34, v34
	v_exp_f32_e32 v35, v35
	v_add_f32_e32 v32, 1.0, v32
	v_add_f32_e32 v33, 1.0, v33
	v_add_f32_e32 v34, 1.0, v34
	v_add_f32_e32 v35, 1.0, v35
	v_rcp_f32_e32 v32, v32
	v_rcp_f32_e32 v33, v33
	v_rcp_f32_e32 v34, v34
	v_rcp_f32_e32 v35, v35
	v_pk_mul_f32 v[32:33], v[32:33], s[22:23] op_sel_hi:[1,0]
	s_nop 0
	v_cvt_pk_f16_f32 v32, v32, v33
	v_pk_mul_f32 v[34:35], v[34:35], s[22:23] op_sel_hi:[1,0]
	s_nop 0
	v_cvt_pk_f16_f32 v33, v34, v35
	v_mov_b32_e32 v246, v32
	v_mov_b32_e32 v247, v33
	s_nop 0
	s_waitcnt vmcnt(3)
	v_add_f32_e32 v32, v44, v146
	v_add_f32_e32 v33, v45, v147
	v_add_f32_e32 v34, v46, v148
	v_add_f32_e32 v35, v47, v149
	v_mul_f32_e32 v32, 0xbfb8aa3b, v32
	v_mul_f32_e32 v33, 0xbfb8aa3b, v33
	v_mul_f32_e32 v34, 0xbfb8aa3b, v34
	v_mul_f32_e32 v35, 0xbfb8aa3b, v35
	v_exp_f32_e32 v32, v32
	v_exp_f32_e32 v33, v33
	v_exp_f32_e32 v34, v34
	v_exp_f32_e32 v35, v35
	v_add_f32_e32 v32, 1.0, v32
	v_add_f32_e32 v33, 1.0, v33
	v_add_f32_e32 v34, 1.0, v34
	v_add_f32_e32 v35, 1.0, v35
	v_rcp_f32_e32 v32, v32
	v_rcp_f32_e32 v33, v33
	v_rcp_f32_e32 v34, v34
	v_rcp_f32_e32 v35, v35
	v_pk_mul_f32 v[32:33], v[32:33], s[22:23] op_sel_hi:[1,0]
	s_nop 0
	v_cvt_pk_f16_f32 v32, v32, v33
	v_pk_mul_f32 v[34:35], v[34:35], s[22:23] op_sel_hi:[1,0]
	s_nop 0
	v_cvt_pk_f16_f32 v33, v34, v35
	v_mov_b32_e32 v248, v32
	v_mov_b32_e32 v249, v33
	s_nop 1
	v_permlane32_swap_b32_e32 v246, v248
	v_permlane32_swap_b32_e32 v247, v249
	global_store_dwordx4 v[238:239], v[246:249], off offset:96
.LBB0_485:
	s_or_b64 exec, exec, s[48:49]
	v_or_b32_e32 v32, 32, v74
	v_cmp_gt_i32_e64 s[40:41], s72, v32
	s_and_saveexec_b64 s[48:49], s[40:41]
	s_cbranch_execz .LBB0_476
	v_ashrrev_i32_e32 v33, 31, v32
	v_lshl_add_u64 v[32:33], v[32:33], 4, v[72:73]
	v_mov_b64_e32 v[34:35], s[42:43]
	v_mad_u64_u32 v[38:39], s[0:1], v32, s75, v[34:35]
	v_mad_i32_i24 v39, v33, s75, v39
	v_lshl_add_u64 v[32:33], v[70:71], 0, v[160:161]
	global_load_dwordx4 v[118:121], v[32:33], off
	global_load_dwordx4 v[122:125], v[32:33], off offset:32
	global_load_dwordx4 v[126:129], v[32:33], off offset:64
	global_load_dwordx4 v[130:133], v[32:33], off offset:96
	global_load_dwordx4 v[134:137], v[32:33], off offset:128
	global_load_dwordx4 v[138:141], v[32:33], off offset:160
	global_load_dwordx4 v[142:145], v[32:33], off offset:192
	global_load_dwordx4 v[146:149], v[32:33], off offset:224
	v_mov_b32_e32 v69, v161
	s_waitcnt vmcnt(7)
	v_add_f32_e32 v16, v16, v118
	v_add_f32_e32 v17, v17, v119
	v_add_f32_e32 v18, v18, v120
	v_add_f32_e32 v19, v19, v121
	v_mul_f32_e32 v16, 0xbfb8aa3b, v16
	v_mul_f32_e32 v17, 0xbfb8aa3b, v17
	v_mul_f32_e32 v18, 0xbfb8aa3b, v18
	v_mul_f32_e32 v19, 0xbfb8aa3b, v19
	v_exp_f32_e32 v16, v16
	v_exp_f32_e32 v17, v17
	v_exp_f32_e32 v18, v18
	v_exp_f32_e32 v19, v19
	v_add_f32_e32 v16, 1.0, v16
	v_add_f32_e32 v17, 1.0, v17
	v_add_f32_e32 v18, 1.0, v18
	v_add_f32_e32 v19, 1.0, v19
	v_rcp_f32_e32 v16, v16
	v_rcp_f32_e32 v17, v17
	v_rcp_f32_e32 v18, v18
	v_rcp_f32_e32 v19, v19
	v_pk_mul_f32 v[16:17], v[16:17], s[22:23] op_sel_hi:[1,0]
	s_nop 0
	v_cvt_pk_f16_f32 v34, v16, v17
	v_pk_mul_f32 v[18:19], v[18:19], s[22:23] op_sel_hi:[1,0]
	v_lshl_add_u64 v[16:17], v[38:39], 0, v[68:69]
	v_cvt_pk_f16_f32 v35, v18, v19
	v_mbcnt_lo_u32_b32 v238, -1, 0
	v_mbcnt_hi_u32_b32 v238, -1, v238
	v_lshrrev_b32_e32 v238, 2, v238
	v_and_b32_e32 v238, 8, v238
	v_mov_b32_e32 v239, 0
	v_lshl_add_u64 v[238:239], v[16:17], 0, v[238:239]
	v_mov_b32_e32 v222, v34
	v_mov_b32_e32 v223, v35
	s_nop 0
	s_waitcnt vmcnt(6)
	v_add_f32_e32 v18, v20, v122
	v_add_f32_e32 v19, v21, v123
	v_add_f32_e32 v20, v22, v124
	v_add_f32_e32 v21, v23, v125
	v_mul_f32_e32 v18, 0xbfb8aa3b, v18
	v_mul_f32_e32 v19, 0xbfb8aa3b, v19
	v_mul_f32_e32 v20, 0xbfb8aa3b, v20
	v_mul_f32_e32 v21, 0xbfb8aa3b, v21
	v_exp_f32_e32 v18, v18
	v_exp_f32_e32 v19, v19
	v_exp_f32_e32 v20, v20
	v_exp_f32_e32 v21, v21
	v_add_f32_e32 v18, 1.0, v18
	v_add_f32_e32 v19, 1.0, v19
	v_add_f32_e32 v20, 1.0, v20
	v_add_f32_e32 v21, 1.0, v21
	v_rcp_f32_e32 v18, v18
	v_rcp_f32_e32 v19, v19
	v_rcp_f32_e32 v20, v20
	v_rcp_f32_e32 v21, v21
	v_pk_mul_f32 v[18:19], v[18:19], s[22:23] op_sel_hi:[1,0]
	s_nop 0
	v_cvt_pk_f16_f32 v18, v18, v19
	v_pk_mul_f32 v[20:21], v[20:21], s[22:23] op_sel_hi:[1,0]
	s_nop 0
	v_cvt_pk_f16_f32 v19, v20, v21
	v_mov_b32_e32 v224, v18
	v_mov_b32_e32 v225, v19
	s_nop 1
	v_permlane32_swap_b32_e32 v222, v224
	v_permlane32_swap_b32_e32 v223, v225
	global_store_dwordx4 v[238:239], v[222:225], off
	s_nop 0
	s_waitcnt vmcnt(6)
; __device__ __forceinline__ float sigm(float x) { return __builtin_amdgcn_rcpf(1.f + __builtin_amdgcn_exp2f(-LOG2E * x)); }
; __device__ __forceinline__ void epi_decay(const f32x16 (&acc)[2][2], int nbase, int tbase, int M, const float* w0, u16* DIR) {
;     ...
; #pragma unroll
;   for (int tb = 0; tb < 2; ++tb) {
;     const int tok = tbase + tb * 32 + l32;
;     if (tok < M) {
;       u16* dst = DIR + ((size_t)tok * 16 + head) * 192;
; #pragma unroll
;       for (int nb = 0; nb < 2; ++nb)
; #pragma unroll
;         for (int i = 0; i < 4; ++i) {
;           const int c = nb * 32 + 8 * i + 4 * h;
;           const f32x4 w = *(const f32x4*)(w0 + nbase + c);
;           float o[4];
; #pragma unroll
;           for (int j = 0; j < 4; ++j) o[j] = 0.6065306597126334f * sigm(w[j] + acc[nb][tb][4 * i + j]);
;           *(u32x2*)(dst + c) = (u32x2){pk_f16(o[0], o[1]), pk_f16(o[2], o[3])};
;         }
;     }
;   }
	v_add_f32_e32 v18, v24, v126
	v_add_f32_e32 v19, v25, v127
	v_add_f32_e32 v20, v26, v128
	v_add_f32_e32 v21, v27, v129
	v_mul_f32_e32 v18, 0xbfb8aa3b, v18
	v_mul_f32_e32 v19, 0xbfb8aa3b, v19
	v_mul_f32_e32 v20, 0xbfb8aa3b, v20
	v_mul_f32_e32 v21, 0xbfb8aa3b, v21
	v_exp_f32_e32 v18, v18
	v_exp_f32_e32 v19, v19
	v_exp_f32_e32 v20, v20
	v_exp_f32_e32 v21, v21
	v_add_f32_e32 v18, 1.0, v18
	v_add_f32_e32 v19, 1.0, v19
	v_add_f32_e32 v20, 1.0, v20
	v_add_f32_e32 v21, 1.0, v21
	v_rcp_f32_e32 v18, v18
	v_rcp_f32_e32 v19, v19
	v_rcp_f32_e32 v20, v20
	v_rcp_f32_e32 v21, v21
	v_pk_mul_f32 v[18:19], v[18:19], s[22:23] op_sel_hi:[1,0]
	s_nop 0
	v_cvt_pk_f16_f32 v18, v18, v19
	v_pk_mul_f32 v[20:21], v[20:21], s[22:23] op_sel_hi:[1,0]
	s_nop 0
	v_cvt_pk_f16_f32 v19, v20, v21
	v_mov_b32_e32 v226, v18
	v_mov_b32_e32 v227, v19
	s_nop 0
	s_waitcnt vmcnt(5)
	v_add_f32_e32 v18, v28, v130
	v_add_f32_e32 v19, v29, v131
	v_add_f32_e32 v20, v30, v132
	v_add_f32_e32 v21, v31, v133
	v_mul_f32_e32 v18, 0xbfb8aa3b, v18
	v_mul_f32_e32 v19, 0xbfb8aa3b, v19
	v_mul_f32_e32 v20, 0xbfb8aa3b, v20
	v_mul_f32_e32 v21, 0xbfb8aa3b, v21
	v_exp_f32_e32 v18, v18
	v_exp_f32_e32 v19, v19
	v_exp_f32_e32 v20, v20
	v_exp_f32_e32 v21, v21
	v_add_f32_e32 v18, 1.0, v18
	v_add_f32_e32 v19, 1.0, v19
	v_add_f32_e32 v20, 1.0, v20
	v_add_f32_e32 v21, 1.0, v21
	v_rcp_f32_e32 v18, v18
	v_rcp_f32_e32 v19, v19
	v_rcp_f32_e32 v20, v20
	v_rcp_f32_e32 v21, v21
	v_pk_mul_f32 v[18:19], v[18:19], s[22:23] op_sel_hi:[1,0]
	s_nop 0
	v_cvt_pk_f16_f32 v18, v18, v19
	v_pk_mul_f32 v[20:21], v[20:21], s[22:23] op_sel_hi:[1,0]
	s_nop 0
	v_cvt_pk_f16_f32 v19, v20, v21
	v_mov_b32_e32 v228, v18
	v_mov_b32_e32 v229, v19
	s_nop 1
	v_permlane32_swap_b32_e32 v226, v228
	v_permlane32_swap_b32_e32 v227, v229
	global_store_dwordx4 v[238:239], v[226:229], off offset:32
	s_nop 0
	s_waitcnt vmcnt(5)
	v_add_f32_e32 v0, v0, v134
	v_add_f32_e32 v1, v1, v135
	v_add_f32_e32 v2, v2, v136
	v_add_f32_e32 v3, v3, v137
	v_mul_f32_e32 v0, 0xbfb8aa3b, v0
	v_mul_f32_e32 v1, 0xbfb8aa3b, v1
	v_mul_f32_e32 v2, 0xbfb8aa3b, v2
	v_mul_f32_e32 v3, 0xbfb8aa3b, v3
	v_exp_f32_e32 v0, v0
	v_exp_f32_e32 v1, v1
	v_exp_f32_e32 v2, v2
	v_exp_f32_e32 v3, v3
	v_add_f32_e32 v0, 1.0, v0
	v_add_f32_e32 v1, 1.0, v1
	v_add_f32_e32 v2, 1.0, v2
	v_add_f32_e32 v3, 1.0, v3
	v_rcp_f32_e32 v0, v0
	v_rcp_f32_e32 v1, v1
	v_rcp_f32_e32 v2, v2
	v_rcp_f32_e32 v3, v3
	v_pk_mul_f32 v[0:1], v[0:1], s[22:23] op_sel_hi:[1,0]
	s_nop 0
	v_cvt_pk_f16_f32 v0, v0, v1
	v_pk_mul_f32 v[2:3], v[2:3], s[22:23] op_sel_hi:[1,0]
	s_nop 0
	v_cvt_pk_f16_f32 v1, v2, v3
	v_mov_b32_e32 v230, v0
	v_mov_b32_e32 v231, v1
	s_nop 0
	s_waitcnt vmcnt(4)
	v_add_f32_e32 v0, v4, v138
	v_add_f32_e32 v1, v5, v139
	v_add_f32_e32 v2, v6, v140
	v_add_f32_e32 v3, v7, v141
	v_mul_f32_e32 v0, 0xbfb8aa3b, v0
	v_mul_f32_e32 v1, 0xbfb8aa3b, v1
	v_mul_f32_e32 v2, 0xbfb8aa3b, v2
	v_mul_f32_e32 v3, 0xbfb8aa3b, v3
	v_exp_f32_e32 v0, v0
	v_exp_f32_e32 v1, v1
	v_exp_f32_e32 v2, v2
	v_exp_f32_e32 v3, v3
	v_add_f32_e32 v0, 1.0, v0
	v_add_f32_e32 v1, 1.0, v1
	v_add_f32_e32 v2, 1.0, v2
	v_add_f32_e32 v3, 1.0, v3
	v_rcp_f32_e32 v0, v0
	v_rcp_f32_e32 v1, v1
	v_rcp_f32_e32 v2, v2
	v_rcp_f32_e32 v3, v3
	v_pk_mul_f32 v[0:1], v[0:1], s[22:23] op_sel_hi:[1,0]
	s_nop 0
	v_cvt_pk_f16_f32 v0, v0, v1
	v_pk_mul_f32 v[2:3], v[2:3], s[22:23] op_sel_hi:[1,0]
	s_nop 0
	v_cvt_pk_f16_f32 v1, v2, v3
	v_mov_b32_e32 v232, v0
	v_mov_b32_e32 v233, v1
	s_nop 1
	v_permlane32_swap_b32_e32 v230, v232
	v_permlane32_swap_b32_e32 v231, v233
	global_store_dwordx4 v[238:239], v[230:233], off offset:64
	s_nop 0
	s_waitcnt vmcnt(4)
	v_add_f32_e32 v0, v8, v142
	v_add_f32_e32 v1, v9, v143
	v_add_f32_e32 v2, v10, v144
	v_add_f32_e32 v3, v11, v145
	v_mul_f32_e32 v0, 0xbfb8aa3b, v0
	v_mul_f32_e32 v1, 0xbfb8aa3b, v1
	v_mul_f32_e32 v2, 0xbfb8aa3b, v2
	v_mul_f32_e32 v3, 0xbfb8aa3b, v3
	v_exp_f32_e32 v0, v0
	v_exp_f32_e32 v1, v1
	v_exp_f32_e32 v2, v2
	v_exp_f32_e32 v3, v3
	v_add_f32_e32 v0, 1.0, v0
	v_add_f32_e32 v1, 1.0, v1
	v_add_f32_e32 v2, 1.0, v2
	v_add_f32_e32 v3, 1.0, v3
	v_rcp_f32_e32 v0, v0
	v_rcp_f32_e32 v1, v1
	v_rcp_f32_e32 v2, v2
	v_rcp_f32_e32 v3, v3
	v_pk_mul_f32 v[0:1], v[0:1], s[22:23] op_sel_hi:[1,0]
	s_nop 0
	v_cvt_pk_f16_f32 v0, v0, v1
	v_pk_mul_f32 v[2:3], v[2:3], s[22:23] op_sel_hi:[1,0]
	s_nop 0
	v_cvt_pk_f16_f32 v1, v2, v3
	v_mov_b32_e32 v234, v0
	v_mov_b32_e32 v235, v1
	s_nop 0
	s_waitcnt vmcnt(3)
	v_add_f32_e32 v0, v12, v146
	v_add_f32_e32 v1, v13, v147
	v_add_f32_e32 v2, v14, v148
	v_add_f32_e32 v3, v15, v149
	v_mul_f32_e32 v0, 0xbfb8aa3b, v0
	v_mul_f32_e32 v1, 0xbfb8aa3b, v1
	v_mul_f32_e32 v2, 0xbfb8aa3b, v2
	v_mul_f32_e32 v3, 0xbfb8aa3b, v3
	v_exp_f32_e32 v0, v0
	v_exp_f32_e32 v1, v1
	v_exp_f32_e32 v2, v2
	v_exp_f32_e32 v3, v3
	v_add_f32_e32 v0, 1.0, v0
	v_add_f32_e32 v1, 1.0, v1
	v_add_f32_e32 v2, 1.0, v2
	v_add_f32_e32 v3, 1.0, v3
	v_rcp_f32_e32 v0, v0
	v_rcp_f32_e32 v1, v1
	v_rcp_f32_e32 v2, v2
	v_rcp_f32_e32 v3, v3
	v_pk_mul_f32 v[0:1], v[0:1], s[22:23] op_sel_hi:[1,0]
	s_nop 0
	v_cvt_pk_f16_f32 v0, v0, v1
	v_pk_mul_f32 v[2:3], v[2:3], s[22:23] op_sel_hi:[1,0]
	s_nop 0
	v_cvt_pk_f16_f32 v1, v2, v3
	v_mov_b32_e32 v236, v0
	v_mov_b32_e32 v237, v1
	s_nop 1
	v_permlane32_swap_b32_e32 v234, v236
	v_permlane32_swap_b32_e32 v235, v237
	global_store_dwordx4 v[238:239], v[234:237], off offset:96
	s_branch .LBB0_476

; __device__ __forceinline__ float h_lo(unsigned u) { f16x2_t r = __builtin_bit_cast(f16x2_t, u); return (float)r.x; }
; __device__ __forceinline__ float h_hi(unsigned u) { f16x2_t r = __builtin_bit_cast(f16x2_t, u); return (float)r.y; }
; __device__ __forceinline__ void epi_adir(const f32x16 (&acc)[2][2], int nbase, int tbase, int M, CP& p, int dir) {
;     ...
;   for (int tb = 0; tb < 2; ++tb) {
;     const int tok = tbase + tb * 32 + l32;
;     const bool valid = tok < M;
;     const int tk = valid ? tok : M - 1;
;     const size_t rec = ((size_t)tk * 16 + head) * 192;
;     float nsq = 0.f;
; #pragma unroll
;     for (int nb = 0; nb < 2; ++nb)
; #pragma unroll
;       for (int i = 0; i < 4; ++i) {
;         const int c = nb * 32 + 8 * i + 4 * h;
;         const u32x2 kr = *(const u32x2*)(DIR + rec + 64 + c);
;         const f32x4 kkw = *(const f32x4*)(p.k_k + nbase + c);
;         const float q0 = h_lo(kr.x) * kkw[0], q1 = h_hi(kr.x) * kkw[1], q2 = h_lo(kr.y) * kkw[2], q3 = h_hi(kr.y) * kkw[3];
;         nsq += q0 * q0 + q1 * q1 + q2 * q2 + q3 * q3;
;       }
;     nsq += __shfl_xor(nsq, 32);
;     const float inv = 1.f / fmaxf(sqrtf(nsq), 1e-12f);
.LBB0_500:
	s_or_b64 exec, exec, s[6:7]
	v_mov_b32_e32 v66, v204
	s_load_dwordx2 s[0:1], s[64:65], 0xa0
	v_lshl_add_u32 v65, v65, 7, v92
	v_lshl_or_b32 v64, v64, 7, v99
	v_and_or_b32 v103, v66, 31, v65
	v_lshrrev_b32_e32 v65, 3, v66
	v_and_b32_e32 v70, 4, v65
	v_ashrrev_i32_e32 v65, 31, v64
	v_ashrrev_i32_e32 v84, 6, v64
	v_lshlrev_b64 v[64:65], 2, v[64:65]
	v_lshl_add_u64 v[66:67], s[48:49], 0, v[64:65]
	v_lshl_add_u64 v[78:79], s[50:51], 0, v[64:65]
	s_waitcnt lgkmcnt(0)
	v_lshl_add_u64 v[80:81], s[0:1], 0, v[64:65]
	v_min_i32_e32 v64, s53, v103
	v_ashrrev_i32_e32 v85, 31, v84
	v_ashrrev_i32_e32 v65, 31, v64
	v_lshl_add_u64 v[64:65], v[64:65], 4, v[84:85]
	v_and_b32_e32 v69, 64, v211
	v_mad_u64_u32 v[88:89], s[0:1], v64, s78, 0
	v_xor_b32_e32 v68, 32, v211
	v_add_u32_e32 v69, 64, v69
	v_mad_i32_i24 v89, v65, s78, v89
	v_cmp_lt_i32_e32 vcc, v68, v69
	v_lshl_add_u64 v[64:65], v[88:89], 1, s[46:47]
	v_lshlrev_b32_e32 v160, 1, v70
	v_cndmask_b32_e32 v68, v211, v68, vcc
	v_lshl_add_u64 v[86:87], v[64:65], 0, v[160:161]
	v_lshlrev_b32_e32 v102, 2, v68
	global_load_dwordx2 v[68:69], v[86:87], off offset:128
	v_lshlrev_b32_e32 v82, 2, v70
	v_mov_b32_e32 v83, v161
	v_lshl_add_u64 v[76:77], v[66:67], 0, v[82:83]
	global_load_dwordx4 v[64:67], v[76:77], off
	v_cmp_gt_i32_e32 vcc, s72, v103
	s_waitcnt vmcnt(1)
	v_cvt_f32_f16_e32 v70, v68
	v_cvt_f32_f16_sdwa v68, v68 dst_sel:DWORD dst_unused:UNUSED_PAD src0_sel:WORD_1
	v_cvt_f32_f16_e32 v71, v69
	v_cvt_f32_f16_sdwa v69, v69 dst_sel:DWORD dst_unused:UNUSED_PAD src0_sel:WORD_1
	s_waitcnt vmcnt(0)
	v_mul_f32_e32 v70, v64, v70
	v_mul_f32_e32 v68, v65, v68
	v_mul_f32_e32 v104, v68, v68
	v_mul_f32_e32 v71, v66, v71
	v_fmac_f32_e32 v104, v70, v70
	v_mul_f32_e32 v69, v67, v69
	v_fmac_f32_e32 v104, v71, v71
	v_fmac_f32_e32 v104, v69, v69
	global_load_dwordx2 v[90:91], v[86:87], off offset:144
	global_load_dwordx4 v[68:71], v[76:77], off offset:32
	s_waitcnt vmcnt(1)
	v_cvt_f32_f16_e32 v105, v90
	v_cvt_f32_f16_sdwa v90, v90 dst_sel:DWORD dst_unused:UNUSED_PAD src0_sel:WORD_1
	s_waitcnt vmcnt(0)
	v_mul_f32_e32 v68, v68, v105
	v_mul_f32_e32 v69, v69, v90
	v_cvt_f32_f16_e32 v90, v91
	v_mul_f32_e32 v69, v69, v69
	v_fmac_f32_e32 v69, v68, v68
	v_mul_f32_e32 v70, v70, v90
	v_cvt_f32_f16_sdwa v90, v91 dst_sel:DWORD dst_unused:UNUSED_PAD src0_sel:WORD_1
	v_fmac_f32_e32 v69, v70, v70
	v_mul_f32_e32 v71, v71, v90
	v_fmac_f32_e32 v69, v71, v71
	v_add_f32_e32 v104, v104, v69
	global_load_dwordx2 v[90:91], v[86:87], off offset:160
	global_load_dwordx4 v[68:71], v[76:77], off offset:64
	s_waitcnt vmcnt(1)
	v_cvt_f32_f16_e32 v105, v90
	v_cvt_f32_f16_sdwa v90, v90 dst_sel:DWORD dst_unused:UNUSED_PAD src0_sel:WORD_1
	s_waitcnt vmcnt(0)
	v_mul_f32_e32 v68, v68, v105
	v_mul_f32_e32 v69, v69, v90
	v_cvt_f32_f16_e32 v90, v91
	v_mul_f32_e32 v69, v69, v69
	v_fmac_f32_e32 v69, v68, v68
	v_mul_f32_e32 v70, v70, v90
	v_cvt_f32_f16_sdwa v90, v91 dst_sel:DWORD dst_unused:UNUSED_PAD src0_sel:WORD_1
	v_fmac_f32_e32 v69, v70, v70
	v_mul_f32_e32 v71, v71, v90
	v_fmac_f32_e32 v69, v71, v71
	v_add_f32_e32 v104, v104, v69
	global_load_dwordx2 v[90:91], v[86:87], off offset:176
	global_load_dwordx4 v[68:71], v[76:77], off offset:96
	s_waitcnt vmcnt(1)
	v_cvt_f32_f16_e32 v105, v90
	v_cvt_f32_f16_sdwa v90, v90 dst_sel:DWORD dst_unused:UNUSED_PAD src0_sel:WORD_1
	s_waitcnt vmcnt(0)
	v_mul_f32_e32 v68, v68, v105
	v_mul_f32_e32 v69, v69, v90
	v_cvt_f32_f16_e32 v90, v91
	v_mul_f32_e32 v69, v69, v69
	v_fmac_f32_e32 v69, v68, v68
	v_mul_f32_e32 v70, v70, v90
	v_cvt_f32_f16_sdwa v90, v91 dst_sel:DWORD dst_unused:UNUSED_PAD src0_sel:WORD_1
	v_fmac_f32_e32 v69, v70, v70
	v_mul_f32_e32 v71, v71, v90
	v_fmac_f32_e32 v69, v71, v71
	v_add_f32_e32 v104, v104, v69
	global_load_dwordx2 v[90:91], v[86:87], off offset:192
	global_load_dwordx4 v[68:71], v[76:77], off offset:128
	s_waitcnt vmcnt(1)
	v_cvt_f32_f16_e32 v105, v90
	v_cvt_f32_f16_sdwa v90, v90 dst_sel:DWORD dst_unused:UNUSED_PAD src0_sel:WORD_1
	s_waitcnt vmcnt(0)
	v_mul_f32_e32 v68, v68, v105
	v_mul_f32_e32 v69, v69, v90
	v_cvt_f32_f16_e32 v90, v91
	v_mul_f32_e32 v69, v69, v69
	v_fmac_f32_e32 v69, v68, v68
	v_mul_f32_e32 v70, v70, v90
	v_cvt_f32_f16_sdwa v90, v91 dst_sel:DWORD dst_unused:UNUSED_PAD src0_sel:WORD_1
	v_fmac_f32_e32 v69, v70, v70
	v_mul_f32_e32 v71, v71, v90
	v_fmac_f32_e32 v69, v71, v71
	v_add_f32_e32 v104, v104, v69
	global_load_dwordx2 v[90:91], v[86:87], off offset:208
	global_load_dwordx4 v[68:71], v[76:77], off offset:160
	s_waitcnt vmcnt(1)
	v_cvt_f32_f16_e32 v105, v90
	v_cvt_f32_f16_sdwa v90, v90 dst_sel:DWORD dst_unused:UNUSED_PAD src0_sel:WORD_1
	s_waitcnt vmcnt(0)
	v_mul_f32_e32 v68, v68, v105
	v_mul_f32_e32 v69, v69, v90
	v_cvt_f32_f16_e32 v90, v91
	v_mul_f32_e32 v69, v69, v69
	v_fmac_f32_e32 v69, v68, v68
	v_mul_f32_e32 v70, v70, v90
	v_cvt_f32_f16_sdwa v90, v91 dst_sel:DWORD dst_unused:UNUSED_PAD src0_sel:WORD_1
	v_fmac_f32_e32 v69, v70, v70
	v_mul_f32_e32 v71, v71, v90
	v_fmac_f32_e32 v69, v71, v71
	v_add_f32_e32 v104, v104, v69
	global_load_dwordx2 v[90:91], v[86:87], off offset:224
	global_load_dwordx4 v[68:71], v[76:77], off offset:192
	s_waitcnt vmcnt(1)
	v_cvt_f32_f16_e32 v105, v90
	v_cvt_f32_f16_sdwa v90, v90 dst_sel:DWORD dst_unused:UNUSED_PAD src0_sel:WORD_1
	s_waitcnt vmcnt(0)
	v_mul_f32_e32 v68, v68, v105
	v_mul_f32_e32 v69, v69, v90
	v_cvt_f32_f16_e32 v90, v91
	v_mul_f32_e32 v69, v69, v69
	v_fmac_f32_e32 v69, v68, v68
	v_mul_f32_e32 v70, v70, v90
	v_cvt_f32_f16_sdwa v90, v91 dst_sel:DWORD dst_unused:UNUSED_PAD src0_sel:WORD_1
	v_fmac_f32_e32 v69, v70, v70
	v_mul_f32_e32 v71, v71, v90
	v_fmac_f32_e32 v69, v71, v71
	v_add_f32_e32 v104, v104, v69
	global_load_dwordx2 v[90:91], v[86:87], off offset:240
	global_load_dwordx4 v[68:71], v[76:77], off offset:224
	s_waitcnt vmcnt(1)
	v_cvt_f32_f16_e32 v105, v90
	v_cvt_f32_f16_sdwa v90, v90 dst_sel:DWORD dst_unused:UNUSED_PAD src0_sel:WORD_1
	s_waitcnt vmcnt(0)
	v_mul_f32_e32 v68, v68, v105
	v_mul_f32_e32 v69, v69, v90
	v_cvt_f32_f16_e32 v90, v91
	v_mul_f32_e32 v69, v69, v69
	v_fmac_f32_e32 v69, v68, v68
	v_mul_f32_e32 v70, v70, v90
	v_cvt_f32_f16_sdwa v90, v91 dst_sel:DWORD dst_unused:UNUSED_PAD src0_sel:WORD_1
	v_fmac_f32_e32 v69, v70, v70
	v_mul_f32_e32 v71, v71, v90
	v_fmac_f32_e32 v69, v71, v71
	v_add_f32_e32 v90, v104, v69
	ds_bpermute_b32 v91, v102, v90
	s_and_saveexec_b64 s[34:35], vcc
	s_cbranch_execz .LBB0_502
; __device__ __forceinline__ float h_lo(unsigned u) { f16x2_t r = __builtin_bit_cast(f16x2_t, u); return (float)r.x; }
; __device__ __forceinline__ float h_hi(unsigned u) { f16x2_t r = __builtin_bit_cast(f16x2_t, u); return (float)r.y; }
; __device__ __forceinline__ float sigm(float x) { return __builtin_amdgcn_rcpf(1.f + __builtin_amdgcn_exp2f(-LOG2E * x)); }
; __device__ __forceinline__ void epi_adir(const f32x16 (&acc)[2][2], int nbase, int tbase, int M, CP& p, int dir) {
;     ...
;     if (valid) {
; #pragma unroll
;       for (int nb = 0; nb < 2; ++nb)
; #pragma unroll
;         for (int i = 0; i < 4; ++i) {
;           const int c = nb * 32 + 8 * i + 4 * h;
;           const u32x2 kr = *(const u32x2*)(DIR + rec + 64 + c);
;           const float kv[4] = {h_lo(kr.x), h_hi(kr.x), h_lo(kr.y), h_hi(kr.y)};
;           const f32x4 kkw = *(const f32x4*)(p.k_k + nbase + c);
;           const f32x4 kaw = *(const f32x4*)(p.k_a + nbase + c);
;           const f32x4 a0v = *(const f32x4*)(a0 + nbase + c);
;           float kk[4], kd[4], bp[4];
; #pragma unroll
;           for (int j = 0; j < 4; ++j) {
;             const float k = kv[j];
;             kk[j] = k * kkw[j] * inv;
;             const float aa = sigm(a0v[j] + acc[nb][tb][4 * i + j]);
;             kd[j] = k * (1.f + (aa - 1.f) * kaw[j]);
;             bp[j] = -kk[j] * aa;
;           }
;           if (dir == 0) *(u32x2*)(p.RKV + rec + 64 + c) = (u32x2){pk_f16(kk[0], kk[1]), pk_f16(kk[2], kk[3])};
;           *(u32x2*)(DIR + rec + 64 + c) = (u32x2){pk_f16(kd[0], kd[1]), pk_f16(kd[2], kd[3])};
;           *(u32x2*)(DIR + rec + 128 + c) = (u32x2){pk_f16(bp[0], bp[1]), pk_f16(bp[2], bp[3])};
;         }
	v_lshl_add_u64 v[70:71], v[80:81], 0, v[82:83]
	global_load_dwordx4 v[104:107], v[70:71], off
	global_load_dwordx2 v[112:113], v[86:87], off offset:128
	v_lshl_add_u64 v[68:69], v[78:79], 0, v[82:83]
	global_load_dwordx4 v[108:111], v[68:69], off
	s_waitcnt lgkmcnt(0)
	v_add_f32_e32 v83, v90, v91
	s_mov_b32 s0, 0xf800000
	v_mul_f32_e32 v90, 0x4f800000, v83
	v_cmp_gt_f32_e32 vcc, s0, v83
	v_lshl_add_u64 v[88:89], v[88:89], 1, s[44:45]
	v_lshl_add_u64 v[88:89], v[88:89], 0, v[160:161]
	v_cndmask_b32_e32 v83, v83, v90, vcc
	v_sqrt_f32_e32 v90, v83
	s_waitcnt vmcnt(2)
	v_add_f32_e32 v49, v49, v105
	v_add_u32_e32 v91, -1, v90
	v_add_u32_e32 v114, 1, v90
	v_fma_f32 v115, -v91, v90, v83
	v_fma_f32 v116, -v114, v90, v83
	v_cmp_ge_f32_e64 s[42:43], 0, v115
	s_waitcnt vmcnt(1)
	v_cvt_f32_f16_sdwa v117, v113 dst_sel:DWORD dst_unused:UNUSED_PAD src0_sel:WORD_1
	v_add_f32_e32 v48, v48, v104
	v_cndmask_b32_e64 v90, v90, v91, s[42:43]
	v_cmp_lt_f32_e64 s[42:43], 0, v116
	v_add_f32_e32 v50, v50, v106
	v_add_f32_e32 v51, v51, v107
	v_cndmask_b32_e64 v90, v90, v114, s[42:43]
	v_mul_f32_e32 v91, 0x37800000, v90
	v_cndmask_b32_e32 v90, v90, v91, vcc
	v_cmp_class_f32_e32 vcc, v83, v207
	v_mul_f32_e32 v49, 0xbfb8aa3b, v49
	v_mul_f32_e32 v48, 0xbfb8aa3b, v48
	v_cndmask_b32_e32 v83, v90, v83, vcc
	v_max_f32_e32 v83, 0x2b8cbccc, v83
	v_div_scale_f32 v90, s[0:1], v83, v83, 1.0
	v_rcp_f32_e32 v91, v90
	v_div_scale_f32 v114, vcc, 1.0, v83, 1.0
	v_mul_f32_e32 v50, 0xbfb8aa3b, v50
	v_fma_f32 v115, -v90, v91, 1.0
	v_fmac_f32_e32 v91, v115, v91
	v_mul_f32_e32 v115, v114, v91
	v_fma_f32 v116, -v90, v115, v114
	v_fmac_f32_e32 v115, v116, v91
	v_fma_f32 v90, -v90, v115, v114
	v_div_fmas_f32 v90, v90, v91, v115
	v_cvt_f32_f16_sdwa v115, v112 dst_sel:DWORD dst_unused:UNUSED_PAD src0_sel:WORD_1
	v_cvt_f32_f16_e32 v114, v112
	v_cvt_f32_f16_e32 v116, v113
	v_mul_f32_e32 v51, 0xbfb8aa3b, v51
	v_exp_f32_e32 v91, v49
	v_div_fixup_f32 v90, v90, v83, 1.0
	v_exp_f32_e32 v83, v48
	v_exp_f32_e32 v104, v50
	v_exp_f32_e32 v105, v51
	v_pk_mul_f32 v[48:49], v[64:65], v[114:115]
	v_pk_mul_f32 v[50:51], v[66:67], v[116:117]
	v_pk_mul_f32 v[48:49], v[90:91], v[48:49] op_sel_hi:[0,1]
	v_pk_mul_f32 v[50:51], v[90:91], v[50:51] op_sel_hi:[0,1]
	v_cvt_pk_f16_f32 v64, v48, v49
	v_cvt_pk_f16_f32 v65, v50, v51
	v_add_f32_e32 v66, 1.0, v83
	v_add_f32_e32 v67, 1.0, v91
	v_add_f32_e32 v83, 1.0, v104
	v_add_f32_e32 v91, 1.0, v105
	v_mbcnt_lo_u32_b32 v238, -1, 0
	v_mbcnt_hi_u32_b32 v238, -1, v238
	v_lshrrev_b32_e32 v238, 2, v238
	v_and_b32_e32 v238, 8, v238
	v_mov_b32_e32 v239, 0
	v_lshl_add_u64 v[238:239], v[88:89], 0, v[238:239]
	v_mov_b32_e32 v242, v64
	v_mov_b32_e32 v243, v65
	v_rcp_f32_e32 v64, v66
	v_rcp_f32_e32 v65, v67
	v_rcp_f32_e32 v66, v83
	v_rcp_f32_e32 v67, v91
	global_load_dwordx2 v[112:113], v[86:87], off offset:144
	v_pk_add_f32 v[104:105], v[64:65], -1.0 op_sel_hi:[1,0]
	v_pk_mul_f32 v[48:49], v[64:65], v[48:49] neg_lo:[0,1] neg_hi:[0,1]
	v_pk_add_f32 v[64:65], v[66:67], -1.0 op_sel_hi:[1,0]
	v_pk_mul_f32 v[50:51], v[66:67], v[50:51] neg_lo:[0,1] neg_hi:[0,1]
	s_waitcnt vmcnt(1)
	v_pk_fma_f32 v[66:67], v[108:109], v[104:105], 1.0 op_sel_hi:[1,1,0]
	v_pk_fma_f32 v[64:65], v[110:111], v[64:65], 1.0 op_sel_hi:[1,1,0]
	v_cvt_pk_f16_f32 v48, v48, v49
	v_cvt_pk_f16_f32 v49, v50, v51
	v_pk_mul_f32 v[50:51], v[66:67], v[114:115]
	v_pk_mul_f32 v[64:65], v[64:65], v[116:117]
	v_mbcnt_lo_u32_b32 v240, -1, 0
	v_mbcnt_hi_u32_b32 v240, -1, v240
	v_lshrrev_b32_e32 v240, 2, v240
	v_and_b32_e32 v240, 8, v240
	v_mov_b32_e32 v241, 0
	v_lshl_add_u64 v[240:241], v[86:87], 0, v[240:241]
	v_mov_b32_e32 v246, v48
	v_mov_b32_e32 v247, v49
	v_cvt_pk_f16_f32 v48, v50, v51
	v_cvt_pk_f16_f32 v49, v64, v65
	v_mov_b32_e32 v222, v48
	v_mov_b32_e32 v223, v49
	global_load_dwordx4 v[48:51], v[70:71], off offset:32
	s_nop 0
	global_load_dwordx4 v[64:67], v[76:77], off offset:32
	global_load_dwordx4 v[104:107], v[68:69], off offset:32
	s_waitcnt vmcnt(3)
	v_cvt_f32_f16_sdwa v109, v112 dst_sel:DWORD dst_unused:UNUSED_PAD src0_sel:WORD_1
	v_cvt_f32_f16_e32 v108, v112
	v_cvt_f32_f16_sdwa v111, v113 dst_sel:DWORD dst_unused:UNUSED_PAD src0_sel:WORD_1
	v_cvt_f32_f16_e32 v110, v113
	s_waitcnt vmcnt(2)
	v_add_f32_e32 v52, v52, v48
	v_add_f32_e32 v53, v53, v49
	v_add_f32_e32 v54, v54, v50
	v_add_f32_e32 v55, v55, v51
	s_waitcnt vmcnt(1)
	v_pk_mul_f32 v[64:65], v[64:65], v[108:109]
	v_mul_f32_e32 v52, 0xbfb8aa3b, v52
	v_mul_f32_e32 v53, 0xbfb8aa3b, v53
	v_mul_f32_e32 v54, 0xbfb8aa3b, v54
	v_mul_f32_e32 v55, 0xbfb8aa3b, v55
	v_pk_mul_f32 v[50:51], v[90:91], v[64:65] op_sel_hi:[0,1]
	v_exp_f32_e32 v64, v52
	v_exp_f32_e32 v65, v53
	v_exp_f32_e32 v54, v54
	v_exp_f32_e32 v55, v55
	v_pk_mul_f32 v[48:49], v[66:67], v[110:111]
	v_cvt_pk_f16_f32 v52, v50, v51
	v_pk_mul_f32 v[48:49], v[90:91], v[48:49] op_sel_hi:[0,1]
	v_cvt_pk_f16_f32 v53, v48, v49
	v_mov_b32_e32 v244, v52
	v_mov_b32_e32 v245, v53
	s_nop 1
	v_permlane32_swap_b32_e32 v242, v244
	v_permlane32_swap_b32_e32 v243, v245
	global_store_dwordx4 v[238:239], v[242:245], off offset:128
	v_add_f32_e32 v52, 1.0, v64
	v_add_f32_e32 v53, 1.0, v65
	v_add_f32_e32 v54, 1.0, v54
	v_add_f32_e32 v55, 1.0, v55
	v_rcp_f32_e32 v52, v52
	v_rcp_f32_e32 v53, v53
	v_rcp_f32_e32 v54, v54
	v_rcp_f32_e32 v55, v55
	global_load_dwordx2 v[112:113], v[86:87], off offset:160
	v_pk_add_f32 v[64:65], v[52:53], -1.0 op_sel_hi:[1,0]
	v_pk_mul_f32 v[50:51], v[52:53], v[50:51] neg_lo:[0,1] neg_hi:[0,1]
	v_pk_add_f32 v[52:53], v[54:55], -1.0 op_sel_hi:[1,0]
	v_pk_mul_f32 v[48:49], v[54:55], v[48:49] neg_lo:[0,1] neg_hi:[0,1]
	s_waitcnt vmcnt(2)
; __device__ __forceinline__ float h_lo(unsigned u) { f16x2_t r = __builtin_bit_cast(f16x2_t, u); return (float)r.x; }
; __device__ __forceinline__ float h_hi(unsigned u) { f16x2_t r = __builtin_bit_cast(f16x2_t, u); return (float)r.y; }
; __device__ __forceinline__ float sigm(float x) { return __builtin_amdgcn_rcpf(1.f + __builtin_amdgcn_exp2f(-LOG2E * x)); }
; __device__ __forceinline__ void epi_adir(const f32x16 (&acc)[2][2], int nbase, int tbase, int M, CP& p, int dir) {
;     ...
;       for (int nb = 0; nb < 2; ++nb)
; #pragma unroll
;         for (int i = 0; i < 4; ++i) {
;           const int c = nb * 32 + 8 * i + 4 * h;
;           const u32x2 kr = *(const u32x2*)(DIR + rec + 64 + c);
;           const float kv[4] = {h_lo(kr.x), h_hi(kr.x), h_lo(kr.y), h_hi(kr.y)};
;           const f32x4 kkw = *(const f32x4*)(p.k_k + nbase + c);
;           const f32x4 kaw = *(const f32x4*)(p.k_a + nbase + c);
;           const f32x4 a0v = *(const f32x4*)(a0 + nbase + c);
;           float kk[4], kd[4], bp[4];
; #pragma unroll
;           for (int j = 0; j < 4; ++j) {
;             const float k = kv[j];
;             kk[j] = k * kkw[j] * inv;
;             const float aa = sigm(a0v[j] + acc[nb][tb][4 * i + j]);
;             kd[j] = k * (1.f + (aa - 1.f) * kaw[j]);
;             bp[j] = -kk[j] * aa;
;           }
;           if (dir == 0) *(u32x2*)(p.RKV + rec + 64 + c) = (u32x2){pk_f16(kk[0], kk[1]), pk_f16(kk[2], kk[3])};
;           *(u32x2*)(DIR + rec + 64 + c) = (u32x2){pk_f16(kd[0], kd[1]), pk_f16(kd[2], kd[3])};
;           *(u32x2*)(DIR + rec + 128 + c) = (u32x2){pk_f16(bp[0], bp[1]), pk_f16(bp[2], bp[3])};
;         }
	v_pk_fma_f32 v[54:55], v[104:105], v[64:65], 1.0 op_sel_hi:[1,1,0]
	v_pk_fma_f32 v[52:53], v[106:107], v[52:53], 1.0 op_sel_hi:[1,1,0]
	v_cvt_pk_f16_f32 v50, v50, v51
	v_cvt_pk_f16_f32 v51, v48, v49
	v_pk_mul_f32 v[48:49], v[54:55], v[108:109]
	v_pk_mul_f32 v[52:53], v[52:53], v[110:111]
	v_cvt_pk_f16_f32 v48, v48, v49
	v_cvt_pk_f16_f32 v49, v52, v53
	v_mov_b32_e32 v248, v50
	v_mov_b32_e32 v249, v51
	s_nop 1
	v_permlane32_swap_b32_e32 v246, v248
	v_permlane32_swap_b32_e32 v247, v249
	global_store_dwordx4 v[240:241], v[246:249], off offset:256
	v_mov_b32_e32 v224, v48
	v_mov_b32_e32 v225, v49
	s_nop 1
	v_permlane32_swap_b32_e32 v222, v224
	v_permlane32_swap_b32_e32 v223, v225
	global_store_dwordx4 v[240:241], v[222:225], off offset:128
	global_load_dwordx4 v[48:51], v[70:71], off offset:64
	s_nop 0
	global_load_dwordx4 v[52:55], v[76:77], off offset:64
	global_load_dwordx4 v[64:67], v[68:69], off offset:64
	s_waitcnt vmcnt(5)
	v_cvt_f32_f16_sdwa v105, v112 dst_sel:DWORD dst_unused:UNUSED_PAD src0_sel:WORD_1
	v_cvt_f32_f16_e32 v104, v112
	v_cvt_f32_f16_sdwa v107, v113 dst_sel:DWORD dst_unused:UNUSED_PAD src0_sel:WORD_1
	v_cvt_f32_f16_e32 v106, v113
	s_waitcnt vmcnt(2)
	v_add_f32_e32 v56, v56, v48
	s_waitcnt vmcnt(1)
	v_pk_mul_f32 v[52:53], v[52:53], v[104:105]
	v_add_f32_e32 v57, v57, v49
	v_add_f32_e32 v58, v58, v50
	v_pk_mul_f32 v[48:49], v[54:55], v[106:107]
	v_add_f32_e32 v54, v59, v51
	v_mul_f32_e32 v55, 0xbfb8aa3b, v56
	v_pk_mul_f32 v[50:51], v[90:91], v[52:53] op_sel_hi:[0,1]
	v_mul_f32_e32 v52, 0xbfb8aa3b, v57
	v_mul_f32_e32 v53, 0xbfb8aa3b, v58
	v_mul_f32_e32 v54, 0xbfb8aa3b, v54
	v_exp_f32_e32 v55, v55
	v_exp_f32_e32 v56, v52
	v_exp_f32_e32 v57, v53
	v_exp_f32_e32 v54, v54
	v_pk_mul_f32 v[48:49], v[90:91], v[48:49] op_sel_hi:[0,1]
	v_cvt_pk_f16_f32 v52, v50, v51
	v_cvt_pk_f16_f32 v53, v48, v49
	v_mov_b32_e32 v226, v52
	v_mov_b32_e32 v227, v53
	v_add_f32_e32 v52, 1.0, v55
	v_add_f32_e32 v53, 1.0, v56
	v_add_f32_e32 v55, 1.0, v57
	v_add_f32_e32 v56, 1.0, v54
	v_rcp_f32_e32 v52, v52
	v_rcp_f32_e32 v53, v53
	v_rcp_f32_e32 v54, v55
	v_rcp_f32_e32 v55, v56
	global_load_dwordx2 v[108:109], v[86:87], off offset:176
	v_pk_add_f32 v[56:57], v[52:53], -1.0 op_sel_hi:[1,0]
	v_pk_mul_f32 v[50:51], v[52:53], v[50:51] neg_lo:[0,1] neg_hi:[0,1]
	v_pk_add_f32 v[52:53], v[54:55], -1.0 op_sel_hi:[1,0]
	v_pk_mul_f32 v[48:49], v[54:55], v[48:49] neg_lo:[0,1] neg_hi:[0,1]
	s_waitcnt vmcnt(1)
	v_pk_fma_f32 v[54:55], v[64:65], v[56:57], 1.0 op_sel_hi:[1,1,0]
	v_pk_fma_f32 v[52:53], v[66:67], v[52:53], 1.0 op_sel_hi:[1,1,0]
	v_cvt_pk_f16_f32 v50, v50, v51
	v_cvt_pk_f16_f32 v51, v48, v49
	v_pk_mul_f32 v[48:49], v[54:55], v[104:105]
	v_pk_mul_f32 v[52:53], v[52:53], v[106:107]
	v_cvt_pk_f16_f32 v48, v48, v49
	v_cvt_pk_f16_f32 v49, v52, v53
	v_mov_b32_e32 v230, v50
	v_mov_b32_e32 v231, v51
	v_mov_b32_e32 v234, v48
	v_mov_b32_e32 v235, v49
	global_load_dwordx4 v[48:51], v[70:71], off offset:96
	s_nop 0
	global_load_dwordx4 v[52:55], v[76:77], off offset:96
	global_load_dwordx4 v[56:59], v[68:69], off offset:96
	s_waitcnt vmcnt(3)
	v_cvt_f32_f16_sdwa v65, v108 dst_sel:DWORD dst_unused:UNUSED_PAD src0_sel:WORD_1
	v_cvt_f32_f16_e32 v64, v108
	v_cvt_f32_f16_sdwa v67, v109 dst_sel:DWORD dst_unused:UNUSED_PAD src0_sel:WORD_1
	v_cvt_f32_f16_e32 v66, v109
	s_waitcnt vmcnt(2)
	v_add_f32_e32 v60, v60, v48
	s_waitcnt vmcnt(1)
	v_pk_mul_f32 v[52:53], v[52:53], v[64:65]
	v_add_f32_e32 v61, v61, v49
	v_add_f32_e32 v62, v62, v50
	v_pk_mul_f32 v[48:49], v[54:55], v[66:67]
	v_add_f32_e32 v54, v63, v51
	v_mul_f32_e32 v55, 0xbfb8aa3b, v60
	v_pk_mul_f32 v[50:51], v[90:91], v[52:53] op_sel_hi:[0,1]
	v_mul_f32_e32 v52, 0xbfb8aa3b, v61
	v_mul_f32_e32 v53, 0xbfb8aa3b, v62
	v_mul_f32_e32 v54, 0xbfb8aa3b, v54
	v_exp_f32_e32 v55, v55
	v_exp_f32_e32 v60, v52
	v_exp_f32_e32 v61, v53
	v_exp_f32_e32 v54, v54
	v_pk_mul_f32 v[48:49], v[90:91], v[48:49] op_sel_hi:[0,1]
	v_cvt_pk_f16_f32 v52, v50, v51
	v_cvt_pk_f16_f32 v53, v48, v49
	v_mov_b32_e32 v228, v52
	v_mov_b32_e32 v229, v53
	s_nop 1
	v_permlane32_swap_b32_e32 v226, v228
	v_permlane32_swap_b32_e32 v227, v229
	global_store_dwordx4 v[238:239], v[226:229], off offset:160
	v_add_f32_e32 v52, 1.0, v55
	v_add_f32_e32 v53, 1.0, v60
	v_add_f32_e32 v55, 1.0, v61
	v_add_f32_e32 v60, 1.0, v54
	v_rcp_f32_e32 v52, v52
	v_rcp_f32_e32 v53, v53
	v_rcp_f32_e32 v54, v55
	v_rcp_f32_e32 v55, v60
	global_load_dwordx2 v[60:61], v[86:87], off offset:192
	v_pk_add_f32 v[62:63], v[52:53], -1.0 op_sel_hi:[1,0]
	v_pk_mul_f32 v[50:51], v[52:53], v[50:51] neg_lo:[0,1] neg_hi:[0,1]
	v_pk_add_f32 v[52:53], v[54:55], -1.0 op_sel_hi:[1,0]
	v_pk_mul_f32 v[48:49], v[54:55], v[48:49] neg_lo:[0,1] neg_hi:[0,1]
	s_waitcnt vmcnt(2)
	v_pk_fma_f32 v[54:55], v[56:57], v[62:63], 1.0 op_sel_hi:[1,1,0]
	v_pk_fma_f32 v[52:53], v[58:59], v[52:53], 1.0 op_sel_hi:[1,1,0]
	v_cvt_pk_f16_f32 v50, v50, v51
	v_cvt_pk_f16_f32 v51, v48, v49
	v_pk_mul_f32 v[48:49], v[54:55], v[64:65]
	v_pk_mul_f32 v[52:53], v[52:53], v[66:67]
	v_cvt_pk_f16_f32 v48, v48, v49
	v_cvt_pk_f16_f32 v49, v52, v53
	v_mov_b32_e32 v232, v50
	v_mov_b32_e32 v233, v51
	s_nop 1
	v_permlane32_swap_b32_e32 v230, v232
	v_permlane32_swap_b32_e32 v231, v233
	global_store_dwordx4 v[240:241], v[230:233], off offset:288
	v_mov_b32_e32 v236, v48
	v_mov_b32_e32 v237, v49
	s_nop 1
	v_permlane32_swap_b32_e32 v234, v236
	v_permlane32_swap_b32_e32 v235, v237
	global_store_dwordx4 v[240:241], v[234:237], off offset:160
	global_load_dwordx4 v[48:51], v[70:71], off offset:128
	s_nop 0
	global_load_dwordx4 v[52:55], v[76:77], off offset:128
	global_load_dwordx4 v[56:59], v[68:69], off offset:128
	s_waitcnt vmcnt(5)
; __device__ __forceinline__ float h_lo(unsigned u) { f16x2_t r = __builtin_bit_cast(f16x2_t, u); return (float)r.x; }
; __device__ __forceinline__ float h_hi(unsigned u) { f16x2_t r = __builtin_bit_cast(f16x2_t, u); return (float)r.y; }
; __device__ __forceinline__ float sigm(float x) { return __builtin_amdgcn_rcpf(1.f + __builtin_amdgcn_exp2f(-LOG2E * x)); }
; __device__ __forceinline__ void epi_adir(const f32x16 (&acc)[2][2], int nbase, int tbase, int M, CP& p, int dir) {
;     ...
;       for (int nb = 0; nb < 2; ++nb)
; #pragma unroll
;         for (int i = 0; i < 4; ++i) {
;           const int c = nb * 32 + 8 * i + 4 * h;
;           const u32x2 kr = *(const u32x2*)(DIR + rec + 64 + c);
;           const float kv[4] = {h_lo(kr.x), h_hi(kr.x), h_lo(kr.y), h_hi(kr.y)};
;           const f32x4 kkw = *(const f32x4*)(p.k_k + nbase + c);
;           const f32x4 kaw = *(const f32x4*)(p.k_a + nbase + c);
;           const f32x4 a0v = *(const f32x4*)(a0 + nbase + c);
;           float kk[4], kd[4], bp[4];
; #pragma unroll
;           for (int j = 0; j < 4; ++j) {
;             const float k = kv[j];
;             kk[j] = k * kkw[j] * inv;
;             const float aa = sigm(a0v[j] + acc[nb][tb][4 * i + j]);
;             kd[j] = k * (1.f + (aa - 1.f) * kaw[j]);
;             bp[j] = -kk[j] * aa;
;           }
;           if (dir == 0) *(u32x2*)(p.RKV + rec + 64 + c) = (u32x2){pk_f16(kk[0], kk[1]), pk_f16(kk[2], kk[3])};
;           *(u32x2*)(DIR + rec + 64 + c) = (u32x2){pk_f16(kd[0], kd[1]), pk_f16(kd[2], kd[3])};
;           *(u32x2*)(DIR + rec + 128 + c) = (u32x2){pk_f16(bp[0], bp[1]), pk_f16(bp[2], bp[3])};
;         }
	v_cvt_f32_f16_sdwa v63, v60 dst_sel:DWORD dst_unused:UNUSED_PAD src0_sel:WORD_1
	v_cvt_f32_f16_e32 v62, v60
	v_cvt_f32_f16_sdwa v65, v61 dst_sel:DWORD dst_unused:UNUSED_PAD src0_sel:WORD_1
	v_cvt_f32_f16_e32 v64, v61
	s_waitcnt vmcnt(2)
	v_add_f32_e32 v48, v32, v48
	v_add_f32_e32 v49, v33, v49
	v_add_f32_e32 v50, v34, v50
	v_add_f32_e32 v51, v35, v51
	s_waitcnt vmcnt(1)
	v_pk_mul_f32 v[52:53], v[52:53], v[62:63]
	v_mul_f32_e32 v48, 0xbfb8aa3b, v48
	v_mul_f32_e32 v49, 0xbfb8aa3b, v49
	v_mul_f32_e32 v50, 0xbfb8aa3b, v50
	v_mul_f32_e32 v51, 0xbfb8aa3b, v51
	v_pk_mul_f32 v[34:35], v[90:91], v[52:53] op_sel_hi:[0,1]
	v_exp_f32_e32 v52, v48
	v_exp_f32_e32 v53, v49
	v_exp_f32_e32 v50, v50
	v_exp_f32_e32 v51, v51
	v_pk_mul_f32 v[32:33], v[54:55], v[64:65]
	v_cvt_pk_f16_f32 v48, v34, v35
	v_pk_mul_f32 v[32:33], v[90:91], v[32:33] op_sel_hi:[0,1]
	v_cvt_pk_f16_f32 v49, v32, v33
	v_mov_b32_e32 v242, v48
	v_mov_b32_e32 v243, v49
	v_add_f32_e32 v48, 1.0, v52
	v_add_f32_e32 v49, 1.0, v53
	v_add_f32_e32 v50, 1.0, v50
	v_add_f32_e32 v51, 1.0, v51
	v_rcp_f32_e32 v48, v48
	v_rcp_f32_e32 v49, v49
	v_rcp_f32_e32 v50, v50
	v_rcp_f32_e32 v51, v51
	global_load_dwordx2 v[60:61], v[86:87], off offset:208
	v_pk_add_f32 v[52:53], v[48:49], -1.0 op_sel_hi:[1,0]
	v_pk_mul_f32 v[34:35], v[48:49], v[34:35] neg_lo:[0,1] neg_hi:[0,1]
	v_pk_add_f32 v[48:49], v[50:51], -1.0 op_sel_hi:[1,0]
	v_pk_mul_f32 v[32:33], v[50:51], v[32:33] neg_lo:[0,1] neg_hi:[0,1]
	s_waitcnt vmcnt(1)
	v_pk_fma_f32 v[50:51], v[56:57], v[52:53], 1.0 op_sel_hi:[1,1,0]
	v_pk_fma_f32 v[48:49], v[58:59], v[48:49], 1.0 op_sel_hi:[1,1,0]
	v_cvt_pk_f16_f32 v34, v34, v35
	v_cvt_pk_f16_f32 v35, v32, v33
	v_pk_mul_f32 v[32:33], v[50:51], v[62:63]
	v_pk_mul_f32 v[48:49], v[48:49], v[64:65]
	v_cvt_pk_f16_f32 v32, v32, v33
	v_cvt_pk_f16_f32 v33, v48, v49
	v_mov_b32_e32 v246, v34
	v_mov_b32_e32 v247, v35
	v_mov_b32_e32 v222, v32
	v_mov_b32_e32 v223, v33
	global_load_dwordx4 v[32:35], v[70:71], off offset:160
	s_nop 0
	global_load_dwordx4 v[48:51], v[76:77], off offset:160
	global_load_dwordx4 v[52:55], v[68:69], off offset:160
	s_waitcnt vmcnt(3)
	v_cvt_f32_f16_sdwa v57, v60 dst_sel:DWORD dst_unused:UNUSED_PAD src0_sel:WORD_1
	v_cvt_f32_f16_e32 v56, v60
	v_cvt_f32_f16_sdwa v59, v61 dst_sel:DWORD dst_unused:UNUSED_PAD src0_sel:WORD_1
	v_cvt_f32_f16_e32 v58, v61
	s_waitcnt vmcnt(2)
	v_add_f32_e32 v36, v36, v32
	v_add_f32_e32 v37, v37, v33
	v_add_f32_e32 v38, v38, v34
	v_add_f32_e32 v39, v39, v35
	s_waitcnt vmcnt(1)
	v_pk_mul_f32 v[48:49], v[48:49], v[56:57]
	v_mul_f32_e32 v36, 0xbfb8aa3b, v36
	v_mul_f32_e32 v37, 0xbfb8aa3b, v37
	v_mul_f32_e32 v38, 0xbfb8aa3b, v38
	v_mul_f32_e32 v39, 0xbfb8aa3b, v39
	v_pk_mul_f32 v[34:35], v[90:91], v[48:49] op_sel_hi:[0,1]
	v_exp_f32_e32 v48, v36
	v_exp_f32_e32 v49, v37
	v_exp_f32_e32 v38, v38
	v_exp_f32_e32 v39, v39
	v_pk_mul_f32 v[32:33], v[50:51], v[58:59]
	v_cvt_pk_f16_f32 v36, v34, v35
	v_pk_mul_f32 v[32:33], v[90:91], v[32:33] op_sel_hi:[0,1]
	v_cvt_pk_f16_f32 v37, v32, v33
	v_mov_b32_e32 v244, v36
	v_mov_b32_e32 v245, v37
	s_nop 1
	v_permlane32_swap_b32_e32 v242, v244
	v_permlane32_swap_b32_e32 v243, v245
	global_store_dwordx4 v[238:239], v[242:245], off offset:192
	v_add_f32_e32 v36, 1.0, v48
	v_add_f32_e32 v37, 1.0, v49
	v_add_f32_e32 v38, 1.0, v38
	v_add_f32_e32 v39, 1.0, v39
	v_rcp_f32_e32 v36, v36
	v_rcp_f32_e32 v37, v37
	v_rcp_f32_e32 v38, v38
	v_rcp_f32_e32 v39, v39
	global_load_dwordx2 v[60:61], v[86:87], off offset:224
	v_pk_add_f32 v[48:49], v[36:37], -1.0 op_sel_hi:[1,0]
	v_pk_mul_f32 v[34:35], v[36:37], v[34:35] neg_lo:[0,1] neg_hi:[0,1]
	v_pk_add_f32 v[36:37], v[38:39], -1.0 op_sel_hi:[1,0]
	v_pk_mul_f32 v[32:33], v[38:39], v[32:33] neg_lo:[0,1] neg_hi:[0,1]
	s_waitcnt vmcnt(2)
	v_pk_fma_f32 v[38:39], v[52:53], v[48:49], 1.0 op_sel_hi:[1,1,0]
	v_pk_fma_f32 v[36:37], v[54:55], v[36:37], 1.0 op_sel_hi:[1,1,0]
	v_cvt_pk_f16_f32 v34, v34, v35
	v_cvt_pk_f16_f32 v35, v32, v33
	v_pk_mul_f32 v[32:33], v[38:39], v[56:57]
	v_pk_mul_f32 v[36:37], v[36:37], v[58:59]
	v_cvt_pk_f16_f32 v32, v32, v33
	v_cvt_pk_f16_f32 v33, v36, v37
	v_mov_b32_e32 v248, v34
	v_mov_b32_e32 v249, v35
	s_nop 1
	v_permlane32_swap_b32_e32 v246, v248
	v_permlane32_swap_b32_e32 v247, v249
	global_store_dwordx4 v[240:241], v[246:249], off offset:320
	v_mov_b32_e32 v224, v32
	v_mov_b32_e32 v225, v33
	s_nop 1
	v_permlane32_swap_b32_e32 v222, v224
	v_permlane32_swap_b32_e32 v223, v225
	global_store_dwordx4 v[240:241], v[222:225], off offset:192
	global_load_dwordx4 v[32:35], v[70:71], off offset:192
	s_nop 0
	global_load_dwordx4 v[36:39], v[76:77], off offset:192
	global_load_dwordx4 v[48:51], v[68:69], off offset:192
	s_waitcnt vmcnt(5)
	v_cvt_f32_f16_sdwa v53, v60 dst_sel:DWORD dst_unused:UNUSED_PAD src0_sel:WORD_1
	v_cvt_f32_f16_e32 v52, v60
	v_cvt_f32_f16_sdwa v55, v61 dst_sel:DWORD dst_unused:UNUSED_PAD src0_sel:WORD_1
	v_cvt_f32_f16_e32 v54, v61
	s_waitcnt vmcnt(2)
	v_add_f32_e32 v40, v40, v32
	s_waitcnt vmcnt(1)
	v_pk_mul_f32 v[36:37], v[36:37], v[52:53]
	v_add_f32_e32 v41, v41, v33
	v_add_f32_e32 v42, v42, v34
	v_pk_mul_f32 v[32:33], v[38:39], v[54:55]
	v_add_f32_e32 v38, v43, v35
	v_mul_f32_e32 v39, 0xbfb8aa3b, v40
	v_pk_mul_f32 v[34:35], v[90:91], v[36:37] op_sel_hi:[0,1]
	v_mul_f32_e32 v36, 0xbfb8aa3b, v41
	v_mul_f32_e32 v37, 0xbfb8aa3b, v42
	v_mul_f32_e32 v38, 0xbfb8aa3b, v38
	v_exp_f32_e32 v39, v39
	v_exp_f32_e32 v40, v36
	v_exp_f32_e32 v41, v37
	v_exp_f32_e32 v38, v38
	v_pk_mul_f32 v[32:33], v[90:91], v[32:33] op_sel_hi:[0,1]
	v_cvt_pk_f16_f32 v36, v34, v35
	v_cvt_pk_f16_f32 v37, v32, v33
	v_mov_b32_e32 v226, v36
	v_mov_b32_e32 v227, v37
	v_add_f32_e32 v36, 1.0, v39
	v_add_f32_e32 v37, 1.0, v40
	v_add_f32_e32 v39, 1.0, v41
	v_add_f32_e32 v40, 1.0, v38
	v_rcp_f32_e32 v36, v36
	v_rcp_f32_e32 v37, v37
	v_rcp_f32_e32 v38, v39
	v_rcp_f32_e32 v39, v40
	global_load_dwordx2 v[56:57], v[86:87], off offset:240
	v_pk_add_f32 v[40:41], v[36:37], -1.0 op_sel_hi:[1,0]
	v_pk_mul_f32 v[34:35], v[36:37], v[34:35] neg_lo:[0,1] neg_hi:[0,1]
	v_pk_add_f32 v[36:37], v[38:39], -1.0 op_sel_hi:[1,0]
	v_pk_mul_f32 v[32:33], v[38:39], v[32:33] neg_lo:[0,1] neg_hi:[0,1]
	s_waitcnt vmcnt(1)
; __device__ __forceinline__ float h_lo(unsigned u) { f16x2_t r = __builtin_bit_cast(f16x2_t, u); return (float)r.x; }
; __device__ __forceinline__ float h_hi(unsigned u) { f16x2_t r = __builtin_bit_cast(f16x2_t, u); return (float)r.y; }
; __device__ __forceinline__ void epi_adir(const f32x16 (&acc)[2][2], int nbase, int tbase, int M, CP& p, int dir) {
;     ...
;   for (int tb = 0; tb < 2; ++tb) {
;     const int tok = tbase + tb * 32 + l32;
;     const bool valid = tok < M;
;     const int tk = valid ? tok : M - 1;
;     const size_t rec = ((size_t)tk * 16 + head) * 192;
;     float nsq = 0.f;
; #pragma unroll
;     for (int nb = 0; nb < 2; ++nb)
; #pragma unroll
;       for (int i = 0; i < 4; ++i) {
;         const int c = nb * 32 + 8 * i + 4 * h;
;         const u32x2 kr = *(const u32x2*)(DIR + rec + 64 + c);
;         const f32x4 kkw = *(const f32x4*)(p.k_k + nbase + c);
;         const float q0 = h_lo(kr.x) * kkw[0], q1 = h_hi(kr.x) * kkw[1], q2 = h_lo(kr.y) * kkw[2], q3 = h_hi(kr.y) * kkw[3];
;         nsq += q0 * q0 + q1 * q1 + q2 * q2 + q3 * q3;
;       }
;     nsq += __shfl_xor(nsq, 32);
;     const float inv = 1.f / fmaxf(sqrtf(nsq), 1e-12f);
;     ...
;       for (int nb = 0; nb < 2; ++nb)
; #pragma unroll
;         for (int i = 0; i < 4; ++i) {
;           const int c = nb * 32 + 8 * i + 4 * h;
;           const u32x2 kr = *(const u32x2*)(DIR + rec + 64 + c);
;           const float kv[4] = {h_lo(kr.x), h_hi(kr.x), h_lo(kr.y), h_hi(kr.y)};
;           const f32x4 kkw = *(const f32x4*)(p.k_k + nbase + c);
;           const f32x4 kaw = *(const f32x4*)(p.k_a + nbase + c);
;           const f32x4 a0v = *(const f32x4*)(a0 + nbase + c);
;           float kk[4], kd[4], bp[4];
; #pragma unroll
;           for (int j = 0; j < 4; ++j) {
;             const float k = kv[j];
;             kk[j] = k * kkw[j] * inv;
;             const float aa = sigm(a0v[j] + acc[nb][tb][4 * i + j]);
;             kd[j] = k * (1.f + (aa - 1.f) * kaw[j]);
;             bp[j] = -kk[j] * aa;
;           }
;           if (dir == 0) *(u32x2*)(p.RKV + rec + 64 + c) = (u32x2){pk_f16(kk[0], kk[1]), pk_f16(kk[2], kk[3])};
;           *(u32x2*)(DIR + rec + 64 + c) = (u32x2){pk_f16(kd[0], kd[1]), pk_f16(kd[2], kd[3])};
;           *(u32x2*)(DIR + rec + 128 + c) = (u32x2){pk_f16(bp[0], bp[1]), pk_f16(bp[2], bp[3])};
;         }
	v_pk_fma_f32 v[38:39], v[48:49], v[40:41], 1.0 op_sel_hi:[1,1,0]
	v_pk_fma_f32 v[36:37], v[50:51], v[36:37], 1.0 op_sel_hi:[1,1,0]
	v_cvt_pk_f16_f32 v34, v34, v35
	v_cvt_pk_f16_f32 v35, v32, v33
	v_pk_mul_f32 v[32:33], v[38:39], v[52:53]
	v_pk_mul_f32 v[36:37], v[36:37], v[54:55]
	v_cvt_pk_f16_f32 v32, v32, v33
	v_cvt_pk_f16_f32 v33, v36, v37
	v_mov_b32_e32 v230, v34
	v_mov_b32_e32 v231, v35
	v_mov_b32_e32 v234, v32
	v_mov_b32_e32 v235, v33
	global_load_dwordx4 v[32:35], v[70:71], off offset:224
	s_nop 0
	global_load_dwordx4 v[36:39], v[76:77], off offset:224
	global_load_dwordx4 v[40:43], v[68:69], off offset:224
	s_waitcnt vmcnt(3)
	v_cvt_f32_f16_sdwa v49, v56 dst_sel:DWORD dst_unused:UNUSED_PAD src0_sel:WORD_1
	v_cvt_f32_f16_e32 v48, v56
	v_cvt_f32_f16_sdwa v51, v57 dst_sel:DWORD dst_unused:UNUSED_PAD src0_sel:WORD_1
	v_cvt_f32_f16_e32 v50, v57
	s_waitcnt vmcnt(2)
	v_add_f32_e32 v44, v44, v32
	s_waitcnt vmcnt(1)
	v_pk_mul_f32 v[36:37], v[36:37], v[48:49]
	v_add_f32_e32 v45, v45, v33
	v_add_f32_e32 v46, v46, v34
	v_pk_mul_f32 v[32:33], v[38:39], v[50:51]
	v_add_f32_e32 v38, v47, v35
	v_mul_f32_e32 v39, 0xbfb8aa3b, v44
	v_pk_mul_f32 v[34:35], v[90:91], v[36:37] op_sel_hi:[0,1]
	v_mul_f32_e32 v36, 0xbfb8aa3b, v45
	v_mul_f32_e32 v37, 0xbfb8aa3b, v46
	v_mul_f32_e32 v38, 0xbfb8aa3b, v38
	v_exp_f32_e32 v39, v39
	v_exp_f32_e32 v44, v36
	v_exp_f32_e32 v45, v37
	v_exp_f32_e32 v38, v38
	v_add_f32_e32 v39, 1.0, v39
	v_add_f32_e32 v44, 1.0, v44
	v_add_f32_e32 v45, 1.0, v45
	v_add_f32_e32 v46, 1.0, v38
	v_rcp_f32_e32 v38, v39
	v_rcp_f32_e32 v39, v44
	v_rcp_f32_e32 v44, v45
	v_rcp_f32_e32 v45, v46
	v_pk_mul_f32 v[32:33], v[90:91], v[32:33] op_sel_hi:[0,1]
	v_cvt_pk_f16_f32 v36, v34, v35
	v_cvt_pk_f16_f32 v37, v32, v33
	v_mov_b32_e32 v228, v36
	v_mov_b32_e32 v229, v37
	s_nop 1
	v_permlane32_swap_b32_e32 v226, v228
	v_permlane32_swap_b32_e32 v227, v229
	global_store_dwordx4 v[238:239], v[226:229], off offset:224
	v_pk_add_f32 v[36:37], v[38:39], -1.0 op_sel_hi:[1,0]
	v_pk_mul_f32 v[34:35], v[38:39], v[34:35] neg_lo:[0,1] neg_hi:[0,1]
	v_pk_add_f32 v[38:39], v[44:45], -1.0 op_sel_hi:[1,0]
	v_pk_mul_f32 v[32:33], v[44:45], v[32:33] neg_lo:[0,1] neg_hi:[0,1]
	s_waitcnt vmcnt(1)
	v_pk_fma_f32 v[36:37], v[40:41], v[36:37], 1.0 op_sel_hi:[1,1,0]
	v_pk_fma_f32 v[38:39], v[42:43], v[38:39], 1.0 op_sel_hi:[1,1,0]
	v_cvt_pk_f16_f32 v34, v34, v35
	v_cvt_pk_f16_f32 v35, v32, v33
	v_pk_mul_f32 v[32:33], v[36:37], v[48:49]
	v_pk_mul_f32 v[36:37], v[38:39], v[50:51]
	v_cvt_pk_f16_f32 v32, v32, v33
	v_cvt_pk_f16_f32 v33, v36, v37
	v_mov_b32_e32 v236, v32
	v_mov_b32_e32 v237, v33
	s_nop 1
	v_permlane32_swap_b32_e32 v234, v236
	v_permlane32_swap_b32_e32 v235, v237
	global_store_dwordx4 v[240:241], v[234:237], off offset:224
	v_mov_b32_e32 v232, v34
	v_mov_b32_e32 v233, v35
	s_nop 1
	v_permlane32_swap_b32_e32 v230, v232
	v_permlane32_swap_b32_e32 v231, v233
	global_store_dwordx4 v[240:241], v[230:233], off offset:352
.LBB0_502:
	s_or_b64 exec, exec, s[34:35]
	v_or_b32_e32 v46, 32, v103
	v_min_i32_e32 v32, s53, v46
	v_ashrrev_i32_e32 v33, 31, v32
	v_lshl_add_u64 v[32:33], v[32:33], 4, v[84:85]
	v_mad_u64_u32 v[42:43], s[0:1], v32, s78, 0
	v_mad_i32_i24 v43, v33, s78, v43
	v_lshl_add_u64 v[32:33], v[42:43], 1, s[46:47]
	v_lshl_add_u64 v[40:41], v[32:33], 0, v[160:161]
	global_load_dwordx2 v[36:37], v[40:41], off offset:128
	global_load_dwordx4 v[32:35], v[76:77], off
	v_cmp_gt_i32_e32 vcc, s72, v46
	s_waitcnt vmcnt(1)
	v_cvt_f32_f16_e32 v38, v36
	v_cvt_f32_f16_sdwa v36, v36 dst_sel:DWORD dst_unused:UNUSED_PAD src0_sel:WORD_1
	v_cvt_f32_f16_e32 v39, v37
	v_cvt_f32_f16_sdwa v37, v37 dst_sel:DWORD dst_unused:UNUSED_PAD src0_sel:WORD_1
	s_waitcnt vmcnt(0)
	v_mul_f32_e32 v38, v32, v38
	v_mul_f32_e32 v36, v33, v36
	v_mul_f32_e32 v47, v36, v36
	v_mul_f32_e32 v39, v34, v39
	v_fmac_f32_e32 v47, v38, v38
	v_mul_f32_e32 v37, v35, v37
	v_fmac_f32_e32 v47, v39, v39
	v_fmac_f32_e32 v47, v37, v37
	global_load_dwordx2 v[44:45], v[40:41], off offset:144
	global_load_dwordx4 v[36:39], v[76:77], off offset:32
	s_waitcnt vmcnt(1)
	v_cvt_f32_f16_e32 v48, v44
	v_cvt_f32_f16_sdwa v44, v44 dst_sel:DWORD dst_unused:UNUSED_PAD src0_sel:WORD_1
	s_waitcnt vmcnt(0)
	v_mul_f32_e32 v36, v36, v48
	v_mul_f32_e32 v37, v37, v44
	v_cvt_f32_f16_e32 v44, v45
	v_mul_f32_e32 v37, v37, v37
	v_fmac_f32_e32 v37, v36, v36
	v_mul_f32_e32 v38, v38, v44
	v_cvt_f32_f16_sdwa v44, v45 dst_sel:DWORD dst_unused:UNUSED_PAD src0_sel:WORD_1
	v_fmac_f32_e32 v37, v38, v38
	v_mul_f32_e32 v39, v39, v44
	v_fmac_f32_e32 v37, v39, v39
	v_add_f32_e32 v47, v47, v37
	global_load_dwordx2 v[44:45], v[40:41], off offset:160
	global_load_dwordx4 v[36:39], v[76:77], off offset:64
	s_waitcnt vmcnt(1)
	v_cvt_f32_f16_e32 v48, v44
	v_cvt_f32_f16_sdwa v44, v44 dst_sel:DWORD dst_unused:UNUSED_PAD src0_sel:WORD_1
	s_waitcnt vmcnt(0)
	v_mul_f32_e32 v36, v36, v48
	v_mul_f32_e32 v37, v37, v44
	v_cvt_f32_f16_e32 v44, v45
	v_mul_f32_e32 v37, v37, v37
	v_fmac_f32_e32 v37, v36, v36
	v_mul_f32_e32 v38, v38, v44
	v_cvt_f32_f16_sdwa v44, v45 dst_sel:DWORD dst_unused:UNUSED_PAD src0_sel:WORD_1
	v_fmac_f32_e32 v37, v38, v38
	v_mul_f32_e32 v39, v39, v44
	v_fmac_f32_e32 v37, v39, v39
	v_add_f32_e32 v47, v47, v37
	global_load_dwordx2 v[44:45], v[40:41], off offset:176
	global_load_dwordx4 v[36:39], v[76:77], off offset:96
	s_waitcnt vmcnt(1)
	v_cvt_f32_f16_e32 v48, v44
	v_cvt_f32_f16_sdwa v44, v44 dst_sel:DWORD dst_unused:UNUSED_PAD src0_sel:WORD_1
	s_waitcnt vmcnt(0)
; __device__ __forceinline__ float h_lo(unsigned u) { f16x2_t r = __builtin_bit_cast(f16x2_t, u); return (float)r.x; }
; __device__ __forceinline__ float h_hi(unsigned u) { f16x2_t r = __builtin_bit_cast(f16x2_t, u); return (float)r.y; }
; __device__ __forceinline__ void epi_adir(const f32x16 (&acc)[2][2], int nbase, int tbase, int M, CP& p, int dir) {
;     ...
;   for (int tb = 0; tb < 2; ++tb) {
;     const int tok = tbase + tb * 32 + l32;
;     const bool valid = tok < M;
;     const int tk = valid ? tok : M - 1;
;     const size_t rec = ((size_t)tk * 16 + head) * 192;
;     float nsq = 0.f;
; #pragma unroll
;     for (int nb = 0; nb < 2; ++nb)
; #pragma unroll
;       for (int i = 0; i < 4; ++i) {
;         const int c = nb * 32 + 8 * i + 4 * h;
;         const u32x2 kr = *(const u32x2*)(DIR + rec + 64 + c);
;         const f32x4 kkw = *(const f32x4*)(p.k_k + nbase + c);
;         const float q0 = h_lo(kr.x) * kkw[0], q1 = h_hi(kr.x) * kkw[1], q2 = h_lo(kr.y) * kkw[2], q3 = h_hi(kr.y) * kkw[3];
;         nsq += q0 * q0 + q1 * q1 + q2 * q2 + q3 * q3;
;       }
;     nsq += __shfl_xor(nsq, 32);
;     const float inv = 1.f / fmaxf(sqrtf(nsq), 1e-12f);
;     if (valid) {
; #pragma unroll
;       for (int nb = 0; nb < 2; ++nb)
; #pragma unroll
;         for (int i = 0; i < 4; ++i) {
;           const int c = nb * 32 + 8 * i + 4 * h;
;           const u32x2 kr = *(const u32x2*)(DIR + rec + 64 + c);
;           const float kv[4] = {h_lo(kr.x), h_hi(kr.x), h_lo(kr.y), h_hi(kr.y)};
;           const f32x4 kkw = *(const f32x4*)(p.k_k + nbase + c);
;           const f32x4 kaw = *(const f32x4*)(p.k_a + nbase + c);
;           const f32x4 a0v = *(const f32x4*)(a0 + nbase + c);
;           float kk[4], kd[4], bp[4];
; #pragma unroll
;           for (int j = 0; j < 4; ++j) {
;             const float k = kv[j];
;             kk[j] = k * kkw[j] * inv;
;             const float aa = sigm(a0v[j] + acc[nb][tb][4 * i + j]);
;             kd[j] = k * (1.f + (aa - 1.f) * kaw[j]);
;             bp[j] = -kk[j] * aa;
;           }
;           if (dir == 0) *(u32x2*)(p.RKV + rec + 64 + c) = (u32x2){pk_f16(kk[0], kk[1]), pk_f16(kk[2], kk[3])};
;           *(u32x2*)(DIR + rec + 64 + c) = (u32x2){pk_f16(kd[0], kd[1]), pk_f16(kd[2], kd[3])};
;           *(u32x2*)(DIR + rec + 128 + c) = (u32x2){pk_f16(bp[0], bp[1]), pk_f16(bp[2], bp[3])};
;         }
	v_mul_f32_e32 v36, v36, v48
	v_mul_f32_e32 v37, v37, v44
	v_cvt_f32_f16_e32 v44, v45
	v_mul_f32_e32 v37, v37, v37
	v_fmac_f32_e32 v37, v36, v36
	v_mul_f32_e32 v38, v38, v44
	v_cvt_f32_f16_sdwa v44, v45 dst_sel:DWORD dst_unused:UNUSED_PAD src0_sel:WORD_1
	v_fmac_f32_e32 v37, v38, v38
	v_mul_f32_e32 v39, v39, v44
	v_fmac_f32_e32 v37, v39, v39
	v_add_f32_e32 v47, v47, v37
	global_load_dwordx2 v[44:45], v[40:41], off offset:192
	global_load_dwordx4 v[36:39], v[76:77], off offset:128
	s_waitcnt vmcnt(1)
	v_cvt_f32_f16_e32 v48, v44
	v_cvt_f32_f16_sdwa v44, v44 dst_sel:DWORD dst_unused:UNUSED_PAD src0_sel:WORD_1
	s_waitcnt vmcnt(0)
	v_mul_f32_e32 v36, v36, v48
	v_mul_f32_e32 v37, v37, v44
	v_cvt_f32_f16_e32 v44, v45
	v_mul_f32_e32 v37, v37, v37
	v_fmac_f32_e32 v37, v36, v36
	v_mul_f32_e32 v38, v38, v44
	v_cvt_f32_f16_sdwa v44, v45 dst_sel:DWORD dst_unused:UNUSED_PAD src0_sel:WORD_1
	v_fmac_f32_e32 v37, v38, v38
	v_mul_f32_e32 v39, v39, v44
	v_fmac_f32_e32 v37, v39, v39
	v_add_f32_e32 v47, v47, v37
	global_load_dwordx2 v[44:45], v[40:41], off offset:208
	global_load_dwordx4 v[36:39], v[76:77], off offset:160
	s_waitcnt vmcnt(1)
	v_cvt_f32_f16_e32 v48, v44
	v_cvt_f32_f16_sdwa v44, v44 dst_sel:DWORD dst_unused:UNUSED_PAD src0_sel:WORD_1
	s_waitcnt vmcnt(0)
	v_mul_f32_e32 v36, v36, v48
	v_mul_f32_e32 v37, v37, v44
	v_cvt_f32_f16_e32 v44, v45
	v_mul_f32_e32 v37, v37, v37
	v_fmac_f32_e32 v37, v36, v36
	v_mul_f32_e32 v38, v38, v44
	v_cvt_f32_f16_sdwa v44, v45 dst_sel:DWORD dst_unused:UNUSED_PAD src0_sel:WORD_1
	v_fmac_f32_e32 v37, v38, v38
	v_mul_f32_e32 v39, v39, v44
	v_fmac_f32_e32 v37, v39, v39
	v_add_f32_e32 v47, v47, v37
	global_load_dwordx2 v[44:45], v[40:41], off offset:224
	global_load_dwordx4 v[36:39], v[76:77], off offset:192
	s_waitcnt vmcnt(1)
	v_cvt_f32_f16_e32 v48, v44
	v_cvt_f32_f16_sdwa v44, v44 dst_sel:DWORD dst_unused:UNUSED_PAD src0_sel:WORD_1
	s_waitcnt vmcnt(0)
	v_mul_f32_e32 v36, v36, v48
	v_mul_f32_e32 v37, v37, v44
	v_cvt_f32_f16_e32 v44, v45
	v_mul_f32_e32 v37, v37, v37
	v_fmac_f32_e32 v37, v36, v36
	v_mul_f32_e32 v38, v38, v44
	v_cvt_f32_f16_sdwa v44, v45 dst_sel:DWORD dst_unused:UNUSED_PAD src0_sel:WORD_1
	v_fmac_f32_e32 v37, v38, v38
	v_mul_f32_e32 v39, v39, v44
	v_fmac_f32_e32 v37, v39, v39
	v_add_f32_e32 v47, v47, v37
	global_load_dwordx2 v[44:45], v[40:41], off offset:240
	global_load_dwordx4 v[36:39], v[76:77], off offset:224
	s_waitcnt vmcnt(1)
	v_cvt_f32_f16_e32 v48, v44
	v_cvt_f32_f16_sdwa v44, v44 dst_sel:DWORD dst_unused:UNUSED_PAD src0_sel:WORD_1
	s_waitcnt vmcnt(0)
	v_mul_f32_e32 v36, v36, v48
	v_mul_f32_e32 v37, v37, v44
	v_cvt_f32_f16_e32 v44, v45
	v_mul_f32_e32 v37, v37, v37
	v_fmac_f32_e32 v37, v36, v36
	v_mul_f32_e32 v38, v38, v44
	v_cvt_f32_f16_sdwa v44, v45 dst_sel:DWORD dst_unused:UNUSED_PAD src0_sel:WORD_1
	v_fmac_f32_e32 v37, v38, v38
	v_mul_f32_e32 v39, v39, v44
	v_fmac_f32_e32 v37, v39, v39
	v_add_f32_e32 v44, v47, v37
	ds_bpermute_b32 v45, v102, v44
	s_and_saveexec_b64 s[34:35], vcc
	s_cbranch_execz .LBB0_493
	v_mov_b32_e32 v83, v161
	v_lshl_add_u64 v[38:39], v[80:81], 0, v[82:83]
	global_load_dwordx2 v[54:55], v[40:41], off offset:128
	global_load_dwordx4 v[46:49], v[38:39], off
	v_lshl_add_u64 v[36:37], v[78:79], 0, v[82:83]
	global_load_dwordx4 v[50:53], v[36:37], off
	s_waitcnt lgkmcnt(0)
	v_add_f32_e32 v44, v44, v45
	s_mov_b32 s0, 0xf800000
	v_mul_f32_e32 v45, 0x4f800000, v44
	v_cmp_gt_f32_e32 vcc, s0, v44
	v_lshl_add_u64 v[42:43], v[42:43], 1, s[44:45]
	v_lshl_add_u64 v[42:43], v[42:43], 0, v[160:161]
	v_cndmask_b32_e32 v44, v44, v45, vcc
	v_sqrt_f32_e32 v45, v44
	s_waitcnt vmcnt(1)
	v_add_f32_e32 v17, v17, v47
	v_add_u32_e32 v56, -1, v45
	v_add_u32_e32 v57, 1, v45
	v_fma_f32 v58, -v56, v45, v44
	v_fma_f32 v59, -v57, v45, v44
	v_cmp_ge_f32_e64 s[42:43], 0, v58
	v_add_f32_e32 v16, v16, v46
	v_add_f32_e32 v18, v18, v48
	v_cndmask_b32_e64 v45, v45, v56, s[42:43]
	v_cmp_lt_f32_e64 s[42:43], 0, v59
	v_add_f32_e32 v19, v19, v49
	v_mul_f32_e32 v16, 0xbfb8aa3b, v16
	v_cndmask_b32_e64 v45, v45, v57, s[42:43]
	v_mul_f32_e32 v56, 0x37800000, v45
	v_cndmask_b32_e32 v45, v45, v56, vcc
	v_cmp_class_f32_e32 vcc, v44, v207
	v_mul_f32_e32 v18, 0xbfb8aa3b, v18
	v_mul_f32_e32 v46, 0xbfb8aa3b, v19
	v_cndmask_b32_e32 v44, v45, v44, vcc
	v_max_f32_e32 v44, 0x2b8cbccc, v44
	v_div_scale_f32 v45, s[0:1], v44, v44, 1.0
	v_rcp_f32_e32 v56, v45
	v_div_scale_f32 v57, vcc, 1.0, v44, 1.0
	v_exp_f32_e32 v47, v16
	v_fma_f32 v58, -v45, v56, 1.0
	v_fmac_f32_e32 v56, v58, v56
	v_mul_f32_e32 v58, v57, v56
	v_fma_f32 v59, -v45, v58, v57
	v_fmac_f32_e32 v58, v59, v56
	v_fma_f32 v45, -v45, v58, v57
	v_div_fmas_f32 v45, v45, v56, v58
	v_cvt_f32_f16_sdwa v59, v55 dst_sel:DWORD dst_unused:UNUSED_PAD src0_sel:WORD_1
	v_cvt_f32_f16_e32 v58, v55
	v_div_fixup_f32 v44, v45, v44, 1.0
	v_cvt_f32_f16_sdwa v57, v54 dst_sel:DWORD dst_unused:UNUSED_PAD src0_sel:WORD_1
	v_cvt_f32_f16_e32 v56, v54
	v_mul_f32_e32 v45, 0xbfb8aa3b, v17
	v_exp_f32_e32 v45, v45
	v_exp_f32_e32 v48, v18
	v_pk_mul_f32 v[18:19], v[34:35], v[58:59]
	v_exp_f32_e32 v34, v46
	v_pk_mul_f32 v[16:17], v[32:33], v[56:57]
	v_pk_mul_f32 v[18:19], v[44:45], v[18:19] op_sel_hi:[0,1]
	v_pk_mul_f32 v[16:17], v[44:45], v[16:17] op_sel_hi:[0,1]
	v_cvt_pk_f16_f32 v32, v16, v17
	v_cvt_pk_f16_f32 v33, v18, v19
	v_mbcnt_lo_u32_b32 v238, -1, 0
	v_mbcnt_hi_u32_b32 v238, -1, v238
	v_lshrrev_b32_e32 v238, 2, v238
	v_and_b32_e32 v238, 8, v238
	v_mov_b32_e32 v239, 0
	v_lshl_add_u64 v[238:239], v[42:43], 0, v[238:239]
	v_mov_b32_e32 v242, v32
	v_mov_b32_e32 v243, v33
	v_add_f32_e32 v32, 1.0, v47
	v_add_f32_e32 v33, 1.0, v45
	v_add_f32_e32 v35, 1.0, v48
	v_add_f32_e32 v45, 1.0, v34
	v_rcp_f32_e32 v32, v32
	v_rcp_f32_e32 v33, v33
	v_rcp_f32_e32 v34, v35
	v_rcp_f32_e32 v35, v45
	global_load_dwordx2 v[54:55], v[40:41], off offset:144
	v_pk_add_f32 v[46:47], v[32:33], -1.0 op_sel_hi:[1,0]
	v_pk_mul_f32 v[16:17], v[32:33], v[16:17] neg_lo:[0,1] neg_hi:[0,1]
	v_pk_add_f32 v[32:33], v[34:35], -1.0 op_sel_hi:[1,0]
	v_pk_mul_f32 v[18:19], v[34:35], v[18:19] neg_lo:[0,1] neg_hi:[0,1]
	s_waitcnt vmcnt(1)
; __device__ __forceinline__ float h_lo(unsigned u) { f16x2_t r = __builtin_bit_cast(f16x2_t, u); return (float)r.x; }
; __device__ __forceinline__ float h_hi(unsigned u) { f16x2_t r = __builtin_bit_cast(f16x2_t, u); return (float)r.y; }
; __device__ __forceinline__ float sigm(float x) { return __builtin_amdgcn_rcpf(1.f + __builtin_amdgcn_exp2f(-LOG2E * x)); }
; __device__ __forceinline__ void epi_adir(const f32x16 (&acc)[2][2], int nbase, int tbase, int M, CP& p, int dir) {
;     ...
;       for (int nb = 0; nb < 2; ++nb)
; #pragma unroll
;         for (int i = 0; i < 4; ++i) {
;           const int c = nb * 32 + 8 * i + 4 * h;
;           const u32x2 kr = *(const u32x2*)(DIR + rec + 64 + c);
;           const float kv[4] = {h_lo(kr.x), h_hi(kr.x), h_lo(kr.y), h_hi(kr.y)};
;           const f32x4 kkw = *(const f32x4*)(p.k_k + nbase + c);
;           const f32x4 kaw = *(const f32x4*)(p.k_a + nbase + c);
;           const f32x4 a0v = *(const f32x4*)(a0 + nbase + c);
;           float kk[4], kd[4], bp[4];
; #pragma unroll
;           for (int j = 0; j < 4; ++j) {
;             const float k = kv[j];
;             kk[j] = k * kkw[j] * inv;
;             const float aa = sigm(a0v[j] + acc[nb][tb][4 * i + j]);
;             kd[j] = k * (1.f + (aa - 1.f) * kaw[j]);
;             bp[j] = -kk[j] * aa;
;           }
;           if (dir == 0) *(u32x2*)(p.RKV + rec + 64 + c) = (u32x2){pk_f16(kk[0], kk[1]), pk_f16(kk[2], kk[3])};
;           *(u32x2*)(DIR + rec + 64 + c) = (u32x2){pk_f16(kd[0], kd[1]), pk_f16(kd[2], kd[3])};
;           *(u32x2*)(DIR + rec + 128 + c) = (u32x2){pk_f16(bp[0], bp[1]), pk_f16(bp[2], bp[3])};
;         }
	v_pk_fma_f32 v[34:35], v[50:51], v[46:47], 1.0 op_sel_hi:[1,1,0]
	v_pk_fma_f32 v[32:33], v[52:53], v[32:33], 1.0 op_sel_hi:[1,1,0]
	v_cvt_pk_f16_f32 v16, v16, v17
	v_cvt_pk_f16_f32 v17, v18, v19
	v_pk_mul_f32 v[18:19], v[34:35], v[56:57]
	v_pk_mul_f32 v[32:33], v[32:33], v[58:59]
	v_mbcnt_lo_u32_b32 v240, -1, 0
	v_mbcnt_hi_u32_b32 v240, -1, v240
	v_lshrrev_b32_e32 v240, 2, v240
	v_and_b32_e32 v240, 8, v240
	v_mov_b32_e32 v241, 0
	v_lshl_add_u64 v[240:241], v[40:41], 0, v[240:241]
	v_mov_b32_e32 v246, v16
	v_mov_b32_e32 v247, v17
	v_cvt_pk_f16_f32 v16, v18, v19
	v_cvt_pk_f16_f32 v17, v32, v33
	v_mov_b32_e32 v222, v16
	v_mov_b32_e32 v223, v17
	global_load_dwordx4 v[16:19], v[38:39], off offset:32
	s_nop 0
	global_load_dwordx4 v[32:35], v[76:77], off offset:32
	global_load_dwordx4 v[46:49], v[36:37], off offset:32
	s_waitcnt vmcnt(3)
	v_cvt_f32_f16_sdwa v51, v54 dst_sel:DWORD dst_unused:UNUSED_PAD src0_sel:WORD_1
	v_cvt_f32_f16_e32 v50, v54
	v_cvt_f32_f16_sdwa v53, v55 dst_sel:DWORD dst_unused:UNUSED_PAD src0_sel:WORD_1
	v_cvt_f32_f16_e32 v52, v55
	s_waitcnt vmcnt(2)
	v_add_f32_e32 v20, v20, v16
	v_add_f32_e32 v21, v21, v17
	v_add_f32_e32 v22, v22, v18
	v_add_f32_e32 v23, v23, v19
	s_waitcnt vmcnt(1)
	v_pk_mul_f32 v[32:33], v[32:33], v[50:51]
	v_mul_f32_e32 v20, 0xbfb8aa3b, v20
	v_mul_f32_e32 v21, 0xbfb8aa3b, v21
	v_mul_f32_e32 v22, 0xbfb8aa3b, v22
	v_mul_f32_e32 v23, 0xbfb8aa3b, v23
	v_pk_mul_f32 v[18:19], v[44:45], v[32:33] op_sel_hi:[0,1]
	v_exp_f32_e32 v32, v20
	v_exp_f32_e32 v33, v21
	v_exp_f32_e32 v22, v22
	v_exp_f32_e32 v23, v23
	v_pk_mul_f32 v[16:17], v[34:35], v[52:53]
	v_cvt_pk_f16_f32 v20, v18, v19
	v_pk_mul_f32 v[16:17], v[44:45], v[16:17] op_sel_hi:[0,1]
	v_cvt_pk_f16_f32 v21, v16, v17
	v_mov_b32_e32 v244, v20
	v_mov_b32_e32 v245, v21
	s_nop 1
	v_permlane32_swap_b32_e32 v242, v244
	v_permlane32_swap_b32_e32 v243, v245
	global_store_dwordx4 v[238:239], v[242:245], off offset:128
	v_add_f32_e32 v20, 1.0, v32
	v_add_f32_e32 v21, 1.0, v33
	v_add_f32_e32 v22, 1.0, v22
	v_add_f32_e32 v23, 1.0, v23
	v_rcp_f32_e32 v20, v20
	v_rcp_f32_e32 v21, v21
	v_rcp_f32_e32 v22, v22
	v_rcp_f32_e32 v23, v23
	global_load_dwordx2 v[54:55], v[40:41], off offset:160
	v_pk_add_f32 v[32:33], v[20:21], -1.0 op_sel_hi:[1,0]
	v_pk_mul_f32 v[18:19], v[20:21], v[18:19] neg_lo:[0,1] neg_hi:[0,1]
	v_pk_add_f32 v[20:21], v[22:23], -1.0 op_sel_hi:[1,0]
	v_pk_mul_f32 v[16:17], v[22:23], v[16:17] neg_lo:[0,1] neg_hi:[0,1]
	s_waitcnt vmcnt(2)
	v_pk_fma_f32 v[22:23], v[46:47], v[32:33], 1.0 op_sel_hi:[1,1,0]
	v_pk_fma_f32 v[20:21], v[48:49], v[20:21], 1.0 op_sel_hi:[1,1,0]
	v_cvt_pk_f16_f32 v18, v18, v19
	v_cvt_pk_f16_f32 v19, v16, v17
	v_pk_mul_f32 v[16:17], v[22:23], v[50:51]
	v_pk_mul_f32 v[20:21], v[20:21], v[52:53]
	v_cvt_pk_f16_f32 v16, v16, v17
	v_cvt_pk_f16_f32 v17, v20, v21
	v_mov_b32_e32 v248, v18
	v_mov_b32_e32 v249, v19
	s_nop 1
	v_permlane32_swap_b32_e32 v246, v248
	v_permlane32_swap_b32_e32 v247, v249
	global_store_dwordx4 v[240:241], v[246:249], off offset:256
	v_mov_b32_e32 v224, v16
	v_mov_b32_e32 v225, v17
	s_nop 1
	v_permlane32_swap_b32_e32 v222, v224
	v_permlane32_swap_b32_e32 v223, v225
	global_store_dwordx4 v[240:241], v[222:225], off offset:128
	global_load_dwordx4 v[16:19], v[38:39], off offset:64
	s_nop 0
	global_load_dwordx4 v[20:23], v[76:77], off offset:64
	global_load_dwordx4 v[32:35], v[36:37], off offset:64
	s_waitcnt vmcnt(5)
	v_cvt_f32_f16_sdwa v47, v54 dst_sel:DWORD dst_unused:UNUSED_PAD src0_sel:WORD_1
	v_cvt_f32_f16_e32 v46, v54
	v_cvt_f32_f16_sdwa v49, v55 dst_sel:DWORD dst_unused:UNUSED_PAD src0_sel:WORD_1
	v_cvt_f32_f16_e32 v48, v55
	s_waitcnt vmcnt(2)
	v_add_f32_e32 v24, v24, v16
	s_waitcnt vmcnt(1)
	v_pk_mul_f32 v[20:21], v[20:21], v[46:47]
	v_add_f32_e32 v25, v25, v17
	v_add_f32_e32 v26, v26, v18
	v_pk_mul_f32 v[16:17], v[22:23], v[48:49]
	v_add_f32_e32 v22, v27, v19
	v_mul_f32_e32 v23, 0xbfb8aa3b, v24
	v_pk_mul_f32 v[18:19], v[44:45], v[20:21] op_sel_hi:[0,1]
	v_mul_f32_e32 v20, 0xbfb8aa3b, v25
	v_mul_f32_e32 v21, 0xbfb8aa3b, v26
	v_mul_f32_e32 v22, 0xbfb8aa3b, v22
	v_exp_f32_e32 v23, v23
	v_exp_f32_e32 v24, v20
	v_exp_f32_e32 v25, v21
	v_exp_f32_e32 v22, v22
	v_pk_mul_f32 v[16:17], v[44:45], v[16:17] op_sel_hi:[0,1]
	v_cvt_pk_f16_f32 v20, v18, v19
	v_cvt_pk_f16_f32 v21, v16, v17
	v_mov_b32_e32 v226, v20
	v_mov_b32_e32 v227, v21
	v_add_f32_e32 v20, 1.0, v23
	v_add_f32_e32 v21, 1.0, v24
	v_add_f32_e32 v23, 1.0, v25
	v_add_f32_e32 v24, 1.0, v22
	v_rcp_f32_e32 v20, v20
	v_rcp_f32_e32 v21, v21
	v_rcp_f32_e32 v22, v23
	v_rcp_f32_e32 v23, v24
	global_load_dwordx2 v[50:51], v[40:41], off offset:176
	v_pk_add_f32 v[24:25], v[20:21], -1.0 op_sel_hi:[1,0]
	v_pk_mul_f32 v[18:19], v[20:21], v[18:19] neg_lo:[0,1] neg_hi:[0,1]
	v_pk_add_f32 v[20:21], v[22:23], -1.0 op_sel_hi:[1,0]
	v_pk_mul_f32 v[16:17], v[22:23], v[16:17] neg_lo:[0,1] neg_hi:[0,1]
	s_waitcnt vmcnt(1)
	v_pk_fma_f32 v[22:23], v[32:33], v[24:25], 1.0 op_sel_hi:[1,1,0]
	v_pk_fma_f32 v[20:21], v[34:35], v[20:21], 1.0 op_sel_hi:[1,1,0]
	v_cvt_pk_f16_f32 v18, v18, v19
	v_cvt_pk_f16_f32 v19, v16, v17
	v_pk_mul_f32 v[16:17], v[22:23], v[46:47]
	v_pk_mul_f32 v[20:21], v[20:21], v[48:49]
	v_cvt_pk_f16_f32 v16, v16, v17
	v_cvt_pk_f16_f32 v17, v20, v21
	v_mov_b32_e32 v230, v18
	v_mov_b32_e32 v231, v19
	v_mov_b32_e32 v234, v16
	v_mov_b32_e32 v235, v17
	global_load_dwordx4 v[16:19], v[38:39], off offset:96
	s_nop 0
	global_load_dwordx4 v[20:23], v[76:77], off offset:96
	global_load_dwordx4 v[24:27], v[36:37], off offset:96
	s_waitcnt vmcnt(3)
	v_cvt_f32_f16_sdwa v33, v50 dst_sel:DWORD dst_unused:UNUSED_PAD src0_sel:WORD_1
	v_cvt_f32_f16_e32 v32, v50
	v_cvt_f32_f16_sdwa v35, v51 dst_sel:DWORD dst_unused:UNUSED_PAD src0_sel:WORD_1
	v_cvt_f32_f16_e32 v34, v51
	s_waitcnt vmcnt(2)
; __device__ __forceinline__ float h_lo(unsigned u) { f16x2_t r = __builtin_bit_cast(f16x2_t, u); return (float)r.x; }
; __device__ __forceinline__ float h_hi(unsigned u) { f16x2_t r = __builtin_bit_cast(f16x2_t, u); return (float)r.y; }
; __device__ __forceinline__ float sigm(float x) { return __builtin_amdgcn_rcpf(1.f + __builtin_amdgcn_exp2f(-LOG2E * x)); }
; __device__ __forceinline__ void epi_adir(const f32x16 (&acc)[2][2], int nbase, int tbase, int M, CP& p, int dir) {
;     ...
;       for (int nb = 0; nb < 2; ++nb)
; #pragma unroll
;         for (int i = 0; i < 4; ++i) {
;           const int c = nb * 32 + 8 * i + 4 * h;
;           const u32x2 kr = *(const u32x2*)(DIR + rec + 64 + c);
;           const float kv[4] = {h_lo(kr.x), h_hi(kr.x), h_lo(kr.y), h_hi(kr.y)};
;           const f32x4 kkw = *(const f32x4*)(p.k_k + nbase + c);
;           const f32x4 kaw = *(const f32x4*)(p.k_a + nbase + c);
;           const f32x4 a0v = *(const f32x4*)(a0 + nbase + c);
;           float kk[4], kd[4], bp[4];
; #pragma unroll
;           for (int j = 0; j < 4; ++j) {
;             const float k = kv[j];
;             kk[j] = k * kkw[j] * inv;
;             const float aa = sigm(a0v[j] + acc[nb][tb][4 * i + j]);
;             kd[j] = k * (1.f + (aa - 1.f) * kaw[j]);
;             bp[j] = -kk[j] * aa;
;           }
;           if (dir == 0) *(u32x2*)(p.RKV + rec + 64 + c) = (u32x2){pk_f16(kk[0], kk[1]), pk_f16(kk[2], kk[3])};
;           *(u32x2*)(DIR + rec + 64 + c) = (u32x2){pk_f16(kd[0], kd[1]), pk_f16(kd[2], kd[3])};
;           *(u32x2*)(DIR + rec + 128 + c) = (u32x2){pk_f16(bp[0], bp[1]), pk_f16(bp[2], bp[3])};
;         }
	v_add_f32_e32 v28, v28, v16
	s_waitcnt vmcnt(1)
	v_pk_mul_f32 v[20:21], v[20:21], v[32:33]
	v_add_f32_e32 v29, v29, v17
	v_add_f32_e32 v30, v30, v18
	v_pk_mul_f32 v[16:17], v[22:23], v[34:35]
	v_add_f32_e32 v22, v31, v19
	v_mul_f32_e32 v23, 0xbfb8aa3b, v28
	v_pk_mul_f32 v[18:19], v[44:45], v[20:21] op_sel_hi:[0,1]
	v_mul_f32_e32 v20, 0xbfb8aa3b, v29
	v_mul_f32_e32 v21, 0xbfb8aa3b, v30
	v_mul_f32_e32 v22, 0xbfb8aa3b, v22
	v_exp_f32_e32 v23, v23
	v_exp_f32_e32 v28, v20
	v_exp_f32_e32 v29, v21
	v_exp_f32_e32 v22, v22
	v_pk_mul_f32 v[16:17], v[44:45], v[16:17] op_sel_hi:[0,1]
	v_cvt_pk_f16_f32 v20, v18, v19
	v_cvt_pk_f16_f32 v21, v16, v17
	v_mov_b32_e32 v228, v20
	v_mov_b32_e32 v229, v21
	s_nop 1
	v_permlane32_swap_b32_e32 v226, v228
	v_permlane32_swap_b32_e32 v227, v229
	global_store_dwordx4 v[238:239], v[226:229], off offset:160
	v_add_f32_e32 v20, 1.0, v23
	v_add_f32_e32 v21, 1.0, v28
	v_add_f32_e32 v23, 1.0, v29
	v_add_f32_e32 v28, 1.0, v22
	v_rcp_f32_e32 v20, v20
	v_rcp_f32_e32 v21, v21
	v_rcp_f32_e32 v22, v23
	v_rcp_f32_e32 v23, v28
	global_load_dwordx2 v[28:29], v[40:41], off offset:192
	v_pk_add_f32 v[30:31], v[20:21], -1.0 op_sel_hi:[1,0]
	v_pk_mul_f32 v[18:19], v[20:21], v[18:19] neg_lo:[0,1] neg_hi:[0,1]
	v_pk_add_f32 v[20:21], v[22:23], -1.0 op_sel_hi:[1,0]
	v_pk_mul_f32 v[16:17], v[22:23], v[16:17] neg_lo:[0,1] neg_hi:[0,1]
	s_waitcnt vmcnt(2)
	v_pk_fma_f32 v[22:23], v[24:25], v[30:31], 1.0 op_sel_hi:[1,1,0]
	v_pk_fma_f32 v[20:21], v[26:27], v[20:21], 1.0 op_sel_hi:[1,1,0]
	v_cvt_pk_f16_f32 v18, v18, v19
	v_cvt_pk_f16_f32 v19, v16, v17
	v_pk_mul_f32 v[16:17], v[22:23], v[32:33]
	v_pk_mul_f32 v[20:21], v[20:21], v[34:35]
	v_cvt_pk_f16_f32 v16, v16, v17
	v_cvt_pk_f16_f32 v17, v20, v21
	v_mov_b32_e32 v232, v18
	v_mov_b32_e32 v233, v19
	s_nop 1
	v_permlane32_swap_b32_e32 v230, v232
	v_permlane32_swap_b32_e32 v231, v233
	global_store_dwordx4 v[240:241], v[230:233], off offset:288
	v_mov_b32_e32 v236, v16
	v_mov_b32_e32 v237, v17
	s_nop 1
	v_permlane32_swap_b32_e32 v234, v236
	v_permlane32_swap_b32_e32 v235, v237
	global_store_dwordx4 v[240:241], v[234:237], off offset:160
	global_load_dwordx4 v[16:19], v[38:39], off offset:128
	s_nop 0
	global_load_dwordx4 v[20:23], v[76:77], off offset:128
	global_load_dwordx4 v[24:27], v[36:37], off offset:128
	s_waitcnt vmcnt(5)
	v_cvt_f32_f16_sdwa v31, v28 dst_sel:DWORD dst_unused:UNUSED_PAD src0_sel:WORD_1
	v_cvt_f32_f16_e32 v30, v28
	v_cvt_f32_f16_sdwa v33, v29 dst_sel:DWORD dst_unused:UNUSED_PAD src0_sel:WORD_1
	v_cvt_f32_f16_e32 v32, v29
	s_waitcnt vmcnt(2)
	v_add_f32_e32 v16, v0, v16
	v_add_f32_e32 v17, v1, v17
	v_add_f32_e32 v18, v2, v18
	v_add_f32_e32 v19, v3, v19
	s_waitcnt vmcnt(1)
	v_pk_mul_f32 v[20:21], v[20:21], v[30:31]
	v_mul_f32_e32 v16, 0xbfb8aa3b, v16
	v_mul_f32_e32 v17, 0xbfb8aa3b, v17
	v_mul_f32_e32 v18, 0xbfb8aa3b, v18
	v_mul_f32_e32 v19, 0xbfb8aa3b, v19
	v_pk_mul_f32 v[2:3], v[44:45], v[20:21] op_sel_hi:[0,1]
	v_exp_f32_e32 v20, v16
	v_exp_f32_e32 v21, v17
	v_exp_f32_e32 v18, v18
	v_exp_f32_e32 v19, v19
	v_pk_mul_f32 v[0:1], v[22:23], v[32:33]
	v_cvt_pk_f16_f32 v16, v2, v3
	v_pk_mul_f32 v[0:1], v[44:45], v[0:1] op_sel_hi:[0,1]
	v_cvt_pk_f16_f32 v17, v0, v1
	v_mov_b32_e32 v242, v16
	v_mov_b32_e32 v243, v17
	v_add_f32_e32 v16, 1.0, v20
	v_add_f32_e32 v17, 1.0, v21
	v_add_f32_e32 v18, 1.0, v18
	v_add_f32_e32 v19, 1.0, v19
	v_rcp_f32_e32 v16, v16
	v_rcp_f32_e32 v17, v17
	v_rcp_f32_e32 v18, v18
	v_rcp_f32_e32 v19, v19
	global_load_dwordx2 v[28:29], v[40:41], off offset:208
	v_pk_add_f32 v[20:21], v[16:17], -1.0 op_sel_hi:[1,0]
	v_pk_mul_f32 v[2:3], v[16:17], v[2:3] neg_lo:[0,1] neg_hi:[0,1]
	v_pk_add_f32 v[16:17], v[18:19], -1.0 op_sel_hi:[1,0]
	v_pk_mul_f32 v[0:1], v[18:19], v[0:1] neg_lo:[0,1] neg_hi:[0,1]
	s_waitcnt vmcnt(1)
	v_pk_fma_f32 v[18:19], v[24:25], v[20:21], 1.0 op_sel_hi:[1,1,0]
	v_pk_fma_f32 v[16:17], v[26:27], v[16:17], 1.0 op_sel_hi:[1,1,0]
	v_cvt_pk_f16_f32 v2, v2, v3
	v_cvt_pk_f16_f32 v3, v0, v1
	v_pk_mul_f32 v[0:1], v[18:19], v[30:31]
	v_pk_mul_f32 v[16:17], v[16:17], v[32:33]
	v_cvt_pk_f16_f32 v0, v0, v1
	v_cvt_pk_f16_f32 v1, v16, v17
	v_mov_b32_e32 v246, v2
	v_mov_b32_e32 v247, v3
	v_mov_b32_e32 v222, v0
	v_mov_b32_e32 v223, v1
	global_load_dwordx4 v[0:3], v[38:39], off offset:160
	s_nop 0
	global_load_dwordx4 v[16:19], v[76:77], off offset:160
	global_load_dwordx4 v[20:23], v[36:37], off offset:160
	s_waitcnt vmcnt(3)
	v_cvt_f32_f16_sdwa v25, v28 dst_sel:DWORD dst_unused:UNUSED_PAD src0_sel:WORD_1
	v_cvt_f32_f16_e32 v24, v28
	v_cvt_f32_f16_sdwa v27, v29 dst_sel:DWORD dst_unused:UNUSED_PAD src0_sel:WORD_1
	v_cvt_f32_f16_e32 v26, v29
	s_waitcnt vmcnt(2)
	v_add_f32_e32 v4, v4, v0
	v_add_f32_e32 v5, v5, v1
	v_add_f32_e32 v6, v6, v2
	v_add_f32_e32 v7, v7, v3
	s_waitcnt vmcnt(1)
	v_pk_mul_f32 v[16:17], v[16:17], v[24:25]
	v_mul_f32_e32 v4, 0xbfb8aa3b, v4
	v_mul_f32_e32 v5, 0xbfb8aa3b, v5
	v_mul_f32_e32 v6, 0xbfb8aa3b, v6
	v_mul_f32_e32 v7, 0xbfb8aa3b, v7
	v_pk_mul_f32 v[2:3], v[44:45], v[16:17] op_sel_hi:[0,1]
	v_exp_f32_e32 v16, v4
	v_exp_f32_e32 v17, v5
	v_exp_f32_e32 v6, v6
	v_exp_f32_e32 v7, v7
	v_pk_mul_f32 v[0:1], v[18:19], v[26:27]
	v_cvt_pk_f16_f32 v4, v2, v3
	v_pk_mul_f32 v[0:1], v[44:45], v[0:1] op_sel_hi:[0,1]
	v_cvt_pk_f16_f32 v5, v0, v1
	v_mov_b32_e32 v244, v4
	v_mov_b32_e32 v245, v5
	s_nop 1
	v_permlane32_swap_b32_e32 v242, v244
	v_permlane32_swap_b32_e32 v243, v245
	global_store_dwordx4 v[238:239], v[242:245], off offset:192
	v_add_f32_e32 v4, 1.0, v16
	v_add_f32_e32 v5, 1.0, v17
	v_add_f32_e32 v6, 1.0, v6
	v_add_f32_e32 v7, 1.0, v7
	v_rcp_f32_e32 v4, v4
	v_rcp_f32_e32 v5, v5
	v_rcp_f32_e32 v6, v6
	v_rcp_f32_e32 v7, v7
	global_load_dwordx2 v[28:29], v[40:41], off offset:224
	v_pk_add_f32 v[16:17], v[4:5], -1.0 op_sel_hi:[1,0]
	v_pk_mul_f32 v[2:3], v[4:5], v[2:3] neg_lo:[0,1] neg_hi:[0,1]
	v_pk_add_f32 v[4:5], v[6:7], -1.0 op_sel_hi:[1,0]
	v_pk_mul_f32 v[0:1], v[6:7], v[0:1] neg_lo:[0,1] neg_hi:[0,1]
	s_waitcnt vmcnt(2)
; __device__ __forceinline__ float h_lo(unsigned u) { f16x2_t r = __builtin_bit_cast(f16x2_t, u); return (float)r.x; }
; __device__ __forceinline__ float h_hi(unsigned u) { f16x2_t r = __builtin_bit_cast(f16x2_t, u); return (float)r.y; }
; __device__ __forceinline__ float sigm(float x) { return __builtin_amdgcn_rcpf(1.f + __builtin_amdgcn_exp2f(-LOG2E * x)); }
; __device__ __forceinline__ void epi_adir(const f32x16 (&acc)[2][2], int nbase, int tbase, int M, CP& p, int dir) {
;     ...
;       for (int nb = 0; nb < 2; ++nb)
; #pragma unroll
;         for (int i = 0; i < 4; ++i) {
;           const int c = nb * 32 + 8 * i + 4 * h;
;           const u32x2 kr = *(const u32x2*)(DIR + rec + 64 + c);
;           const float kv[4] = {h_lo(kr.x), h_hi(kr.x), h_lo(kr.y), h_hi(kr.y)};
;           const f32x4 kkw = *(const f32x4*)(p.k_k + nbase + c);
;           const f32x4 kaw = *(const f32x4*)(p.k_a + nbase + c);
;           const f32x4 a0v = *(const f32x4*)(a0 + nbase + c);
;           float kk[4], kd[4], bp[4];
; #pragma unroll
;           for (int j = 0; j < 4; ++j) {
;             const float k = kv[j];
;             kk[j] = k * kkw[j] * inv;
;             const float aa = sigm(a0v[j] + acc[nb][tb][4 * i + j]);
;             kd[j] = k * (1.f + (aa - 1.f) * kaw[j]);
;             bp[j] = -kk[j] * aa;
;           }
;           if (dir == 0) *(u32x2*)(p.RKV + rec + 64 + c) = (u32x2){pk_f16(kk[0], kk[1]), pk_f16(kk[2], kk[3])};
;           *(u32x2*)(DIR + rec + 64 + c) = (u32x2){pk_f16(kd[0], kd[1]), pk_f16(kd[2], kd[3])};
;           *(u32x2*)(DIR + rec + 128 + c) = (u32x2){pk_f16(bp[0], bp[1]), pk_f16(bp[2], bp[3])};
;         }
	v_pk_fma_f32 v[6:7], v[20:21], v[16:17], 1.0 op_sel_hi:[1,1,0]
	v_pk_fma_f32 v[4:5], v[22:23], v[4:5], 1.0 op_sel_hi:[1,1,0]
	v_cvt_pk_f16_f32 v2, v2, v3
	v_cvt_pk_f16_f32 v3, v0, v1
	v_pk_mul_f32 v[0:1], v[6:7], v[24:25]
	v_pk_mul_f32 v[4:5], v[4:5], v[26:27]
	v_cvt_pk_f16_f32 v0, v0, v1
	v_cvt_pk_f16_f32 v1, v4, v5
	v_mov_b32_e32 v248, v2
	v_mov_b32_e32 v249, v3
	s_nop 1
	v_permlane32_swap_b32_e32 v246, v248
	v_permlane32_swap_b32_e32 v247, v249
	global_store_dwordx4 v[240:241], v[246:249], off offset:320
	v_mov_b32_e32 v224, v0
	v_mov_b32_e32 v225, v1
	s_nop 1
	v_permlane32_swap_b32_e32 v222, v224
	v_permlane32_swap_b32_e32 v223, v225
	global_store_dwordx4 v[240:241], v[222:225], off offset:192
	global_load_dwordx4 v[0:3], v[38:39], off offset:192
	s_nop 0
	global_load_dwordx4 v[4:7], v[76:77], off offset:192
	global_load_dwordx4 v[16:19], v[36:37], off offset:192
	s_waitcnt vmcnt(5)
	v_cvt_f32_f16_sdwa v21, v28 dst_sel:DWORD dst_unused:UNUSED_PAD src0_sel:WORD_1
	v_cvt_f32_f16_e32 v20, v28
	v_cvt_f32_f16_sdwa v23, v29 dst_sel:DWORD dst_unused:UNUSED_PAD src0_sel:WORD_1
	v_cvt_f32_f16_e32 v22, v29
	s_waitcnt vmcnt(2)
	v_add_f32_e32 v8, v8, v0
	s_waitcnt vmcnt(1)
	v_pk_mul_f32 v[4:5], v[4:5], v[20:21]
	v_add_f32_e32 v9, v9, v1
	v_add_f32_e32 v10, v10, v2
	v_pk_mul_f32 v[0:1], v[6:7], v[22:23]
	v_add_f32_e32 v6, v11, v3
	v_mul_f32_e32 v7, 0xbfb8aa3b, v8
	v_pk_mul_f32 v[2:3], v[44:45], v[4:5] op_sel_hi:[0,1]
	v_mul_f32_e32 v4, 0xbfb8aa3b, v9
	v_mul_f32_e32 v5, 0xbfb8aa3b, v10
	v_mul_f32_e32 v6, 0xbfb8aa3b, v6
	v_exp_f32_e32 v7, v7
	v_exp_f32_e32 v8, v4
	v_exp_f32_e32 v9, v5
	v_exp_f32_e32 v6, v6
	v_pk_mul_f32 v[0:1], v[44:45], v[0:1] op_sel_hi:[0,1]
	v_cvt_pk_f16_f32 v4, v2, v3
	v_cvt_pk_f16_f32 v5, v0, v1
	v_mov_b32_e32 v226, v4
	v_mov_b32_e32 v227, v5
	v_add_f32_e32 v4, 1.0, v7
	v_add_f32_e32 v5, 1.0, v8
	v_add_f32_e32 v7, 1.0, v9
	v_add_f32_e32 v8, 1.0, v6
	v_rcp_f32_e32 v4, v4
	v_rcp_f32_e32 v5, v5
	v_rcp_f32_e32 v6, v7
	v_rcp_f32_e32 v7, v8
	global_load_dwordx2 v[24:25], v[40:41], off offset:240
	v_pk_add_f32 v[8:9], v[4:5], -1.0 op_sel_hi:[1,0]
	v_pk_mul_f32 v[2:3], v[4:5], v[2:3] neg_lo:[0,1] neg_hi:[0,1]
	v_pk_add_f32 v[4:5], v[6:7], -1.0 op_sel_hi:[1,0]
	v_pk_mul_f32 v[0:1], v[6:7], v[0:1] neg_lo:[0,1] neg_hi:[0,1]
	s_waitcnt vmcnt(1)
	v_pk_fma_f32 v[6:7], v[16:17], v[8:9], 1.0 op_sel_hi:[1,1,0]
	v_pk_fma_f32 v[4:5], v[18:19], v[4:5], 1.0 op_sel_hi:[1,1,0]
	v_cvt_pk_f16_f32 v2, v2, v3
	v_cvt_pk_f16_f32 v3, v0, v1
	v_pk_mul_f32 v[0:1], v[6:7], v[20:21]
	v_pk_mul_f32 v[4:5], v[4:5], v[22:23]
	v_cvt_pk_f16_f32 v0, v0, v1
	v_cvt_pk_f16_f32 v1, v4, v5
	v_mov_b32_e32 v230, v2
	v_mov_b32_e32 v231, v3
	v_mov_b32_e32 v234, v0
	v_mov_b32_e32 v235, v1
	global_load_dwordx4 v[0:3], v[38:39], off offset:224
	s_nop 0
	global_load_dwordx4 v[4:7], v[76:77], off offset:224
	global_load_dwordx4 v[8:11], v[36:37], off offset:224
	s_waitcnt vmcnt(3)
	v_cvt_f32_f16_sdwa v17, v24 dst_sel:DWORD dst_unused:UNUSED_PAD src0_sel:WORD_1
	v_cvt_f32_f16_e32 v16, v24
	v_cvt_f32_f16_sdwa v19, v25 dst_sel:DWORD dst_unused:UNUSED_PAD src0_sel:WORD_1
	v_cvt_f32_f16_e32 v18, v25
	s_waitcnt vmcnt(2)
	v_add_f32_e32 v12, v12, v0
	s_waitcnt vmcnt(1)
	v_pk_mul_f32 v[4:5], v[4:5], v[16:17]
	v_add_f32_e32 v13, v13, v1
	v_add_f32_e32 v14, v14, v2
	v_pk_mul_f32 v[0:1], v[6:7], v[18:19]
	v_add_f32_e32 v6, v15, v3
	v_mul_f32_e32 v7, 0xbfb8aa3b, v12
	v_pk_mul_f32 v[2:3], v[44:45], v[4:5] op_sel_hi:[0,1]
	v_mul_f32_e32 v4, 0xbfb8aa3b, v13
	v_mul_f32_e32 v5, 0xbfb8aa3b, v14
	v_mul_f32_e32 v6, 0xbfb8aa3b, v6
	v_exp_f32_e32 v7, v7
	v_exp_f32_e32 v12, v4
	v_exp_f32_e32 v13, v5
	v_exp_f32_e32 v6, v6
	v_add_f32_e32 v7, 1.0, v7
	v_add_f32_e32 v12, 1.0, v12
	v_add_f32_e32 v13, 1.0, v13
	v_add_f32_e32 v14, 1.0, v6
	v_rcp_f32_e32 v6, v7
	v_rcp_f32_e32 v7, v12
	v_rcp_f32_e32 v12, v13
	v_rcp_f32_e32 v13, v14
	v_pk_mul_f32 v[0:1], v[44:45], v[0:1] op_sel_hi:[0,1]
	v_cvt_pk_f16_f32 v4, v2, v3
	v_cvt_pk_f16_f32 v5, v0, v1
	v_mov_b32_e32 v228, v4
	v_mov_b32_e32 v229, v5
	s_nop 1
	v_permlane32_swap_b32_e32 v226, v228
	v_permlane32_swap_b32_e32 v227, v229
	global_store_dwordx4 v[238:239], v[226:229], off offset:224
	v_pk_add_f32 v[4:5], v[6:7], -1.0 op_sel_hi:[1,0]
	v_pk_mul_f32 v[2:3], v[6:7], v[2:3] neg_lo:[0,1] neg_hi:[0,1]
	v_pk_add_f32 v[6:7], v[12:13], -1.0 op_sel_hi:[1,0]
	v_pk_mul_f32 v[0:1], v[12:13], v[0:1] neg_lo:[0,1] neg_hi:[0,1]
	s_waitcnt vmcnt(1)
	v_pk_fma_f32 v[4:5], v[8:9], v[4:5], 1.0 op_sel_hi:[1,1,0]
	v_pk_fma_f32 v[6:7], v[10:11], v[6:7], 1.0 op_sel_hi:[1,1,0]
	v_cvt_pk_f16_f32 v2, v2, v3
	v_cvt_pk_f16_f32 v3, v0, v1
	v_pk_mul_f32 v[0:1], v[4:5], v[16:17]
	v_pk_mul_f32 v[4:5], v[6:7], v[18:19]
	v_cvt_pk_f16_f32 v0, v0, v1
	v_cvt_pk_f16_f32 v1, v4, v5
	v_mov_b32_e32 v236, v0
	v_mov_b32_e32 v237, v1
	s_nop 1
	v_permlane32_swap_b32_e32 v234, v236
	v_permlane32_swap_b32_e32 v235, v237
	global_store_dwordx4 v[240:241], v[234:237], off offset:224
	v_mov_b32_e32 v232, v2
	v_mov_b32_e32 v233, v3
	s_nop 1
	v_permlane32_swap_b32_e32 v230, v232
	v_permlane32_swap_b32_e32 v231, v233
	global_store_dwordx4 v[240:241], v[230:233], off offset:352
	s_branch .LBB0_493

; __device__ __forceinline__ float h_lo(unsigned u) { f16x2_t r = __builtin_bit_cast(f16x2_t, u); return (float)r.x; }
; __device__ __forceinline__ float h_hi(unsigned u) { f16x2_t r = __builtin_bit_cast(f16x2_t, u); return (float)r.y; }
; __device__ __forceinline__ void epi_adir(const f32x16 (&acc)[2][2], int nbase, int tbase, int M, CP& p, int dir) {
;     ...
;   for (int tb = 0; tb < 2; ++tb) {
;     const int tok = tbase + tb * 32 + l32;
;     const bool valid = tok < M;
;     const int tk = valid ? tok : M - 1;
;     const size_t rec = ((size_t)tk * 16 + head) * 192;
;     float nsq = 0.f;
; #pragma unroll
;     for (int nb = 0; nb < 2; ++nb)
; #pragma unroll
;       for (int i = 0; i < 4; ++i) {
;         const int c = nb * 32 + 8 * i + 4 * h;
;         const u32x2 kr = *(const u32x2*)(DIR + rec + 64 + c);
;         const f32x4 kkw = *(const f32x4*)(p.k_k + nbase + c);
;         const float q0 = h_lo(kr.x) * kkw[0], q1 = h_hi(kr.x) * kkw[1], q2 = h_lo(kr.y) * kkw[2], q3 = h_hi(kr.y) * kkw[3];
;         nsq += q0 * q0 + q1 * q1 + q2 * q2 + q3 * q3;
;       }
;     nsq += __shfl_xor(nsq, 32);
;     const float inv = 1.f / fmaxf(sqrtf(nsq), 1e-12f);
.LBB0_517:
	s_or_b64 exec, exec, s[6:7]
	v_lshl_add_u32 v65, v65, 7, v90
	v_mov_b32_e32 v66, v204
	v_lshl_or_b32 v64, v64, 7, v97
	v_and_b32_e32 v69, 64, v211
	v_and_or_b32 v101, v66, 31, v65
	v_lshrrev_b32_e32 v65, 3, v66
	v_and_b32_e32 v70, 4, v65
	v_ashrrev_i32_e32 v65, 31, v64
	v_ashrrev_i32_e32 v84, 6, v64
	v_lshlrev_b64 v[64:65], 2, v[64:65]
	v_xor_b32_e32 v68, 32, v211
	v_add_u32_e32 v69, 64, v69
	v_lshl_add_u64 v[66:67], s[44:45], 0, v[64:65]
	v_cmp_lt_i32_e32 vcc, v68, v69
	v_lshl_add_u64 v[80:81], s[46:47], 0, v[64:65]
	v_lshl_add_u64 v[78:79], s[54:55], 0, v[64:65]
	v_min_i32_e32 v64, s51, v101
	v_ashrrev_i32_e32 v85, 31, v84
	v_cndmask_b32_e32 v68, v211, v68, vcc
	v_ashrrev_i32_e32 v65, 31, v64
	v_lshlrev_b32_e32 v100, 2, v68
	v_lshl_add_u64 v[64:65], v[64:65], 4, v[84:85]
	v_mov_b64_e32 v[68:69], s[58:59]
	v_mad_u64_u32 v[68:69], s[0:1], v64, s75, v[68:69]
	v_mad_i32_i24 v69, v65, s75, v69
	v_lshlrev_b32_e32 v160, 1, v70
	v_lshl_add_u64 v[86:87], v[68:69], 0, v[160:161]
	global_load_dwordx2 v[68:69], v[86:87], off offset:128
	v_lshlrev_b32_e32 v82, 2, v70
	v_mov_b32_e32 v83, v161
	v_lshl_add_u64 v[76:77], v[66:67], 0, v[82:83]
	global_load_dwordx4 v[64:67], v[76:77], off
	v_cmp_gt_i32_e32 vcc, s72, v101
	s_waitcnt vmcnt(1)
	v_cvt_f32_f16_e32 v70, v68
	v_cvt_f32_f16_sdwa v68, v68 dst_sel:DWORD dst_unused:UNUSED_PAD src0_sel:WORD_1
	v_cvt_f32_f16_e32 v71, v69
	v_cvt_f32_f16_sdwa v69, v69 dst_sel:DWORD dst_unused:UNUSED_PAD src0_sel:WORD_1
	s_waitcnt vmcnt(0)
	v_mul_f32_e32 v70, v64, v70
	v_mul_f32_e32 v68, v65, v68
	v_mul_f32_e32 v102, v68, v68
	v_mul_f32_e32 v71, v66, v71
	v_fmac_f32_e32 v102, v70, v70
	v_mul_f32_e32 v69, v67, v69
	v_fmac_f32_e32 v102, v71, v71
	v_fmac_f32_e32 v102, v69, v69
	global_load_dwordx2 v[88:89], v[86:87], off offset:144
	global_load_dwordx4 v[68:71], v[76:77], off offset:32
	s_waitcnt vmcnt(1)
	v_cvt_f32_f16_e32 v103, v88
	v_cvt_f32_f16_sdwa v88, v88 dst_sel:DWORD dst_unused:UNUSED_PAD src0_sel:WORD_1
	s_waitcnt vmcnt(0)
	v_mul_f32_e32 v68, v68, v103
	v_mul_f32_e32 v69, v69, v88
	v_cvt_f32_f16_e32 v88, v89
	v_mul_f32_e32 v69, v69, v69
	v_fmac_f32_e32 v69, v68, v68
	v_mul_f32_e32 v70, v70, v88
	v_cvt_f32_f16_sdwa v88, v89 dst_sel:DWORD dst_unused:UNUSED_PAD src0_sel:WORD_1
	v_fmac_f32_e32 v69, v70, v70
	v_mul_f32_e32 v71, v71, v88
	v_fmac_f32_e32 v69, v71, v71
	v_add_f32_e32 v102, v102, v69
	global_load_dwordx2 v[88:89], v[86:87], off offset:160
	global_load_dwordx4 v[68:71], v[76:77], off offset:64
	s_waitcnt vmcnt(1)
	v_cvt_f32_f16_e32 v103, v88
	v_cvt_f32_f16_sdwa v88, v88 dst_sel:DWORD dst_unused:UNUSED_PAD src0_sel:WORD_1
	s_waitcnt vmcnt(0)
	v_mul_f32_e32 v68, v68, v103
	v_mul_f32_e32 v69, v69, v88
	v_cvt_f32_f16_e32 v88, v89
	v_mul_f32_e32 v69, v69, v69
	v_fmac_f32_e32 v69, v68, v68
	v_mul_f32_e32 v70, v70, v88
	v_cvt_f32_f16_sdwa v88, v89 dst_sel:DWORD dst_unused:UNUSED_PAD src0_sel:WORD_1
	v_fmac_f32_e32 v69, v70, v70
	v_mul_f32_e32 v71, v71, v88
	v_fmac_f32_e32 v69, v71, v71
	v_add_f32_e32 v102, v102, v69
	global_load_dwordx2 v[88:89], v[86:87], off offset:176
	global_load_dwordx4 v[68:71], v[76:77], off offset:96
	s_waitcnt vmcnt(1)
	v_cvt_f32_f16_e32 v103, v88
	v_cvt_f32_f16_sdwa v88, v88 dst_sel:DWORD dst_unused:UNUSED_PAD src0_sel:WORD_1
	s_waitcnt vmcnt(0)
	v_mul_f32_e32 v68, v68, v103
	v_mul_f32_e32 v69, v69, v88
	v_cvt_f32_f16_e32 v88, v89
	v_mul_f32_e32 v69, v69, v69
	v_fmac_f32_e32 v69, v68, v68
	v_mul_f32_e32 v70, v70, v88
	v_cvt_f32_f16_sdwa v88, v89 dst_sel:DWORD dst_unused:UNUSED_PAD src0_sel:WORD_1
	v_fmac_f32_e32 v69, v70, v70
	v_mul_f32_e32 v71, v71, v88
	v_fmac_f32_e32 v69, v71, v71
	v_add_f32_e32 v102, v102, v69
	global_load_dwordx2 v[88:89], v[86:87], off offset:192
	global_load_dwordx4 v[68:71], v[76:77], off offset:128
	s_waitcnt vmcnt(1)
	v_cvt_f32_f16_e32 v103, v88
	v_cvt_f32_f16_sdwa v88, v88 dst_sel:DWORD dst_unused:UNUSED_PAD src0_sel:WORD_1
	s_waitcnt vmcnt(0)
	v_mul_f32_e32 v68, v68, v103
	v_mul_f32_e32 v69, v69, v88
	v_cvt_f32_f16_e32 v88, v89
	v_mul_f32_e32 v69, v69, v69
	v_fmac_f32_e32 v69, v68, v68
	v_mul_f32_e32 v70, v70, v88
	v_cvt_f32_f16_sdwa v88, v89 dst_sel:DWORD dst_unused:UNUSED_PAD src0_sel:WORD_1
	v_fmac_f32_e32 v69, v70, v70
	v_mul_f32_e32 v71, v71, v88
	v_fmac_f32_e32 v69, v71, v71
	v_add_f32_e32 v102, v102, v69
	global_load_dwordx2 v[88:89], v[86:87], off offset:208
	global_load_dwordx4 v[68:71], v[76:77], off offset:160
	s_waitcnt vmcnt(1)
	v_cvt_f32_f16_e32 v103, v88
	v_cvt_f32_f16_sdwa v88, v88 dst_sel:DWORD dst_unused:UNUSED_PAD src0_sel:WORD_1
	s_waitcnt vmcnt(0)
	v_mul_f32_e32 v68, v68, v103
	v_mul_f32_e32 v69, v69, v88
	v_cvt_f32_f16_e32 v88, v89
	v_mul_f32_e32 v69, v69, v69
	v_fmac_f32_e32 v69, v68, v68
	v_mul_f32_e32 v70, v70, v88
	v_cvt_f32_f16_sdwa v88, v89 dst_sel:DWORD dst_unused:UNUSED_PAD src0_sel:WORD_1
	v_fmac_f32_e32 v69, v70, v70
	v_mul_f32_e32 v71, v71, v88
	v_fmac_f32_e32 v69, v71, v71
	v_add_f32_e32 v102, v102, v69
	global_load_dwordx2 v[88:89], v[86:87], off offset:224
	global_load_dwordx4 v[68:71], v[76:77], off offset:192
	s_waitcnt vmcnt(1)
	v_cvt_f32_f16_e32 v103, v88
	v_cvt_f32_f16_sdwa v88, v88 dst_sel:DWORD dst_unused:UNUSED_PAD src0_sel:WORD_1
	s_waitcnt vmcnt(0)
	v_mul_f32_e32 v68, v68, v103
	v_mul_f32_e32 v69, v69, v88
	v_cvt_f32_f16_e32 v88, v89
	v_mul_f32_e32 v69, v69, v69
	v_fmac_f32_e32 v69, v68, v68
	v_mul_f32_e32 v70, v70, v88
	v_cvt_f32_f16_sdwa v88, v89 dst_sel:DWORD dst_unused:UNUSED_PAD src0_sel:WORD_1
	v_fmac_f32_e32 v69, v70, v70
	v_mul_f32_e32 v71, v71, v88
	v_fmac_f32_e32 v69, v71, v71
	v_add_f32_e32 v102, v102, v69
	global_load_dwordx2 v[88:89], v[86:87], off offset:240
	global_load_dwordx4 v[68:71], v[76:77], off offset:224
	s_waitcnt vmcnt(1)
	v_cvt_f32_f16_e32 v103, v88
	v_cvt_f32_f16_sdwa v88, v88 dst_sel:DWORD dst_unused:UNUSED_PAD src0_sel:WORD_1
	s_waitcnt vmcnt(0)
	v_mul_f32_e32 v68, v68, v103
	v_mul_f32_e32 v69, v69, v88
	v_cvt_f32_f16_e32 v88, v89
	v_mul_f32_e32 v69, v69, v69
	v_fmac_f32_e32 v69, v68, v68
	v_mul_f32_e32 v70, v70, v88
	v_cvt_f32_f16_sdwa v88, v89 dst_sel:DWORD dst_unused:UNUSED_PAD src0_sel:WORD_1
	v_fmac_f32_e32 v69, v70, v70
	v_mul_f32_e32 v71, v71, v88
	v_fmac_f32_e32 v69, v71, v71
	v_add_f32_e32 v68, v102, v69
	ds_bpermute_b32 v69, v100, v68
	s_and_saveexec_b64 s[34:35], vcc
	s_cbranch_execz .LBB0_519
; __device__ __forceinline__ float h_lo(unsigned u) { f16x2_t r = __builtin_bit_cast(f16x2_t, u); return (float)r.x; }
; __device__ __forceinline__ float h_hi(unsigned u) { f16x2_t r = __builtin_bit_cast(f16x2_t, u); return (float)r.y; }
; __device__ __forceinline__ float sigm(float x) { return __builtin_amdgcn_rcpf(1.f + __builtin_amdgcn_exp2f(-LOG2E * x)); }
; __device__ __forceinline__ void epi_adir(const f32x16 (&acc)[2][2], int nbase, int tbase, int M, CP& p, int dir) {
;     ...
;     if (valid) {
; #pragma unroll
;       for (int nb = 0; nb < 2; ++nb)
; #pragma unroll
;         for (int i = 0; i < 4; ++i) {
;           const int c = nb * 32 + 8 * i + 4 * h;
;           const u32x2 kr = *(const u32x2*)(DIR + rec + 64 + c);
;           const float kv[4] = {h_lo(kr.x), h_hi(kr.x), h_lo(kr.y), h_hi(kr.y)};
;           const f32x4 kkw = *(const f32x4*)(p.k_k + nbase + c);
;           const f32x4 kaw = *(const f32x4*)(p.k_a + nbase + c);
;           const f32x4 a0v = *(const f32x4*)(a0 + nbase + c);
;           float kk[4], kd[4], bp[4];
; #pragma unroll
;           for (int j = 0; j < 4; ++j) {
;             const float k = kv[j];
;             kk[j] = k * kkw[j] * inv;
;             const float aa = sigm(a0v[j] + acc[nb][tb][4 * i + j]);
;             kd[j] = k * (1.f + (aa - 1.f) * kaw[j]);
;             bp[j] = -kk[j] * aa;
;           }
;           if (dir == 0) *(u32x2*)(p.RKV + rec + 64 + c) = (u32x2){pk_f16(kk[0], kk[1]), pk_f16(kk[2], kk[3])};
;           *(u32x2*)(DIR + rec + 64 + c) = (u32x2){pk_f16(kd[0], kd[1]), pk_f16(kd[2], kd[3])};
;           *(u32x2*)(DIR + rec + 128 + c) = (u32x2){pk_f16(bp[0], bp[1]), pk_f16(bp[2], bp[3])};
;         }
	s_waitcnt lgkmcnt(0)
	v_add_f32_e32 v68, v68, v69
	s_mov_b32 s0, 0xf800000
	v_cmp_gt_f32_e32 vcc, s0, v68
	v_mul_f32_e32 v69, 0x4f800000, v68
	global_load_dwordx2 v[110:111], v[86:87], off offset:128
	v_cndmask_b32_e32 v68, v68, v69, vcc
	v_sqrt_f32_e32 v69, v68
	s_nop 0
	v_add_u32_e32 v70, -1, v69
	v_fma_f32 v71, -v70, v69, v68
	v_cmp_ge_f32_e64 s[42:43], 0, v71
	v_add_u32_e32 v71, 1, v69
	s_nop 0
	v_cndmask_b32_e64 v70, v69, v70, s[42:43]
	v_fma_f32 v69, -v71, v69, v68
	v_cmp_lt_f32_e64 s[42:43], 0, v69
	s_nop 1
	v_cndmask_b32_e64 v69, v70, v71, s[42:43]
	v_mul_f32_e32 v70, 0x37800000, v69
	v_cndmask_b32_e32 v69, v69, v70, vcc
	v_cmp_class_f32_e32 vcc, v68, v207
	s_nop 1
	v_cndmask_b32_e32 v68, v69, v68, vcc
	v_max_f32_e32 v68, 0x2b8cbccc, v68
	v_div_scale_f32 v69, s[0:1], v68, v68, 1.0
	v_rcp_f32_e32 v70, v69
	s_nop 0
	v_fma_f32 v71, -v69, v70, 1.0
	v_fmac_f32_e32 v70, v71, v70
	v_div_scale_f32 v71, vcc, 1.0, v68, 1.0
	v_mul_f32_e32 v88, v71, v70
	v_fma_f32 v89, -v69, v88, v71
	v_fmac_f32_e32 v88, v89, v70
	v_fma_f32 v69, -v69, v88, v71
	v_div_fmas_f32 v69, v69, v70, v88
	v_lshl_add_u64 v[70:71], v[78:79], 0, v[82:83]
	global_load_dwordx4 v[106:109], v[70:71], off
	v_lshl_add_u64 v[88:89], v[80:81], 0, v[82:83]
	global_load_dwordx4 v[102:105], v[88:89], off
	v_div_fixup_f32 v68, v69, v68, 1.0
	s_waitcnt vmcnt(1)
	v_add_f32_e32 v48, v48, v106
	v_add_f32_e32 v49, v49, v107
	v_mul_f32_e32 v48, 0xbfb8aa3b, v48
	v_mul_f32_e32 v49, 0xbfb8aa3b, v49
	v_exp_f32_e32 v48, v48
	v_exp_f32_e32 v49, v49
	v_cvt_f32_f16_sdwa v107, v110 dst_sel:DWORD dst_unused:UNUSED_PAD src0_sel:WORD_1
	v_cvt_f32_f16_e32 v106, v110
	v_add_f32_e32 v48, 1.0, v48
	v_add_f32_e32 v49, 1.0, v49
	v_rcp_f32_e32 v48, v48
	v_rcp_f32_e32 v49, v49
	v_add_f32_e32 v50, v50, v108
	v_add_f32_e32 v51, v51, v109
	v_mul_f32_e32 v50, 0xbfb8aa3b, v50
	v_mul_f32_e32 v51, 0xbfb8aa3b, v51
	v_pk_mul_f32 v[64:65], v[64:65], v[106:107] neg_lo:[0,1] neg_hi:[0,1]
	v_exp_f32_e32 v50, v50
	v_exp_f32_e32 v51, v51
	v_pk_mul_f32 v[64:65], v[68:69], v[64:65] op_sel_hi:[0,1]
	v_pk_mul_f32 v[64:65], v[64:65], v[48:49]
	v_pk_add_f32 v[48:49], v[48:49], -1.0 op_sel_hi:[1,0]
	v_add_f32_e32 v50, 1.0, v50
	s_waitcnt vmcnt(0)
	v_pk_fma_f32 v[48:49], v[102:103], v[48:49], 1.0 op_sel_hi:[1,1,0]
	v_cvt_f32_f16_sdwa v103, v111 dst_sel:DWORD dst_unused:UNUSED_PAD src0_sel:WORD_1
	v_cvt_f32_f16_e32 v102, v111
	v_add_f32_e32 v51, 1.0, v51
	v_rcp_f32_e32 v50, v50
	v_rcp_f32_e32 v51, v51
	v_pk_mul_f32 v[66:67], v[66:67], v[102:103] neg_lo:[0,1] neg_hi:[0,1]
	v_pk_mul_f32 v[48:49], v[48:49], v[106:107]
	v_pk_mul_f32 v[66:67], v[68:69], v[66:67] op_sel_hi:[0,1]
	v_pk_mul_f32 v[66:67], v[66:67], v[50:51]
	v_pk_add_f32 v[50:51], v[50:51], -1.0 op_sel_hi:[1,0]
	v_cvt_pk_f16_f32 v48, v48, v49
	v_pk_fma_f32 v[50:51], v[104:105], v[50:51], 1.0 op_sel_hi:[1,1,0]
	s_nop 0
	v_pk_mul_f32 v[50:51], v[50:51], v[102:103]
	s_nop 0
	v_cvt_pk_f16_f32 v49, v50, v51
	v_mbcnt_lo_u32_b32 v238, -1, 0
	v_mbcnt_hi_u32_b32 v238, -1, v238
	v_lshrrev_b32_e32 v238, 2, v238
	v_and_b32_e32 v238, 8, v238
	v_mov_b32_e32 v239, 0
	v_lshl_add_u64 v[238:239], v[86:87], 0, v[238:239]
	v_mov_b32_e32 v242, v48
	v_mov_b32_e32 v243, v49
	v_cvt_pk_f16_f32 v48, v64, v65
	v_cvt_pk_f16_f32 v49, v66, v67
	v_mov_b32_e32 v246, v48
	v_mov_b32_e32 v247, v49
	global_load_dwordx2 v[106:107], v[86:87], off offset:144
	s_nop 0
	global_load_dwordx4 v[48:51], v[76:77], off offset:32
	global_load_dwordx4 v[64:67], v[88:89], off offset:32
	global_load_dwordx4 v[102:105], v[70:71], off offset:32
	s_waitcnt vmcnt(0)
	v_add_f32_e32 v52, v52, v102
	v_add_f32_e32 v53, v53, v103
	v_mul_f32_e32 v52, 0xbfb8aa3b, v52
	v_mul_f32_e32 v53, 0xbfb8aa3b, v53
	v_exp_f32_e32 v52, v52
	v_exp_f32_e32 v53, v53
	v_cvt_f32_f16_sdwa v103, v106 dst_sel:DWORD dst_unused:UNUSED_PAD src0_sel:WORD_1
	v_cvt_f32_f16_e32 v102, v106
	v_add_f32_e32 v52, 1.0, v52
	v_add_f32_e32 v53, 1.0, v53
	v_rcp_f32_e32 v52, v52
	v_rcp_f32_e32 v53, v53
	v_add_f32_e32 v54, v54, v104
	v_add_f32_e32 v55, v55, v105
	v_mul_f32_e32 v54, 0xbfb8aa3b, v54
	v_mul_f32_e32 v55, 0xbfb8aa3b, v55
	v_pk_mul_f32 v[48:49], v[48:49], v[102:103] neg_lo:[0,1] neg_hi:[0,1]
	v_exp_f32_e32 v54, v54
	v_exp_f32_e32 v55, v55
	v_pk_mul_f32 v[48:49], v[68:69], v[48:49] op_sel_hi:[0,1]
	v_pk_mul_f32 v[48:49], v[48:49], v[52:53]
	v_pk_add_f32 v[52:53], v[52:53], -1.0 op_sel_hi:[1,0]
	v_add_f32_e32 v54, 1.0, v54
	v_pk_fma_f32 v[52:53], v[64:65], v[52:53], 1.0 op_sel_hi:[1,1,0]
	v_cvt_f32_f16_sdwa v65, v107 dst_sel:DWORD dst_unused:UNUSED_PAD src0_sel:WORD_1
	v_cvt_f32_f16_e32 v64, v107
	v_add_f32_e32 v55, 1.0, v55
	v_rcp_f32_e32 v54, v54
	v_rcp_f32_e32 v55, v55
	v_pk_mul_f32 v[50:51], v[50:51], v[64:65] neg_lo:[0,1] neg_hi:[0,1]
	v_pk_mul_f32 v[52:53], v[52:53], v[102:103]
	v_pk_mul_f32 v[50:51], v[68:69], v[50:51] op_sel_hi:[0,1]
	v_pk_mul_f32 v[50:51], v[50:51], v[54:55]
	v_pk_add_f32 v[54:55], v[54:55], -1.0 op_sel_hi:[1,0]
	v_cvt_pk_f16_f32 v52, v52, v53
	v_pk_fma_f32 v[54:55], v[66:67], v[54:55], 1.0 op_sel_hi:[1,1,0]
	v_cvt_pk_f16_f32 v48, v48, v49
	v_pk_mul_f32 v[54:55], v[54:55], v[64:65]
	v_cvt_pk_f16_f32 v49, v50, v51
	v_cvt_pk_f16_f32 v53, v54, v55
	v_mov_b32_e32 v244, v52
	v_mov_b32_e32 v245, v53
	s_nop 1
	v_permlane32_swap_b32_e32 v242, v244
	v_permlane32_swap_b32_e32 v243, v245
	global_store_dwordx4 v[238:239], v[242:245], off offset:128
	v_mov_b32_e32 v248, v48
	v_mov_b32_e32 v249, v49
	s_nop 1
	v_permlane32_swap_b32_e32 v246, v248
	v_permlane32_swap_b32_e32 v247, v249
	global_store_dwordx4 v[238:239], v[246:249], off offset:256
	global_load_dwordx2 v[102:103], v[86:87], off offset:160
	s_nop 0
	global_load_dwordx4 v[48:51], v[76:77], off offset:64
	global_load_dwordx4 v[52:55], v[88:89], off offset:64
	global_load_dwordx4 v[64:67], v[70:71], off offset:64
	s_waitcnt vmcnt(0)
; __device__ __forceinline__ float h_lo(unsigned u) { f16x2_t r = __builtin_bit_cast(f16x2_t, u); return (float)r.x; }
; __device__ __forceinline__ float h_hi(unsigned u) { f16x2_t r = __builtin_bit_cast(f16x2_t, u); return (float)r.y; }
; __device__ __forceinline__ float sigm(float x) { return __builtin_amdgcn_rcpf(1.f + __builtin_amdgcn_exp2f(-LOG2E * x)); }
; __device__ __forceinline__ void epi_adir(const f32x16 (&acc)[2][2], int nbase, int tbase, int M, CP& p, int dir) {
;     ...
;     if (valid) {
; #pragma unroll
;       for (int nb = 0; nb < 2; ++nb)
; #pragma unroll
;         for (int i = 0; i < 4; ++i) {
;           const int c = nb * 32 + 8 * i + 4 * h;
;           const u32x2 kr = *(const u32x2*)(DIR + rec + 64 + c);
;           const float kv[4] = {h_lo(kr.x), h_hi(kr.x), h_lo(kr.y), h_hi(kr.y)};
;           const f32x4 kkw = *(const f32x4*)(p.k_k + nbase + c);
;           const f32x4 kaw = *(const f32x4*)(p.k_a + nbase + c);
;           const f32x4 a0v = *(const f32x4*)(a0 + nbase + c);
;           float kk[4], kd[4], bp[4];
; #pragma unroll
;           for (int j = 0; j < 4; ++j) {
;             const float k = kv[j];
;             kk[j] = k * kkw[j] * inv;
;             const float aa = sigm(a0v[j] + acc[nb][tb][4 * i + j]);
;             kd[j] = k * (1.f + (aa - 1.f) * kaw[j]);
;             bp[j] = -kk[j] * aa;
;           }
;           if (dir == 0) *(u32x2*)(p.RKV + rec + 64 + c) = (u32x2){pk_f16(kk[0], kk[1]), pk_f16(kk[2], kk[3])};
;           *(u32x2*)(DIR + rec + 64 + c) = (u32x2){pk_f16(kd[0], kd[1]), pk_f16(kd[2], kd[3])};
;           *(u32x2*)(DIR + rec + 128 + c) = (u32x2){pk_f16(bp[0], bp[1]), pk_f16(bp[2], bp[3])};
;         }
	v_add_f32_e32 v56, v56, v64
	v_add_f32_e32 v57, v57, v65
	v_mul_f32_e32 v56, 0xbfb8aa3b, v56
	v_mul_f32_e32 v57, 0xbfb8aa3b, v57
	v_exp_f32_e32 v56, v56
	v_exp_f32_e32 v57, v57
	v_cvt_f32_f16_sdwa v65, v102 dst_sel:DWORD dst_unused:UNUSED_PAD src0_sel:WORD_1
	v_cvt_f32_f16_e32 v64, v102
	v_add_f32_e32 v56, 1.0, v56
	v_add_f32_e32 v57, 1.0, v57
	v_rcp_f32_e32 v56, v56
	v_rcp_f32_e32 v57, v57
	v_pk_mul_f32 v[48:49], v[48:49], v[64:65] neg_lo:[0,1] neg_hi:[0,1]
	s_nop 0
	v_pk_mul_f32 v[48:49], v[68:69], v[48:49] op_sel_hi:[0,1]
	v_pk_mul_f32 v[48:49], v[48:49], v[56:57]
	v_pk_add_f32 v[56:57], v[56:57], -1.0 op_sel_hi:[1,0]
	v_cvt_pk_f16_f32 v48, v48, v49
	v_pk_fma_f32 v[52:53], v[52:53], v[56:57], 1.0 op_sel_hi:[1,1,0]
	v_add_f32_e32 v56, v58, v66
	v_add_f32_e32 v57, v59, v67
	v_mul_f32_e32 v56, 0xbfb8aa3b, v56
	v_mul_f32_e32 v57, 0xbfb8aa3b, v57
	v_exp_f32_e32 v56, v56
	v_exp_f32_e32 v57, v57
	v_cvt_f32_f16_sdwa v59, v103 dst_sel:DWORD dst_unused:UNUSED_PAD src0_sel:WORD_1
	v_cvt_f32_f16_e32 v58, v103
	v_add_f32_e32 v56, 1.0, v56
	v_add_f32_e32 v57, 1.0, v57
	v_rcp_f32_e32 v56, v56
	v_rcp_f32_e32 v57, v57
	v_pk_mul_f32 v[50:51], v[50:51], v[58:59] neg_lo:[0,1] neg_hi:[0,1]
	v_pk_mul_f32 v[52:53], v[52:53], v[64:65]
	v_pk_mul_f32 v[50:51], v[68:69], v[50:51] op_sel_hi:[0,1]
	v_pk_mul_f32 v[50:51], v[50:51], v[56:57]
	v_pk_add_f32 v[56:57], v[56:57], -1.0 op_sel_hi:[1,0]
	v_cvt_pk_f16_f32 v52, v52, v53
	v_pk_fma_f32 v[54:55], v[54:55], v[56:57], 1.0 op_sel_hi:[1,1,0]
	v_cvt_pk_f16_f32 v49, v50, v51
	v_pk_mul_f32 v[54:55], v[54:55], v[58:59]
	v_mov_b32_e32 v222, v48
	v_mov_b32_e32 v223, v49
	v_cvt_pk_f16_f32 v53, v54, v55
	v_mov_b32_e32 v226, v52
	v_mov_b32_e32 v227, v53
	global_load_dwordx2 v[56:57], v[86:87], off offset:176
	s_nop 0
	global_load_dwordx4 v[52:55], v[76:77], off offset:96
	global_load_dwordx4 v[48:51], v[88:89], off offset:96
	global_load_dwordx4 v[64:67], v[70:71], off offset:96
	s_waitcnt vmcnt(0)
	v_add_f32_e32 v58, v60, v64
	v_add_f32_e32 v59, v61, v65
	v_mul_f32_e32 v58, 0xbfb8aa3b, v58
	v_mul_f32_e32 v59, 0xbfb8aa3b, v59
	v_exp_f32_e32 v58, v58
	v_exp_f32_e32 v59, v59
	v_cvt_f32_f16_sdwa v61, v56 dst_sel:DWORD dst_unused:UNUSED_PAD src0_sel:WORD_1
	v_cvt_f32_f16_e32 v60, v56
	v_add_f32_e32 v56, v62, v66
	v_add_f32_e32 v58, 1.0, v58
	v_add_f32_e32 v59, 1.0, v59
	v_mul_f32_e32 v56, 0xbfb8aa3b, v56
	v_rcp_f32_e32 v58, v58
	v_rcp_f32_e32 v59, v59
	v_exp_f32_e32 v56, v56
	v_pk_mul_f32 v[52:53], v[52:53], v[60:61] neg_lo:[0,1] neg_hi:[0,1]
	v_add_f32_e32 v56, 1.0, v56
	v_pk_mul_f32 v[52:53], v[68:69], v[52:53] op_sel_hi:[0,1]
	v_pk_mul_f32 v[52:53], v[52:53], v[58:59]
	v_pk_add_f32 v[58:59], v[58:59], -1.0 op_sel_hi:[1,0]
	s_nop 0
	v_pk_fma_f32 v[48:49], v[48:49], v[58:59], 1.0 op_sel_hi:[1,1,0]
	v_rcp_f32_e32 v58, v56
	v_add_f32_e32 v56, v63, v67
	v_mul_f32_e32 v56, 0xbfb8aa3b, v56
	v_exp_f32_e32 v56, v56
	v_pk_mul_f32 v[48:49], v[48:49], v[60:61]
	v_cvt_f32_f16_sdwa v61, v57 dst_sel:DWORD dst_unused:UNUSED_PAD src0_sel:WORD_1
	v_cvt_f32_f16_e32 v60, v57
	v_add_f32_e32 v56, 1.0, v56
	v_rcp_f32_e32 v59, v56
	v_cvt_pk_f16_f32 v48, v48, v49
	v_pk_mul_f32 v[54:55], v[54:55], v[60:61] neg_lo:[0,1] neg_hi:[0,1]
	v_pk_add_f32 v[56:57], v[58:59], -1.0 op_sel_hi:[1,0]
	s_nop 0
	v_pk_fma_f32 v[50:51], v[50:51], v[56:57], 1.0 op_sel_hi:[1,1,0]
	v_pk_mul_f32 v[54:55], v[68:69], v[54:55] op_sel_hi:[0,1]
	v_pk_mul_f32 v[50:51], v[50:51], v[60:61]
	v_pk_mul_f32 v[54:55], v[54:55], v[58:59]
	v_cvt_pk_f16_f32 v49, v50, v51
	v_mov_b32_e32 v228, v48
	v_mov_b32_e32 v229, v49
	s_nop 1
	v_permlane32_swap_b32_e32 v226, v228
	v_permlane32_swap_b32_e32 v227, v229
	global_store_dwordx4 v[238:239], v[226:229], off offset:160
	v_cvt_pk_f16_f32 v48, v52, v53
	v_cvt_pk_f16_f32 v49, v54, v55
	v_mov_b32_e32 v224, v48
	v_mov_b32_e32 v225, v49
	s_nop 1
	v_permlane32_swap_b32_e32 v222, v224
	v_permlane32_swap_b32_e32 v223, v225
	global_store_dwordx4 v[238:239], v[222:225], off offset:288
	global_load_dwordx2 v[60:61], v[86:87], off offset:192
	s_nop 0
	global_load_dwordx4 v[48:51], v[76:77], off offset:128
	global_load_dwordx4 v[52:55], v[88:89], off offset:128
	global_load_dwordx4 v[56:59], v[70:71], off offset:128
	s_waitcnt vmcnt(0)
	v_add_f32_e32 v32, v32, v56
	v_add_f32_e32 v33, v33, v57
	v_mul_f32_e32 v32, 0xbfb8aa3b, v32
	v_mul_f32_e32 v33, 0xbfb8aa3b, v33
	v_exp_f32_e32 v32, v32
	v_exp_f32_e32 v33, v33
	v_cvt_f32_f16_sdwa v57, v60 dst_sel:DWORD dst_unused:UNUSED_PAD src0_sel:WORD_1
	v_cvt_f32_f16_e32 v56, v60
	v_add_f32_e32 v32, 1.0, v32
	v_add_f32_e32 v33, 1.0, v33
	v_rcp_f32_e32 v32, v32
	v_rcp_f32_e32 v33, v33
	v_add_f32_e32 v34, v34, v58
	v_add_f32_e32 v35, v35, v59
	v_mul_f32_e32 v34, 0xbfb8aa3b, v34
	v_mul_f32_e32 v35, 0xbfb8aa3b, v35
	v_pk_mul_f32 v[48:49], v[48:49], v[56:57] neg_lo:[0,1] neg_hi:[0,1]
	v_exp_f32_e32 v34, v34
	v_exp_f32_e32 v35, v35
	v_pk_mul_f32 v[48:49], v[68:69], v[48:49] op_sel_hi:[0,1]
	v_pk_mul_f32 v[48:49], v[48:49], v[32:33]
	v_pk_add_f32 v[32:33], v[32:33], -1.0 op_sel_hi:[1,0]
	v_add_f32_e32 v34, 1.0, v34
	v_pk_fma_f32 v[32:33], v[52:53], v[32:33], 1.0 op_sel_hi:[1,1,0]
	v_cvt_f32_f16_sdwa v53, v61 dst_sel:DWORD dst_unused:UNUSED_PAD src0_sel:WORD_1
	v_cvt_f32_f16_e32 v52, v61
	v_add_f32_e32 v35, 1.0, v35
	v_rcp_f32_e32 v34, v34
	v_rcp_f32_e32 v35, v35
	v_pk_mul_f32 v[50:51], v[50:51], v[52:53] neg_lo:[0,1] neg_hi:[0,1]
	v_pk_mul_f32 v[32:33], v[32:33], v[56:57]
	v_pk_mul_f32 v[50:51], v[68:69], v[50:51] op_sel_hi:[0,1]
	v_pk_mul_f32 v[50:51], v[50:51], v[34:35]
	v_pk_add_f32 v[34:35], v[34:35], -1.0 op_sel_hi:[1,0]
	v_cvt_pk_f16_f32 v32, v32, v33
	v_pk_fma_f32 v[34:35], v[54:55], v[34:35], 1.0 op_sel_hi:[1,1,0]
	s_nop 0
	v_pk_mul_f32 v[34:35], v[34:35], v[52:53]
	s_nop 0
	v_cvt_pk_f16_f32 v33, v34, v35
	v_mov_b32_e32 v230, v32
	v_mov_b32_e32 v231, v33
	v_cvt_pk_f16_f32 v32, v48, v49
	v_cvt_pk_f16_f32 v33, v50, v51
	v_mov_b32_e32 v234, v32
	v_mov_b32_e32 v235, v33
	global_load_dwordx2 v[56:57], v[86:87], off offset:208
	s_nop 0
	global_load_dwordx4 v[32:35], v[76:77], off offset:160
	global_load_dwordx4 v[48:51], v[88:89], off offset:160
	global_load_dwordx4 v[52:55], v[70:71], off offset:160
	s_waitcnt vmcnt(0)
; __device__ __forceinline__ float h_lo(unsigned u) { f16x2_t r = __builtin_bit_cast(f16x2_t, u); return (float)r.x; }
; __device__ __forceinline__ float h_hi(unsigned u) { f16x2_t r = __builtin_bit_cast(f16x2_t, u); return (float)r.y; }
; __device__ __forceinline__ float sigm(float x) { return __builtin_amdgcn_rcpf(1.f + __builtin_amdgcn_exp2f(-LOG2E * x)); }
; __device__ __forceinline__ void epi_adir(const f32x16 (&acc)[2][2], int nbase, int tbase, int M, CP& p, int dir) {
;     ...
;     if (valid) {
; #pragma unroll
;       for (int nb = 0; nb < 2; ++nb)
; #pragma unroll
;         for (int i = 0; i < 4; ++i) {
;           const int c = nb * 32 + 8 * i + 4 * h;
;           const u32x2 kr = *(const u32x2*)(DIR + rec + 64 + c);
;           const float kv[4] = {h_lo(kr.x), h_hi(kr.x), h_lo(kr.y), h_hi(kr.y)};
;           const f32x4 kkw = *(const f32x4*)(p.k_k + nbase + c);
;           const f32x4 kaw = *(const f32x4*)(p.k_a + nbase + c);
;           const f32x4 a0v = *(const f32x4*)(a0 + nbase + c);
;           float kk[4], kd[4], bp[4];
; #pragma unroll
;           for (int j = 0; j < 4; ++j) {
;             const float k = kv[j];
;             kk[j] = k * kkw[j] * inv;
;             const float aa = sigm(a0v[j] + acc[nb][tb][4 * i + j]);
;             kd[j] = k * (1.f + (aa - 1.f) * kaw[j]);
;             bp[j] = -kk[j] * aa;
;           }
;           if (dir == 0) *(u32x2*)(p.RKV + rec + 64 + c) = (u32x2){pk_f16(kk[0], kk[1]), pk_f16(kk[2], kk[3])};
;           *(u32x2*)(DIR + rec + 64 + c) = (u32x2){pk_f16(kd[0], kd[1]), pk_f16(kd[2], kd[3])};
;           *(u32x2*)(DIR + rec + 128 + c) = (u32x2){pk_f16(bp[0], bp[1]), pk_f16(bp[2], bp[3])};
;         }
	v_add_f32_e32 v36, v36, v52
	v_add_f32_e32 v37, v37, v53
	v_mul_f32_e32 v36, 0xbfb8aa3b, v36
	v_mul_f32_e32 v37, 0xbfb8aa3b, v37
	v_exp_f32_e32 v36, v36
	v_exp_f32_e32 v37, v37
	v_cvt_f32_f16_sdwa v53, v56 dst_sel:DWORD dst_unused:UNUSED_PAD src0_sel:WORD_1
	v_cvt_f32_f16_e32 v52, v56
	v_add_f32_e32 v36, 1.0, v36
	v_add_f32_e32 v37, 1.0, v37
	v_rcp_f32_e32 v36, v36
	v_rcp_f32_e32 v37, v37
	v_add_f32_e32 v38, v38, v54
	v_add_f32_e32 v39, v39, v55
	v_mul_f32_e32 v38, 0xbfb8aa3b, v38
	v_mul_f32_e32 v39, 0xbfb8aa3b, v39
	v_pk_mul_f32 v[32:33], v[32:33], v[52:53] neg_lo:[0,1] neg_hi:[0,1]
	v_exp_f32_e32 v38, v38
	v_exp_f32_e32 v39, v39
	v_pk_mul_f32 v[32:33], v[68:69], v[32:33] op_sel_hi:[0,1]
	v_pk_mul_f32 v[32:33], v[32:33], v[36:37]
	v_pk_add_f32 v[36:37], v[36:37], -1.0 op_sel_hi:[1,0]
	v_add_f32_e32 v38, 1.0, v38
	v_pk_fma_f32 v[36:37], v[48:49], v[36:37], 1.0 op_sel_hi:[1,1,0]
	v_cvt_f32_f16_sdwa v49, v57 dst_sel:DWORD dst_unused:UNUSED_PAD src0_sel:WORD_1
	v_cvt_f32_f16_e32 v48, v57
	v_add_f32_e32 v39, 1.0, v39
	v_rcp_f32_e32 v38, v38
	v_rcp_f32_e32 v39, v39
	v_pk_mul_f32 v[34:35], v[34:35], v[48:49] neg_lo:[0,1] neg_hi:[0,1]
	v_pk_mul_f32 v[36:37], v[36:37], v[52:53]
	v_pk_mul_f32 v[34:35], v[68:69], v[34:35] op_sel_hi:[0,1]
	v_pk_mul_f32 v[34:35], v[34:35], v[38:39]
	v_pk_add_f32 v[38:39], v[38:39], -1.0 op_sel_hi:[1,0]
	v_cvt_pk_f16_f32 v36, v36, v37
	v_pk_fma_f32 v[38:39], v[50:51], v[38:39], 1.0 op_sel_hi:[1,1,0]
	v_cvt_pk_f16_f32 v32, v32, v33
	v_pk_mul_f32 v[38:39], v[38:39], v[48:49]
	v_cvt_pk_f16_f32 v33, v34, v35
	v_cvt_pk_f16_f32 v37, v38, v39
	v_mov_b32_e32 v232, v36
	v_mov_b32_e32 v233, v37
	s_nop 1
	v_permlane32_swap_b32_e32 v230, v232
	v_permlane32_swap_b32_e32 v231, v233
	global_store_dwordx4 v[238:239], v[230:233], off offset:192
	v_mov_b32_e32 v236, v32
	v_mov_b32_e32 v237, v33
	s_nop 1
	v_permlane32_swap_b32_e32 v234, v236
	v_permlane32_swap_b32_e32 v235, v237
	global_store_dwordx4 v[238:239], v[234:237], off offset:320
	global_load_dwordx2 v[52:53], v[86:87], off offset:224
	s_nop 0
	global_load_dwordx4 v[32:35], v[76:77], off offset:192
	global_load_dwordx4 v[36:39], v[88:89], off offset:192
	global_load_dwordx4 v[48:51], v[70:71], off offset:192
	s_waitcnt vmcnt(0)
	v_add_f32_e32 v40, v40, v48
	v_add_f32_e32 v41, v41, v49
	v_mul_f32_e32 v40, 0xbfb8aa3b, v40
	v_mul_f32_e32 v41, 0xbfb8aa3b, v41
	v_exp_f32_e32 v40, v40
	v_exp_f32_e32 v41, v41
	v_cvt_f32_f16_sdwa v49, v52 dst_sel:DWORD dst_unused:UNUSED_PAD src0_sel:WORD_1
	v_cvt_f32_f16_e32 v48, v52
	v_add_f32_e32 v40, 1.0, v40
	v_add_f32_e32 v41, 1.0, v41
	v_rcp_f32_e32 v40, v40
	v_rcp_f32_e32 v41, v41
	v_pk_mul_f32 v[32:33], v[32:33], v[48:49] neg_lo:[0,1] neg_hi:[0,1]
	s_nop 0
	v_pk_mul_f32 v[32:33], v[68:69], v[32:33] op_sel_hi:[0,1]
	v_pk_mul_f32 v[32:33], v[32:33], v[40:41]
	v_pk_add_f32 v[40:41], v[40:41], -1.0 op_sel_hi:[1,0]
	v_cvt_pk_f16_f32 v32, v32, v33
	v_pk_fma_f32 v[36:37], v[36:37], v[40:41], 1.0 op_sel_hi:[1,1,0]
	v_add_f32_e32 v40, v42, v50
	v_add_f32_e32 v41, v43, v51
	v_mul_f32_e32 v40, 0xbfb8aa3b, v40
	v_mul_f32_e32 v41, 0xbfb8aa3b, v41
	v_exp_f32_e32 v40, v40
	v_exp_f32_e32 v41, v41
	v_cvt_f32_f16_sdwa v43, v53 dst_sel:DWORD dst_unused:UNUSED_PAD src0_sel:WORD_1
	v_cvt_f32_f16_e32 v42, v53
	v_add_f32_e32 v40, 1.0, v40
	v_add_f32_e32 v41, 1.0, v41
	v_rcp_f32_e32 v40, v40
	v_rcp_f32_e32 v41, v41
	v_pk_mul_f32 v[34:35], v[34:35], v[42:43] neg_lo:[0,1] neg_hi:[0,1]
	v_pk_mul_f32 v[36:37], v[36:37], v[48:49]
	v_pk_mul_f32 v[34:35], v[68:69], v[34:35] op_sel_hi:[0,1]
	v_pk_mul_f32 v[34:35], v[34:35], v[40:41]
	v_pk_add_f32 v[40:41], v[40:41], -1.0 op_sel_hi:[1,0]
	v_cvt_pk_f16_f32 v36, v36, v37
	v_pk_fma_f32 v[38:39], v[38:39], v[40:41], 1.0 op_sel_hi:[1,1,0]
	v_cvt_pk_f16_f32 v33, v34, v35
	v_pk_mul_f32 v[38:39], v[38:39], v[42:43]
	v_mov_b32_e32 v242, v32
	v_mov_b32_e32 v243, v33
	v_cvt_pk_f16_f32 v37, v38, v39
	v_mov_b32_e32 v246, v36
	v_mov_b32_e32 v247, v37
	global_load_dwordx2 v[40:41], v[86:87], off offset:240
	s_nop 0
	global_load_dwordx4 v[36:39], v[76:77], off offset:224
	global_load_dwordx4 v[32:35], v[88:89], off offset:224
	global_load_dwordx4 v[48:51], v[70:71], off offset:224
	s_waitcnt vmcnt(0)
	v_add_f32_e32 v42, v44, v48
	v_add_f32_e32 v43, v45, v49
	v_mul_f32_e32 v42, 0xbfb8aa3b, v42
	v_mul_f32_e32 v43, 0xbfb8aa3b, v43
	v_exp_f32_e32 v42, v42
	v_exp_f32_e32 v43, v43
	v_cvt_f32_f16_sdwa v45, v40 dst_sel:DWORD dst_unused:UNUSED_PAD src0_sel:WORD_1
	v_cvt_f32_f16_e32 v44, v40
	v_add_f32_e32 v40, v46, v50
	v_add_f32_e32 v42, 1.0, v42
	v_add_f32_e32 v43, 1.0, v43
	v_mul_f32_e32 v40, 0xbfb8aa3b, v40
	v_rcp_f32_e32 v42, v42
	v_rcp_f32_e32 v43, v43
	v_exp_f32_e32 v40, v40
	v_pk_mul_f32 v[36:37], v[36:37], v[44:45] neg_lo:[0,1] neg_hi:[0,1]
	v_add_f32_e32 v40, 1.0, v40
	v_pk_mul_f32 v[36:37], v[68:69], v[36:37] op_sel_hi:[0,1]
	v_pk_mul_f32 v[36:37], v[36:37], v[42:43]
	v_pk_add_f32 v[42:43], v[42:43], -1.0 op_sel_hi:[1,0]
	s_nop 0
	v_pk_fma_f32 v[32:33], v[32:33], v[42:43], 1.0 op_sel_hi:[1,1,0]
	v_rcp_f32_e32 v42, v40
	v_add_f32_e32 v40, v47, v51
	v_mul_f32_e32 v40, 0xbfb8aa3b, v40
	v_exp_f32_e32 v40, v40
	v_pk_mul_f32 v[32:33], v[32:33], v[44:45]
	v_cvt_f32_f16_sdwa v45, v41 dst_sel:DWORD dst_unused:UNUSED_PAD src0_sel:WORD_1
	v_cvt_f32_f16_e32 v44, v41
	v_add_f32_e32 v40, 1.0, v40
	v_rcp_f32_e32 v43, v40
	v_cvt_pk_f16_f32 v32, v32, v33
	v_pk_mul_f32 v[38:39], v[38:39], v[44:45] neg_lo:[0,1] neg_hi:[0,1]
	v_pk_add_f32 v[40:41], v[42:43], -1.0 op_sel_hi:[1,0]
	s_nop 0
	v_pk_fma_f32 v[34:35], v[34:35], v[40:41], 1.0 op_sel_hi:[1,1,0]
	v_pk_mul_f32 v[38:39], v[68:69], v[38:39] op_sel_hi:[0,1]
	v_pk_mul_f32 v[34:35], v[34:35], v[44:45]
	v_pk_mul_f32 v[38:39], v[38:39], v[42:43]
	v_cvt_pk_f16_f32 v33, v34, v35
	v_mov_b32_e32 v248, v32
	v_mov_b32_e32 v249, v33
	s_nop 1
	v_permlane32_swap_b32_e32 v246, v248
	v_permlane32_swap_b32_e32 v247, v249
	global_store_dwordx4 v[238:239], v[246:249], off offset:224
	v_cvt_pk_f16_f32 v32, v36, v37
	v_cvt_pk_f16_f32 v33, v38, v39
	v_mov_b32_e32 v244, v32
	v_mov_b32_e32 v245, v33
	s_nop 1
	v_permlane32_swap_b32_e32 v242, v244
	v_permlane32_swap_b32_e32 v243, v245
	global_store_dwordx4 v[238:239], v[242:245], off offset:352
; __device__ __forceinline__ float h_lo(unsigned u) { f16x2_t r = __builtin_bit_cast(f16x2_t, u); return (float)r.x; }
; __device__ __forceinline__ float h_hi(unsigned u) { f16x2_t r = __builtin_bit_cast(f16x2_t, u); return (float)r.y; }
; __device__ __forceinline__ void epi_adir(const f32x16 (&acc)[2][2], int nbase, int tbase, int M, CP& p, int dir) {
;     ...
;   for (int tb = 0; tb < 2; ++tb) {
;     const int tok = tbase + tb * 32 + l32;
;     const bool valid = tok < M;
;     const int tk = valid ? tok : M - 1;
;     const size_t rec = ((size_t)tk * 16 + head) * 192;
;     float nsq = 0.f;
; #pragma unroll
;     for (int nb = 0; nb < 2; ++nb)
; #pragma unroll
;       for (int i = 0; i < 4; ++i) {
;         const int c = nb * 32 + 8 * i + 4 * h;
;         const u32x2 kr = *(const u32x2*)(DIR + rec + 64 + c);
;         const f32x4 kkw = *(const f32x4*)(p.k_k + nbase + c);
;         const float q0 = h_lo(kr.x) * kkw[0], q1 = h_hi(kr.x) * kkw[1], q2 = h_lo(kr.y) * kkw[2], q3 = h_hi(kr.y) * kkw[3];
;         nsq += q0 * q0 + q1 * q1 + q2 * q2 + q3 * q3;
;       }
;     nsq += __shfl_xor(nsq, 32);
;     const float inv = 1.f / fmaxf(sqrtf(nsq), 1e-12f);
.LBB0_519:
	s_or_b64 exec, exec, s[34:35]
	v_or_b32_e32 v44, 32, v101
	v_min_i32_e32 v32, s51, v44
	v_ashrrev_i32_e32 v33, 31, v32
	v_lshl_add_u64 v[32:33], v[32:33], 4, v[84:85]
	v_mov_b64_e32 v[34:35], s[58:59]
	v_mad_u64_u32 v[34:35], s[0:1], v32, s75, v[34:35]
	v_mad_i32_i24 v35, v33, s75, v35
	v_lshl_add_u64 v[40:41], v[34:35], 0, v[160:161]
	global_load_dwordx2 v[36:37], v[40:41], off offset:128
	global_load_dwordx4 v[32:35], v[76:77], off
	v_cmp_gt_i32_e32 vcc, s72, v44
	s_waitcnt vmcnt(1)
	v_cvt_f32_f16_e32 v38, v36
	v_cvt_f32_f16_sdwa v36, v36 dst_sel:DWORD dst_unused:UNUSED_PAD src0_sel:WORD_1
	v_cvt_f32_f16_e32 v39, v37
	v_cvt_f32_f16_sdwa v37, v37 dst_sel:DWORD dst_unused:UNUSED_PAD src0_sel:WORD_1
	s_waitcnt vmcnt(0)
	v_mul_f32_e32 v38, v32, v38
	v_mul_f32_e32 v36, v33, v36
	v_mul_f32_e32 v45, v36, v36
	v_mul_f32_e32 v39, v34, v39
	v_fmac_f32_e32 v45, v38, v38
	v_mul_f32_e32 v37, v35, v37
	v_fmac_f32_e32 v45, v39, v39
	v_fmac_f32_e32 v45, v37, v37
	global_load_dwordx2 v[42:43], v[40:41], off offset:144
	global_load_dwordx4 v[36:39], v[76:77], off offset:32
	s_waitcnt vmcnt(1)
	v_cvt_f32_f16_e32 v46, v42
	v_cvt_f32_f16_sdwa v42, v42 dst_sel:DWORD dst_unused:UNUSED_PAD src0_sel:WORD_1
	s_waitcnt vmcnt(0)
	v_mul_f32_e32 v36, v36, v46
	v_mul_f32_e32 v37, v37, v42
	v_cvt_f32_f16_e32 v42, v43
	v_mul_f32_e32 v37, v37, v37
	v_fmac_f32_e32 v37, v36, v36
	v_mul_f32_e32 v38, v38, v42
	v_cvt_f32_f16_sdwa v42, v43 dst_sel:DWORD dst_unused:UNUSED_PAD src0_sel:WORD_1
	v_fmac_f32_e32 v37, v38, v38
	v_mul_f32_e32 v39, v39, v42
	v_fmac_f32_e32 v37, v39, v39
	v_add_f32_e32 v45, v45, v37
	global_load_dwordx2 v[42:43], v[40:41], off offset:160
	global_load_dwordx4 v[36:39], v[76:77], off offset:64
	s_waitcnt vmcnt(1)
	v_cvt_f32_f16_e32 v46, v42
	v_cvt_f32_f16_sdwa v42, v42 dst_sel:DWORD dst_unused:UNUSED_PAD src0_sel:WORD_1
	s_waitcnt vmcnt(0)
	v_mul_f32_e32 v36, v36, v46
	v_mul_f32_e32 v37, v37, v42
	v_cvt_f32_f16_e32 v42, v43
	v_mul_f32_e32 v37, v37, v37
	v_fmac_f32_e32 v37, v36, v36
	v_mul_f32_e32 v38, v38, v42
	v_cvt_f32_f16_sdwa v42, v43 dst_sel:DWORD dst_unused:UNUSED_PAD src0_sel:WORD_1
	v_fmac_f32_e32 v37, v38, v38
	v_mul_f32_e32 v39, v39, v42
	v_fmac_f32_e32 v37, v39, v39
	v_add_f32_e32 v45, v45, v37
	global_load_dwordx2 v[42:43], v[40:41], off offset:176
	global_load_dwordx4 v[36:39], v[76:77], off offset:96
	s_waitcnt vmcnt(1)
	v_cvt_f32_f16_e32 v46, v42
	v_cvt_f32_f16_sdwa v42, v42 dst_sel:DWORD dst_unused:UNUSED_PAD src0_sel:WORD_1
	s_waitcnt vmcnt(0)
	v_mul_f32_e32 v36, v36, v46
	v_mul_f32_e32 v37, v37, v42
	v_cvt_f32_f16_e32 v42, v43
	v_mul_f32_e32 v37, v37, v37
	v_fmac_f32_e32 v37, v36, v36
	v_mul_f32_e32 v38, v38, v42
	v_cvt_f32_f16_sdwa v42, v43 dst_sel:DWORD dst_unused:UNUSED_PAD src0_sel:WORD_1
	v_fmac_f32_e32 v37, v38, v38
	v_mul_f32_e32 v39, v39, v42
	v_fmac_f32_e32 v37, v39, v39
	v_add_f32_e32 v45, v45, v37
	global_load_dwordx2 v[42:43], v[40:41], off offset:192
	global_load_dwordx4 v[36:39], v[76:77], off offset:128
	s_waitcnt vmcnt(1)
	v_cvt_f32_f16_e32 v46, v42
	v_cvt_f32_f16_sdwa v42, v42 dst_sel:DWORD dst_unused:UNUSED_PAD src0_sel:WORD_1
	s_waitcnt vmcnt(0)
	v_mul_f32_e32 v36, v36, v46
	v_mul_f32_e32 v37, v37, v42
	v_cvt_f32_f16_e32 v42, v43
	v_mul_f32_e32 v37, v37, v37
	v_fmac_f32_e32 v37, v36, v36
	v_mul_f32_e32 v38, v38, v42
	v_cvt_f32_f16_sdwa v42, v43 dst_sel:DWORD dst_unused:UNUSED_PAD src0_sel:WORD_1
	v_fmac_f32_e32 v37, v38, v38
	v_mul_f32_e32 v39, v39, v42
	v_fmac_f32_e32 v37, v39, v39
	v_add_f32_e32 v45, v45, v37
	global_load_dwordx2 v[42:43], v[40:41], off offset:208
	global_load_dwordx4 v[36:39], v[76:77], off offset:160
	s_waitcnt vmcnt(1)
	v_cvt_f32_f16_e32 v46, v42
	v_cvt_f32_f16_sdwa v42, v42 dst_sel:DWORD dst_unused:UNUSED_PAD src0_sel:WORD_1
	s_waitcnt vmcnt(0)
	v_mul_f32_e32 v36, v36, v46
	v_mul_f32_e32 v37, v37, v42
	v_cvt_f32_f16_e32 v42, v43
	v_mul_f32_e32 v37, v37, v37
	v_fmac_f32_e32 v37, v36, v36
	v_mul_f32_e32 v38, v38, v42
	v_cvt_f32_f16_sdwa v42, v43 dst_sel:DWORD dst_unused:UNUSED_PAD src0_sel:WORD_1
	v_fmac_f32_e32 v37, v38, v38
	v_mul_f32_e32 v39, v39, v42
	v_fmac_f32_e32 v37, v39, v39
	v_add_f32_e32 v45, v45, v37
	global_load_dwordx2 v[42:43], v[40:41], off offset:224
	global_load_dwordx4 v[36:39], v[76:77], off offset:192
	s_waitcnt vmcnt(1)
	v_cvt_f32_f16_e32 v46, v42
	v_cvt_f32_f16_sdwa v42, v42 dst_sel:DWORD dst_unused:UNUSED_PAD src0_sel:WORD_1
	s_waitcnt vmcnt(0)
	v_mul_f32_e32 v36, v36, v46
	v_mul_f32_e32 v37, v37, v42
	v_cvt_f32_f16_e32 v42, v43
	v_mul_f32_e32 v37, v37, v37
	v_fmac_f32_e32 v37, v36, v36
	v_mul_f32_e32 v38, v38, v42
	v_cvt_f32_f16_sdwa v42, v43 dst_sel:DWORD dst_unused:UNUSED_PAD src0_sel:WORD_1
	v_fmac_f32_e32 v37, v38, v38
	v_mul_f32_e32 v39, v39, v42
	v_fmac_f32_e32 v37, v39, v39
	v_add_f32_e32 v45, v45, v37
	global_load_dwordx2 v[42:43], v[40:41], off offset:240
	global_load_dwordx4 v[36:39], v[76:77], off offset:224
	s_waitcnt vmcnt(1)
	v_cvt_f32_f16_e32 v46, v42
	v_cvt_f32_f16_sdwa v42, v42 dst_sel:DWORD dst_unused:UNUSED_PAD src0_sel:WORD_1
	s_waitcnt vmcnt(0)
	v_mul_f32_e32 v36, v36, v46
	v_mul_f32_e32 v37, v37, v42
	v_cvt_f32_f16_e32 v42, v43
	v_mul_f32_e32 v37, v37, v37
	v_fmac_f32_e32 v37, v36, v36
	v_mul_f32_e32 v38, v38, v42
	v_cvt_f32_f16_sdwa v42, v43 dst_sel:DWORD dst_unused:UNUSED_PAD src0_sel:WORD_1
	v_fmac_f32_e32 v37, v38, v38
	v_mul_f32_e32 v39, v39, v42
	v_fmac_f32_e32 v37, v39, v39
	v_add_f32_e32 v36, v45, v37
	ds_bpermute_b32 v37, v100, v36
	s_and_saveexec_b64 s[34:35], vcc
	s_cbranch_execz .LBB0_510
; __device__ __forceinline__ float h_lo(unsigned u) { f16x2_t r = __builtin_bit_cast(f16x2_t, u); return (float)r.x; }
; __device__ __forceinline__ float h_hi(unsigned u) { f16x2_t r = __builtin_bit_cast(f16x2_t, u); return (float)r.y; }
; __device__ __forceinline__ float sigm(float x) { return __builtin_amdgcn_rcpf(1.f + __builtin_amdgcn_exp2f(-LOG2E * x)); }
; __device__ __forceinline__ void epi_adir(const f32x16 (&acc)[2][2], int nbase, int tbase, int M, CP& p, int dir) {
;     ...
;     if (valid) {
; #pragma unroll
;       for (int nb = 0; nb < 2; ++nb)
; #pragma unroll
;         for (int i = 0; i < 4; ++i) {
;           const int c = nb * 32 + 8 * i + 4 * h;
;           const u32x2 kr = *(const u32x2*)(DIR + rec + 64 + c);
;           const float kv[4] = {h_lo(kr.x), h_hi(kr.x), h_lo(kr.y), h_hi(kr.y)};
;           const f32x4 kkw = *(const f32x4*)(p.k_k + nbase + c);
;           const f32x4 kaw = *(const f32x4*)(p.k_a + nbase + c);
;           const f32x4 a0v = *(const f32x4*)(a0 + nbase + c);
;           float kk[4], kd[4], bp[4];
; #pragma unroll
;           for (int j = 0; j < 4; ++j) {
;             const float k = kv[j];
;             kk[j] = k * kkw[j] * inv;
;             const float aa = sigm(a0v[j] + acc[nb][tb][4 * i + j]);
;             kd[j] = k * (1.f + (aa - 1.f) * kaw[j]);
;             bp[j] = -kk[j] * aa;
;           }
;           if (dir == 0) *(u32x2*)(p.RKV + rec + 64 + c) = (u32x2){pk_f16(kk[0], kk[1]), pk_f16(kk[2], kk[3])};
;           *(u32x2*)(DIR + rec + 64 + c) = (u32x2){pk_f16(kd[0], kd[1]), pk_f16(kd[2], kd[3])};
;           *(u32x2*)(DIR + rec + 128 + c) = (u32x2){pk_f16(bp[0], bp[1]), pk_f16(bp[2], bp[3])};
;         }
	s_waitcnt lgkmcnt(0)
	v_add_f32_e32 v36, v36, v37
	s_mov_b32 s0, 0xf800000
	v_cmp_gt_f32_e32 vcc, s0, v36
	v_mul_f32_e32 v37, 0x4f800000, v36
	v_mov_b32_e32 v83, v161
	v_cndmask_b32_e32 v36, v36, v37, vcc
	v_sqrt_f32_e32 v37, v36
	global_load_dwordx2 v[52:53], v[40:41], off offset:128
	v_add_u32_e32 v38, -1, v37
	v_fma_f32 v39, -v38, v37, v36
	v_cmp_ge_f32_e64 s[42:43], 0, v39
	v_add_u32_e32 v39, 1, v37
	s_nop 0
	v_cndmask_b32_e64 v38, v37, v38, s[42:43]
	v_fma_f32 v37, -v39, v37, v36
	v_cmp_lt_f32_e64 s[42:43], 0, v37
	s_nop 1
	v_cndmask_b32_e64 v37, v38, v39, s[42:43]
	v_mul_f32_e32 v38, 0x37800000, v37
	v_cndmask_b32_e32 v37, v37, v38, vcc
	v_cmp_class_f32_e32 vcc, v36, v207
	s_nop 1
	v_cndmask_b32_e32 v36, v37, v36, vcc
	v_max_f32_e32 v36, 0x2b8cbccc, v36
	v_div_scale_f32 v37, s[0:1], v36, v36, 1.0
	v_rcp_f32_e32 v38, v37
	s_nop 0
	v_fma_f32 v39, -v37, v38, 1.0
	v_fmac_f32_e32 v38, v39, v38
	v_div_scale_f32 v39, vcc, 1.0, v36, 1.0
	v_mul_f32_e32 v42, v39, v38
	v_fma_f32 v43, -v37, v42, v39
	v_fmac_f32_e32 v42, v43, v38
	v_fma_f32 v37, -v37, v42, v39
	v_div_fmas_f32 v37, v37, v38, v42
	v_lshl_add_u64 v[38:39], v[78:79], 0, v[82:83]
	global_load_dwordx4 v[48:51], v[38:39], off
	v_lshl_add_u64 v[42:43], v[80:81], 0, v[82:83]
	global_load_dwordx4 v[44:47], v[42:43], off
	v_div_fixup_f32 v36, v37, v36, 1.0
	s_waitcnt vmcnt(1)
	v_add_f32_e32 v16, v16, v48
	v_add_f32_e32 v17, v17, v49
	v_mul_f32_e32 v16, 0xbfb8aa3b, v16
	v_mul_f32_e32 v17, 0xbfb8aa3b, v17
	v_exp_f32_e32 v16, v16
	v_exp_f32_e32 v17, v17
	v_cvt_f32_f16_sdwa v49, v52 dst_sel:DWORD dst_unused:UNUSED_PAD src0_sel:WORD_1
	v_cvt_f32_f16_e32 v48, v52
	v_add_f32_e32 v16, 1.0, v16
	v_add_f32_e32 v17, 1.0, v17
	v_rcp_f32_e32 v16, v16
	v_rcp_f32_e32 v17, v17
	v_add_f32_e32 v18, v18, v50
	v_add_f32_e32 v19, v19, v51
	v_mul_f32_e32 v18, 0xbfb8aa3b, v18
	v_mul_f32_e32 v19, 0xbfb8aa3b, v19
	v_pk_mul_f32 v[32:33], v[32:33], v[48:49] neg_lo:[0,1] neg_hi:[0,1]
	v_exp_f32_e32 v18, v18
	v_exp_f32_e32 v19, v19
	v_pk_mul_f32 v[32:33], v[36:37], v[32:33] op_sel_hi:[0,1]
	v_pk_mul_f32 v[32:33], v[32:33], v[16:17]
	v_pk_add_f32 v[16:17], v[16:17], -1.0 op_sel_hi:[1,0]
	v_add_f32_e32 v18, 1.0, v18
	s_waitcnt vmcnt(0)
	v_pk_fma_f32 v[16:17], v[44:45], v[16:17], 1.0 op_sel_hi:[1,1,0]
	v_cvt_f32_f16_sdwa v45, v53 dst_sel:DWORD dst_unused:UNUSED_PAD src0_sel:WORD_1
	v_cvt_f32_f16_e32 v44, v53
	v_add_f32_e32 v19, 1.0, v19
	v_rcp_f32_e32 v18, v18
	v_rcp_f32_e32 v19, v19
	v_pk_mul_f32 v[34:35], v[34:35], v[44:45] neg_lo:[0,1] neg_hi:[0,1]
	v_pk_mul_f32 v[16:17], v[16:17], v[48:49]
	v_pk_mul_f32 v[34:35], v[36:37], v[34:35] op_sel_hi:[0,1]
	v_pk_mul_f32 v[34:35], v[34:35], v[18:19]
	v_pk_add_f32 v[18:19], v[18:19], -1.0 op_sel_hi:[1,0]
	v_cvt_pk_f16_f32 v16, v16, v17
	v_pk_fma_f32 v[18:19], v[46:47], v[18:19], 1.0 op_sel_hi:[1,1,0]
	s_nop 0
	v_pk_mul_f32 v[18:19], v[18:19], v[44:45]
	s_nop 0
	v_cvt_pk_f16_f32 v17, v18, v19
	v_mbcnt_lo_u32_b32 v238, -1, 0
	v_mbcnt_hi_u32_b32 v238, -1, v238
	v_lshrrev_b32_e32 v238, 2, v238
	v_and_b32_e32 v238, 8, v238
	v_mov_b32_e32 v239, 0
	v_lshl_add_u64 v[238:239], v[40:41], 0, v[238:239]
	v_mov_b32_e32 v222, v16
	v_mov_b32_e32 v223, v17
	v_cvt_pk_f16_f32 v16, v32, v33
	v_cvt_pk_f16_f32 v17, v34, v35
	v_mov_b32_e32 v226, v16
	v_mov_b32_e32 v227, v17
	global_load_dwordx2 v[48:49], v[40:41], off offset:144
	s_nop 0
	global_load_dwordx4 v[16:19], v[76:77], off offset:32
	global_load_dwordx4 v[32:35], v[42:43], off offset:32
	global_load_dwordx4 v[44:47], v[38:39], off offset:32
	s_waitcnt vmcnt(0)
	v_add_f32_e32 v20, v20, v44
	v_add_f32_e32 v21, v21, v45
	v_mul_f32_e32 v20, 0xbfb8aa3b, v20
	v_mul_f32_e32 v21, 0xbfb8aa3b, v21
	v_exp_f32_e32 v20, v20
	v_exp_f32_e32 v21, v21
	v_cvt_f32_f16_sdwa v45, v48 dst_sel:DWORD dst_unused:UNUSED_PAD src0_sel:WORD_1
	v_cvt_f32_f16_e32 v44, v48
	v_add_f32_e32 v20, 1.0, v20
	v_add_f32_e32 v21, 1.0, v21
	v_rcp_f32_e32 v20, v20
	v_rcp_f32_e32 v21, v21
	v_add_f32_e32 v22, v22, v46
	v_add_f32_e32 v23, v23, v47
	v_mul_f32_e32 v22, 0xbfb8aa3b, v22
	v_mul_f32_e32 v23, 0xbfb8aa3b, v23
	v_pk_mul_f32 v[16:17], v[16:17], v[44:45] neg_lo:[0,1] neg_hi:[0,1]
	v_exp_f32_e32 v22, v22
	v_exp_f32_e32 v23, v23
	v_pk_mul_f32 v[16:17], v[36:37], v[16:17] op_sel_hi:[0,1]
	v_pk_mul_f32 v[16:17], v[16:17], v[20:21]
	v_pk_add_f32 v[20:21], v[20:21], -1.0 op_sel_hi:[1,0]
	v_add_f32_e32 v22, 1.0, v22
	v_pk_fma_f32 v[20:21], v[32:33], v[20:21], 1.0 op_sel_hi:[1,1,0]
	v_cvt_f32_f16_sdwa v33, v49 dst_sel:DWORD dst_unused:UNUSED_PAD src0_sel:WORD_1
	v_cvt_f32_f16_e32 v32, v49
	v_add_f32_e32 v23, 1.0, v23
	v_rcp_f32_e32 v22, v22
	v_rcp_f32_e32 v23, v23
	v_pk_mul_f32 v[18:19], v[18:19], v[32:33] neg_lo:[0,1] neg_hi:[0,1]
	v_pk_mul_f32 v[20:21], v[20:21], v[44:45]
	v_pk_mul_f32 v[18:19], v[36:37], v[18:19] op_sel_hi:[0,1]
	v_pk_mul_f32 v[18:19], v[18:19], v[22:23]
	v_pk_add_f32 v[22:23], v[22:23], -1.0 op_sel_hi:[1,0]
	v_cvt_pk_f16_f32 v20, v20, v21
	v_pk_fma_f32 v[22:23], v[34:35], v[22:23], 1.0 op_sel_hi:[1,1,0]
	v_cvt_pk_f16_f32 v16, v16, v17
	v_pk_mul_f32 v[22:23], v[22:23], v[32:33]
	v_cvt_pk_f16_f32 v17, v18, v19
	v_cvt_pk_f16_f32 v21, v22, v23
	v_mov_b32_e32 v224, v20
	v_mov_b32_e32 v225, v21
	s_nop 1
	v_permlane32_swap_b32_e32 v222, v224
	v_permlane32_swap_b32_e32 v223, v225
	global_store_dwordx4 v[238:239], v[222:225], off offset:128
	v_mov_b32_e32 v228, v16
	v_mov_b32_e32 v229, v17
	s_nop 1
	v_permlane32_swap_b32_e32 v226, v228
	v_permlane32_swap_b32_e32 v227, v229
	global_store_dwordx4 v[238:239], v[226:229], off offset:256
	global_load_dwordx2 v[44:45], v[40:41], off offset:160
	s_nop 0
	global_load_dwordx4 v[16:19], v[76:77], off offset:64
	global_load_dwordx4 v[20:23], v[42:43], off offset:64
	global_load_dwordx4 v[32:35], v[38:39], off offset:64
	s_waitcnt vmcnt(0)
; __device__ __forceinline__ float h_lo(unsigned u) { f16x2_t r = __builtin_bit_cast(f16x2_t, u); return (float)r.x; }
; __device__ __forceinline__ float h_hi(unsigned u) { f16x2_t r = __builtin_bit_cast(f16x2_t, u); return (float)r.y; }
; __device__ __forceinline__ float sigm(float x) { return __builtin_amdgcn_rcpf(1.f + __builtin_amdgcn_exp2f(-LOG2E * x)); }
; __device__ __forceinline__ void epi_adir(const f32x16 (&acc)[2][2], int nbase, int tbase, int M, CP& p, int dir) {
;     ...
;     if (valid) {
; #pragma unroll
;       for (int nb = 0; nb < 2; ++nb)
; #pragma unroll
;         for (int i = 0; i < 4; ++i) {
;           const int c = nb * 32 + 8 * i + 4 * h;
;           const u32x2 kr = *(const u32x2*)(DIR + rec + 64 + c);
;           const float kv[4] = {h_lo(kr.x), h_hi(kr.x), h_lo(kr.y), h_hi(kr.y)};
;           const f32x4 kkw = *(const f32x4*)(p.k_k + nbase + c);
;           const f32x4 kaw = *(const f32x4*)(p.k_a + nbase + c);
;           const f32x4 a0v = *(const f32x4*)(a0 + nbase + c);
;           float kk[4], kd[4], bp[4];
; #pragma unroll
;           for (int j = 0; j < 4; ++j) {
;             const float k = kv[j];
;             kk[j] = k * kkw[j] * inv;
;             const float aa = sigm(a0v[j] + acc[nb][tb][4 * i + j]);
;             kd[j] = k * (1.f + (aa - 1.f) * kaw[j]);
;             bp[j] = -kk[j] * aa;
;           }
;           if (dir == 0) *(u32x2*)(p.RKV + rec + 64 + c) = (u32x2){pk_f16(kk[0], kk[1]), pk_f16(kk[2], kk[3])};
;           *(u32x2*)(DIR + rec + 64 + c) = (u32x2){pk_f16(kd[0], kd[1]), pk_f16(kd[2], kd[3])};
;           *(u32x2*)(DIR + rec + 128 + c) = (u32x2){pk_f16(bp[0], bp[1]), pk_f16(bp[2], bp[3])};
;         }
	v_add_f32_e32 v24, v24, v32
	v_add_f32_e32 v25, v25, v33
	v_mul_f32_e32 v24, 0xbfb8aa3b, v24
	v_mul_f32_e32 v25, 0xbfb8aa3b, v25
	v_exp_f32_e32 v24, v24
	v_exp_f32_e32 v25, v25
	v_cvt_f32_f16_sdwa v33, v44 dst_sel:DWORD dst_unused:UNUSED_PAD src0_sel:WORD_1
	v_cvt_f32_f16_e32 v32, v44
	v_add_f32_e32 v24, 1.0, v24
	v_add_f32_e32 v25, 1.0, v25
	v_rcp_f32_e32 v24, v24
	v_rcp_f32_e32 v25, v25
	v_pk_mul_f32 v[16:17], v[16:17], v[32:33] neg_lo:[0,1] neg_hi:[0,1]
	s_nop 0
	v_pk_mul_f32 v[16:17], v[36:37], v[16:17] op_sel_hi:[0,1]
	v_pk_mul_f32 v[16:17], v[16:17], v[24:25]
	v_pk_add_f32 v[24:25], v[24:25], -1.0 op_sel_hi:[1,0]
	v_cvt_pk_f16_f32 v16, v16, v17
	v_pk_fma_f32 v[20:21], v[20:21], v[24:25], 1.0 op_sel_hi:[1,1,0]
	v_add_f32_e32 v24, v26, v34
	v_add_f32_e32 v25, v27, v35
	v_mul_f32_e32 v24, 0xbfb8aa3b, v24
	v_mul_f32_e32 v25, 0xbfb8aa3b, v25
	v_exp_f32_e32 v24, v24
	v_exp_f32_e32 v25, v25
	v_cvt_f32_f16_sdwa v27, v45 dst_sel:DWORD dst_unused:UNUSED_PAD src0_sel:WORD_1
	v_cvt_f32_f16_e32 v26, v45
	v_add_f32_e32 v24, 1.0, v24
	v_add_f32_e32 v25, 1.0, v25
	v_rcp_f32_e32 v24, v24
	v_rcp_f32_e32 v25, v25
	v_pk_mul_f32 v[18:19], v[18:19], v[26:27] neg_lo:[0,1] neg_hi:[0,1]
	v_pk_mul_f32 v[20:21], v[20:21], v[32:33]
	v_pk_mul_f32 v[18:19], v[36:37], v[18:19] op_sel_hi:[0,1]
	v_pk_mul_f32 v[18:19], v[18:19], v[24:25]
	v_pk_add_f32 v[24:25], v[24:25], -1.0 op_sel_hi:[1,0]
	v_cvt_pk_f16_f32 v20, v20, v21
	v_pk_fma_f32 v[22:23], v[22:23], v[24:25], 1.0 op_sel_hi:[1,1,0]
	v_cvt_pk_f16_f32 v17, v18, v19
	v_pk_mul_f32 v[22:23], v[22:23], v[26:27]
	v_mov_b32_e32 v230, v16
	v_mov_b32_e32 v231, v17
	v_cvt_pk_f16_f32 v21, v22, v23
	v_mov_b32_e32 v234, v20
	v_mov_b32_e32 v235, v21
	global_load_dwordx2 v[24:25], v[40:41], off offset:176
	s_nop 0
	global_load_dwordx4 v[20:23], v[76:77], off offset:96
	global_load_dwordx4 v[16:19], v[42:43], off offset:96
	global_load_dwordx4 v[32:35], v[38:39], off offset:96
	s_waitcnt vmcnt(0)
	v_add_f32_e32 v26, v28, v32
	v_add_f32_e32 v27, v29, v33
	v_mul_f32_e32 v26, 0xbfb8aa3b, v26
	v_mul_f32_e32 v27, 0xbfb8aa3b, v27
	v_exp_f32_e32 v26, v26
	v_exp_f32_e32 v27, v27
	v_cvt_f32_f16_sdwa v29, v24 dst_sel:DWORD dst_unused:UNUSED_PAD src0_sel:WORD_1
	v_cvt_f32_f16_e32 v28, v24
	v_add_f32_e32 v24, v30, v34
	v_add_f32_e32 v26, 1.0, v26
	v_add_f32_e32 v27, 1.0, v27
	v_mul_f32_e32 v24, 0xbfb8aa3b, v24
	v_rcp_f32_e32 v26, v26
	v_rcp_f32_e32 v27, v27
	v_exp_f32_e32 v24, v24
	v_pk_mul_f32 v[20:21], v[20:21], v[28:29] neg_lo:[0,1] neg_hi:[0,1]
	v_add_f32_e32 v24, 1.0, v24
	v_pk_mul_f32 v[20:21], v[36:37], v[20:21] op_sel_hi:[0,1]
	v_pk_mul_f32 v[20:21], v[20:21], v[26:27]
	v_pk_add_f32 v[26:27], v[26:27], -1.0 op_sel_hi:[1,0]
	s_nop 0
	v_pk_fma_f32 v[16:17], v[16:17], v[26:27], 1.0 op_sel_hi:[1,1,0]
	v_rcp_f32_e32 v26, v24
	v_add_f32_e32 v24, v31, v35
	v_mul_f32_e32 v24, 0xbfb8aa3b, v24
	v_exp_f32_e32 v24, v24
	v_pk_mul_f32 v[16:17], v[16:17], v[28:29]
	v_cvt_f32_f16_sdwa v29, v25 dst_sel:DWORD dst_unused:UNUSED_PAD src0_sel:WORD_1
	v_cvt_f32_f16_e32 v28, v25
	v_add_f32_e32 v24, 1.0, v24
	v_rcp_f32_e32 v27, v24
	v_cvt_pk_f16_f32 v16, v16, v17
	v_pk_mul_f32 v[22:23], v[22:23], v[28:29] neg_lo:[0,1] neg_hi:[0,1]
	v_pk_add_f32 v[24:25], v[26:27], -1.0 op_sel_hi:[1,0]
	s_nop 0
	v_pk_fma_f32 v[18:19], v[18:19], v[24:25], 1.0 op_sel_hi:[1,1,0]
	v_pk_mul_f32 v[22:23], v[36:37], v[22:23] op_sel_hi:[0,1]
	v_pk_mul_f32 v[18:19], v[18:19], v[28:29]
	v_pk_mul_f32 v[22:23], v[22:23], v[26:27]
	v_cvt_pk_f16_f32 v17, v18, v19
	v_mov_b32_e32 v236, v16
	v_mov_b32_e32 v237, v17
	s_nop 1
	v_permlane32_swap_b32_e32 v234, v236
	v_permlane32_swap_b32_e32 v235, v237
	global_store_dwordx4 v[238:239], v[234:237], off offset:160
	v_cvt_pk_f16_f32 v16, v20, v21
	v_cvt_pk_f16_f32 v17, v22, v23
	v_mov_b32_e32 v232, v16
	v_mov_b32_e32 v233, v17
	s_nop 1
	v_permlane32_swap_b32_e32 v230, v232
	v_permlane32_swap_b32_e32 v231, v233
	global_store_dwordx4 v[238:239], v[230:233], off offset:288
	global_load_dwordx2 v[28:29], v[40:41], off offset:192
	s_nop 0
	global_load_dwordx4 v[16:19], v[76:77], off offset:128
	global_load_dwordx4 v[20:23], v[42:43], off offset:128
	global_load_dwordx4 v[24:27], v[38:39], off offset:128
	s_waitcnt vmcnt(0)
	v_add_f32_e32 v0, v0, v24
	v_add_f32_e32 v1, v1, v25
	v_mul_f32_e32 v0, 0xbfb8aa3b, v0
	v_mul_f32_e32 v1, 0xbfb8aa3b, v1
	v_exp_f32_e32 v0, v0
	v_exp_f32_e32 v1, v1
	v_cvt_f32_f16_sdwa v25, v28 dst_sel:DWORD dst_unused:UNUSED_PAD src0_sel:WORD_1
	v_cvt_f32_f16_e32 v24, v28
	v_add_f32_e32 v0, 1.0, v0
	v_add_f32_e32 v1, 1.0, v1
	v_rcp_f32_e32 v0, v0
	v_rcp_f32_e32 v1, v1
	v_add_f32_e32 v2, v2, v26
	v_add_f32_e32 v3, v3, v27
	v_mul_f32_e32 v2, 0xbfb8aa3b, v2
	v_mul_f32_e32 v3, 0xbfb8aa3b, v3
	v_pk_mul_f32 v[16:17], v[16:17], v[24:25] neg_lo:[0,1] neg_hi:[0,1]
	v_exp_f32_e32 v2, v2
	v_exp_f32_e32 v3, v3
	v_pk_mul_f32 v[16:17], v[36:37], v[16:17] op_sel_hi:[0,1]
	v_pk_mul_f32 v[16:17], v[16:17], v[0:1]
	v_pk_add_f32 v[0:1], v[0:1], -1.0 op_sel_hi:[1,0]
	v_add_f32_e32 v2, 1.0, v2
	v_pk_fma_f32 v[0:1], v[20:21], v[0:1], 1.0 op_sel_hi:[1,1,0]
	v_cvt_f32_f16_sdwa v21, v29 dst_sel:DWORD dst_unused:UNUSED_PAD src0_sel:WORD_1
	v_cvt_f32_f16_e32 v20, v29
	v_add_f32_e32 v3, 1.0, v3
	v_rcp_f32_e32 v2, v2
	v_rcp_f32_e32 v3, v3
	v_pk_mul_f32 v[18:19], v[18:19], v[20:21] neg_lo:[0,1] neg_hi:[0,1]
	v_pk_mul_f32 v[0:1], v[0:1], v[24:25]
	v_pk_mul_f32 v[18:19], v[36:37], v[18:19] op_sel_hi:[0,1]
	v_pk_mul_f32 v[18:19], v[18:19], v[2:3]
	v_pk_add_f32 v[2:3], v[2:3], -1.0 op_sel_hi:[1,0]
	v_cvt_pk_f16_f32 v0, v0, v1
	v_pk_fma_f32 v[2:3], v[22:23], v[2:3], 1.0 op_sel_hi:[1,1,0]
	s_nop 0
	v_pk_mul_f32 v[2:3], v[2:3], v[20:21]
	s_nop 0
	v_cvt_pk_f16_f32 v1, v2, v3
	v_mov_b32_e32 v242, v0
	v_mov_b32_e32 v243, v1
	v_cvt_pk_f16_f32 v0, v16, v17
	v_cvt_pk_f16_f32 v1, v18, v19
	v_mov_b32_e32 v246, v0
	v_mov_b32_e32 v247, v1
	global_load_dwordx2 v[24:25], v[40:41], off offset:208
	s_nop 0
	global_load_dwordx4 v[0:3], v[76:77], off offset:160
	global_load_dwordx4 v[16:19], v[42:43], off offset:160
	global_load_dwordx4 v[20:23], v[38:39], off offset:160
	s_waitcnt vmcnt(0)
; __device__ __forceinline__ float h_lo(unsigned u) { f16x2_t r = __builtin_bit_cast(f16x2_t, u); return (float)r.x; }
; __device__ __forceinline__ float h_hi(unsigned u) { f16x2_t r = __builtin_bit_cast(f16x2_t, u); return (float)r.y; }
; __device__ __forceinline__ float sigm(float x) { return __builtin_amdgcn_rcpf(1.f + __builtin_amdgcn_exp2f(-LOG2E * x)); }
; __device__ __forceinline__ void epi_adir(const f32x16 (&acc)[2][2], int nbase, int tbase, int M, CP& p, int dir) {
;     ...
;     if (valid) {
; #pragma unroll
;       for (int nb = 0; nb < 2; ++nb)
; #pragma unroll
;         for (int i = 0; i < 4; ++i) {
;           const int c = nb * 32 + 8 * i + 4 * h;
;           const u32x2 kr = *(const u32x2*)(DIR + rec + 64 + c);
;           const float kv[4] = {h_lo(kr.x), h_hi(kr.x), h_lo(kr.y), h_hi(kr.y)};
;           const f32x4 kkw = *(const f32x4*)(p.k_k + nbase + c);
;           const f32x4 kaw = *(const f32x4*)(p.k_a + nbase + c);
;           const f32x4 a0v = *(const f32x4*)(a0 + nbase + c);
;           float kk[4], kd[4], bp[4];
; #pragma unroll
;           for (int j = 0; j < 4; ++j) {
;             const float k = kv[j];
;             kk[j] = k * kkw[j] * inv;
;             const float aa = sigm(a0v[j] + acc[nb][tb][4 * i + j]);
;             kd[j] = k * (1.f + (aa - 1.f) * kaw[j]);
;             bp[j] = -kk[j] * aa;
;           }
;           if (dir == 0) *(u32x2*)(p.RKV + rec + 64 + c) = (u32x2){pk_f16(kk[0], kk[1]), pk_f16(kk[2], kk[3])};
;           *(u32x2*)(DIR + rec + 64 + c) = (u32x2){pk_f16(kd[0], kd[1]), pk_f16(kd[2], kd[3])};
;           *(u32x2*)(DIR + rec + 128 + c) = (u32x2){pk_f16(bp[0], bp[1]), pk_f16(bp[2], bp[3])};
;         }
	v_add_f32_e32 v4, v4, v20
	v_add_f32_e32 v5, v5, v21
	v_mul_f32_e32 v4, 0xbfb8aa3b, v4
	v_mul_f32_e32 v5, 0xbfb8aa3b, v5
	v_exp_f32_e32 v4, v4
	v_exp_f32_e32 v5, v5
	v_cvt_f32_f16_sdwa v21, v24 dst_sel:DWORD dst_unused:UNUSED_PAD src0_sel:WORD_1
	v_cvt_f32_f16_e32 v20, v24
	v_add_f32_e32 v4, 1.0, v4
	v_add_f32_e32 v5, 1.0, v5
	v_rcp_f32_e32 v4, v4
	v_rcp_f32_e32 v5, v5
	v_add_f32_e32 v6, v6, v22
	v_add_f32_e32 v7, v7, v23
	v_mul_f32_e32 v6, 0xbfb8aa3b, v6
	v_mul_f32_e32 v7, 0xbfb8aa3b, v7
	v_pk_mul_f32 v[0:1], v[0:1], v[20:21] neg_lo:[0,1] neg_hi:[0,1]
	v_exp_f32_e32 v6, v6
	v_exp_f32_e32 v7, v7
	v_pk_mul_f32 v[0:1], v[36:37], v[0:1] op_sel_hi:[0,1]
	v_pk_mul_f32 v[0:1], v[0:1], v[4:5]
	v_pk_add_f32 v[4:5], v[4:5], -1.0 op_sel_hi:[1,0]
	v_add_f32_e32 v6, 1.0, v6
	v_pk_fma_f32 v[4:5], v[16:17], v[4:5], 1.0 op_sel_hi:[1,1,0]
	v_cvt_f32_f16_sdwa v17, v25 dst_sel:DWORD dst_unused:UNUSED_PAD src0_sel:WORD_1
	v_cvt_f32_f16_e32 v16, v25
	v_add_f32_e32 v7, 1.0, v7
	v_rcp_f32_e32 v6, v6
	v_rcp_f32_e32 v7, v7
	v_pk_mul_f32 v[2:3], v[2:3], v[16:17] neg_lo:[0,1] neg_hi:[0,1]
	v_pk_mul_f32 v[4:5], v[4:5], v[20:21]
	v_pk_mul_f32 v[2:3], v[36:37], v[2:3] op_sel_hi:[0,1]
	v_pk_mul_f32 v[2:3], v[2:3], v[6:7]
	v_pk_add_f32 v[6:7], v[6:7], -1.0 op_sel_hi:[1,0]
	v_cvt_pk_f16_f32 v4, v4, v5
	v_pk_fma_f32 v[6:7], v[18:19], v[6:7], 1.0 op_sel_hi:[1,1,0]
	v_cvt_pk_f16_f32 v0, v0, v1
	v_pk_mul_f32 v[6:7], v[6:7], v[16:17]
	v_cvt_pk_f16_f32 v1, v2, v3
	v_cvt_pk_f16_f32 v5, v6, v7
	v_mov_b32_e32 v244, v4
	v_mov_b32_e32 v245, v5
	s_nop 1
	v_permlane32_swap_b32_e32 v242, v244
	v_permlane32_swap_b32_e32 v243, v245
	global_store_dwordx4 v[238:239], v[242:245], off offset:192
	v_mov_b32_e32 v248, v0
	v_mov_b32_e32 v249, v1
	s_nop 1
	v_permlane32_swap_b32_e32 v246, v248
	v_permlane32_swap_b32_e32 v247, v249
	global_store_dwordx4 v[238:239], v[246:249], off offset:320
	global_load_dwordx2 v[20:21], v[40:41], off offset:224
	s_nop 0
	global_load_dwordx4 v[0:3], v[76:77], off offset:192
	global_load_dwordx4 v[4:7], v[42:43], off offset:192
	global_load_dwordx4 v[16:19], v[38:39], off offset:192
	s_waitcnt vmcnt(0)
	v_add_f32_e32 v8, v8, v16
	v_add_f32_e32 v9, v9, v17
	v_mul_f32_e32 v8, 0xbfb8aa3b, v8
	v_mul_f32_e32 v9, 0xbfb8aa3b, v9
	v_exp_f32_e32 v8, v8
	v_exp_f32_e32 v9, v9
	v_cvt_f32_f16_sdwa v17, v20 dst_sel:DWORD dst_unused:UNUSED_PAD src0_sel:WORD_1
	v_cvt_f32_f16_e32 v16, v20
	v_add_f32_e32 v8, 1.0, v8
	v_add_f32_e32 v9, 1.0, v9
	v_rcp_f32_e32 v8, v8
	v_rcp_f32_e32 v9, v9
	v_pk_mul_f32 v[0:1], v[0:1], v[16:17] neg_lo:[0,1] neg_hi:[0,1]
	s_nop 0
	v_pk_mul_f32 v[0:1], v[36:37], v[0:1] op_sel_hi:[0,1]
	v_pk_mul_f32 v[0:1], v[0:1], v[8:9]
	v_pk_add_f32 v[8:9], v[8:9], -1.0 op_sel_hi:[1,0]
	v_cvt_pk_f16_f32 v0, v0, v1
	v_pk_fma_f32 v[4:5], v[4:5], v[8:9], 1.0 op_sel_hi:[1,1,0]
	v_add_f32_e32 v8, v10, v18
	v_add_f32_e32 v9, v11, v19
	v_mul_f32_e32 v8, 0xbfb8aa3b, v8
	v_mul_f32_e32 v9, 0xbfb8aa3b, v9
	v_exp_f32_e32 v8, v8
	v_exp_f32_e32 v9, v9
	v_cvt_f32_f16_sdwa v11, v21 dst_sel:DWORD dst_unused:UNUSED_PAD src0_sel:WORD_1
	v_cvt_f32_f16_e32 v10, v21
	v_add_f32_e32 v8, 1.0, v8
	v_add_f32_e32 v9, 1.0, v9
	v_rcp_f32_e32 v8, v8
	v_rcp_f32_e32 v9, v9
	v_pk_mul_f32 v[2:3], v[2:3], v[10:11] neg_lo:[0,1] neg_hi:[0,1]
	v_pk_mul_f32 v[4:5], v[4:5], v[16:17]
	v_pk_mul_f32 v[2:3], v[36:37], v[2:3] op_sel_hi:[0,1]
	v_pk_mul_f32 v[2:3], v[2:3], v[8:9]
	v_pk_add_f32 v[8:9], v[8:9], -1.0 op_sel_hi:[1,0]
	v_cvt_pk_f16_f32 v4, v4, v5
	v_pk_fma_f32 v[6:7], v[6:7], v[8:9], 1.0 op_sel_hi:[1,1,0]
	v_cvt_pk_f16_f32 v1, v2, v3
	v_pk_mul_f32 v[6:7], v[6:7], v[10:11]
	v_mov_b32_e32 v222, v0
	v_mov_b32_e32 v223, v1
	v_cvt_pk_f16_f32 v5, v6, v7
	v_mov_b32_e32 v226, v4
	v_mov_b32_e32 v227, v5
	global_load_dwordx2 v[8:9], v[40:41], off offset:240
	s_nop 0
	global_load_dwordx4 v[4:7], v[76:77], off offset:224
	global_load_dwordx4 v[0:3], v[42:43], off offset:224
	global_load_dwordx4 v[16:19], v[38:39], off offset:224
	s_waitcnt vmcnt(0)
	v_add_f32_e32 v10, v12, v16
	v_add_f32_e32 v11, v13, v17
	v_mul_f32_e32 v10, 0xbfb8aa3b, v10
	v_mul_f32_e32 v11, 0xbfb8aa3b, v11
	v_exp_f32_e32 v10, v10
	v_exp_f32_e32 v11, v11
	v_cvt_f32_f16_sdwa v13, v8 dst_sel:DWORD dst_unused:UNUSED_PAD src0_sel:WORD_1
	v_cvt_f32_f16_e32 v12, v8
	v_add_f32_e32 v8, v14, v18
	v_add_f32_e32 v10, 1.0, v10
	v_add_f32_e32 v11, 1.0, v11
	v_mul_f32_e32 v8, 0xbfb8aa3b, v8
	v_rcp_f32_e32 v10, v10
	v_rcp_f32_e32 v11, v11
	v_exp_f32_e32 v8, v8
	v_pk_mul_f32 v[4:5], v[4:5], v[12:13] neg_lo:[0,1] neg_hi:[0,1]
	v_add_f32_e32 v8, 1.0, v8
	v_pk_mul_f32 v[4:5], v[36:37], v[4:5] op_sel_hi:[0,1]
	v_pk_mul_f32 v[4:5], v[4:5], v[10:11]
	v_pk_add_f32 v[10:11], v[10:11], -1.0 op_sel_hi:[1,0]
	s_nop 0
	v_pk_fma_f32 v[0:1], v[0:1], v[10:11], 1.0 op_sel_hi:[1,1,0]
	v_rcp_f32_e32 v10, v8
	v_add_f32_e32 v8, v15, v19
	v_mul_f32_e32 v8, 0xbfb8aa3b, v8
	v_exp_f32_e32 v8, v8
	v_pk_mul_f32 v[0:1], v[0:1], v[12:13]
	v_cvt_f32_f16_sdwa v13, v9 dst_sel:DWORD dst_unused:UNUSED_PAD src0_sel:WORD_1
	v_cvt_f32_f16_e32 v12, v9
	v_add_f32_e32 v8, 1.0, v8
	v_rcp_f32_e32 v11, v8
	v_cvt_pk_f16_f32 v0, v0, v1
	v_pk_mul_f32 v[6:7], v[6:7], v[12:13] neg_lo:[0,1] neg_hi:[0,1]
	v_pk_add_f32 v[8:9], v[10:11], -1.0 op_sel_hi:[1,0]
	s_nop 0
	v_pk_fma_f32 v[2:3], v[2:3], v[8:9], 1.0 op_sel_hi:[1,1,0]
	v_pk_mul_f32 v[6:7], v[36:37], v[6:7] op_sel_hi:[0,1]
	v_pk_mul_f32 v[2:3], v[2:3], v[12:13]
	v_pk_mul_f32 v[6:7], v[6:7], v[10:11]
	v_cvt_pk_f16_f32 v1, v2, v3
	v_mov_b32_e32 v228, v0
	v_mov_b32_e32 v229, v1
	s_nop 1
	v_permlane32_swap_b32_e32 v226, v228
	v_permlane32_swap_b32_e32 v227, v229
	global_store_dwordx4 v[238:239], v[226:229], off offset:224
	v_cvt_pk_f16_f32 v0, v4, v5
	v_cvt_pk_f16_f32 v1, v6, v7
	v_mov_b32_e32 v224, v0
	v_mov_b32_e32 v225, v1
	s_nop 1
	v_permlane32_swap_b32_e32 v222, v224
	v_permlane32_swap_b32_e32 v223, v225
	global_store_dwordx4 v[238:239], v[222:225], off offset:352
	s_branch .LBB0_510

; __device__ __forceinline__ int ltid() { int t = threadIdx.x; asm volatile("" : "+v"(t)); return t; }
; __device__ void run_phase(CP& p, int ph, char* lds) {
;     ...
;       gemm_phase(p.F + 256, 384, Mall, p.G2T, 128, 1024, lds, gctr + 32, [&](const f32x16 (&acc)[2][2], int nbase, int tbase) {
;         const int lane = ltid() & 63, l32 = lane & 31, h = lane >> 5;
; #pragma unroll
;         for (int tb = 0; tb < 2; ++tb) {
;           const int tok = tbase + tb * 32 + l32;
;           if (tok < Mall) {
;             u16* dst = p.G + (size_t)tok * 1024 + nbase + 4 * h;
; #pragma unroll
;             for (int nb = 0; nb < 2; ++nb)
; #pragma unroll
;               for (int i = 0; i < 4; ++i)
;                 *(u32x2*)(dst + nb * 32 + 8 * i) = (u32x2){pk_bf16(acc[nb][tb][4 * i], acc[nb][tb][4 * i + 1]), pk_bf16(acc[nb][tb][4 * i + 2], acc[nb][tb][4 * i + 3])};
;           }
;         }
;       });
.LBB0_534:
	s_or_b64 exec, exec, s[6:7]
	v_mov_b32_e32 v79, v204
	v_lshl_add_u32 v77, v77, 7, v80
	v_lshl_or_b32 v76, v76, 7, v87
	v_and_or_b32 v78, v79, 31, v77
	v_lshrrev_b32_e32 v79, 3, v79
	v_and_b32_e32 v79, 4, v79
	v_ashrrev_i32_e32 v77, 31, v76
	v_cmp_gt_i32_e64 s[40:41], s72, v78
	v_lshlrev_b32_e32 v160, 1, v79
	s_and_saveexec_b64 s[6:7], s[40:41]
	s_cbranch_execz .LBB0_536
	v_ashrrev_i32_e32 v79, 31, v78
	v_lshlrev_b64 v[90:91], 11, v[78:79]
	v_lshl_add_u64 v[90:91], s[42:43], 0, v[90:91]
	v_lshl_add_u64 v[90:91], v[76:77], 1, v[90:91]
	v_lshl_add_u64 v[90:91], v[90:91], 0, v[160:161]
	v_cvt_pk_bf16_f32 v32, v32, v33
	v_cvt_pk_bf16_f32 v33, v34, v35
	v_mbcnt_lo_u32_b32 v238, -1, 0
	v_mbcnt_hi_u32_b32 v238, -1, v238
	v_lshrrev_b32_e32 v238, 2, v238
	v_and_b32_e32 v238, 8, v238
	v_mov_b32_e32 v239, 0
	v_lshl_add_u64 v[238:239], v[90:91], 0, v[238:239]
	v_mov_b32_e32 v230, v32
	v_mov_b32_e32 v231, v33
	v_cvt_pk_bf16_f32 v32, v36, v37
	v_cvt_pk_bf16_f32 v33, v38, v39
	v_mov_b32_e32 v232, v32
	v_mov_b32_e32 v233, v33
	s_nop 1
	v_permlane32_swap_b32_e32 v230, v232
	v_permlane32_swap_b32_e32 v231, v233
	global_store_dwordx4 v[238:239], v[230:233], off
	v_cvt_pk_bf16_f32 v32, v40, v41
	v_cvt_pk_bf16_f32 v33, v42, v43
	v_mov_b32_e32 v234, v32
	v_mov_b32_e32 v235, v33
	v_cvt_pk_bf16_f32 v32, v44, v45
	v_cvt_pk_bf16_f32 v33, v46, v47
	v_mov_b32_e32 v236, v32
	v_mov_b32_e32 v237, v33
	s_nop 1
	v_permlane32_swap_b32_e32 v234, v236
	v_permlane32_swap_b32_e32 v235, v237
	global_store_dwordx4 v[238:239], v[234:237], off offset:32
	v_cvt_pk_bf16_f32 v32, v48, v49
	v_cvt_pk_bf16_f32 v33, v50, v51
	v_mov_b32_e32 v242, v32
	v_mov_b32_e32 v243, v33
	v_cvt_pk_bf16_f32 v32, v52, v53
	v_cvt_pk_bf16_f32 v33, v54, v55
	v_mov_b32_e32 v244, v32
	v_mov_b32_e32 v245, v33
	s_nop 1
	v_permlane32_swap_b32_e32 v242, v244
	v_permlane32_swap_b32_e32 v243, v245
	global_store_dwordx4 v[238:239], v[242:245], off offset:64
	v_cvt_pk_bf16_f32 v32, v56, v57
	v_cvt_pk_bf16_f32 v33, v58, v59
	v_mov_b32_e32 v246, v32
	v_mov_b32_e32 v247, v33
	v_cvt_pk_bf16_f32 v32, v60, v61
	v_cvt_pk_bf16_f32 v33, v62, v63
	v_mov_b32_e32 v248, v32
	v_mov_b32_e32 v249, v33
	s_nop 1
	v_permlane32_swap_b32_e32 v246, v248
	v_permlane32_swap_b32_e32 v247, v249
	global_store_dwordx4 v[238:239], v[246:249], off offset:96
.LBB0_536:
	s_or_b64 exec, exec, s[6:7]
	v_or_b32_e32 v32, 32, v78
	v_cmp_gt_i32_e64 s[40:41], s72, v32
	s_and_saveexec_b64 s[6:7], s[40:41]
	s_cbranch_execz .LBB0_527
	v_ashrrev_i32_e32 v33, 31, v32
	v_lshlrev_b64 v[32:33], 11, v[32:33]
	v_lshl_add_u64 v[32:33], s[42:43], 0, v[32:33]
	v_lshl_add_u64 v[32:33], v[76:77], 1, v[32:33]
	v_lshl_add_u64 v[32:33], v[32:33], 0, v[160:161]
	v_cvt_pk_bf16_f32 v16, v16, v17
	v_cvt_pk_bf16_f32 v17, v18, v19
	v_cvt_pk_bf16_f32 v0, v0, v1
	v_cvt_pk_bf16_f32 v1, v2, v3
	v_mbcnt_lo_u32_b32 v238, -1, 0
	v_mbcnt_hi_u32_b32 v238, -1, v238
	v_lshrrev_b32_e32 v238, 2, v238
	v_and_b32_e32 v238, 8, v238
	v_mov_b32_e32 v239, 0
	v_lshl_add_u64 v[238:239], v[32:33], 0, v[238:239]
	v_mov_b32_e32 v222, v16
	v_mov_b32_e32 v223, v17
	v_cvt_pk_bf16_f32 v16, v20, v21
	v_cvt_pk_bf16_f32 v17, v22, v23
	v_mov_b32_e32 v226, v0
	v_mov_b32_e32 v227, v1
	v_cvt_pk_bf16_f32 v0, v4, v5
	v_cvt_pk_bf16_f32 v1, v6, v7
	v_mov_b32_e32 v224, v16
	v_mov_b32_e32 v225, v17
	s_nop 1
	v_permlane32_swap_b32_e32 v222, v224
	v_permlane32_swap_b32_e32 v223, v225
	global_store_dwordx4 v[238:239], v[222:225], off
	v_cvt_pk_bf16_f32 v16, v24, v25
	v_cvt_pk_bf16_f32 v17, v26, v27
	v_mov_b32_e32 v228, v0
	v_mov_b32_e32 v229, v1
	s_nop 1
	v_permlane32_swap_b32_e32 v226, v228
	v_permlane32_swap_b32_e32 v227, v229
	global_store_dwordx4 v[238:239], v[226:229], off offset:64
	v_cvt_pk_bf16_f32 v0, v8, v9
	v_cvt_pk_bf16_f32 v1, v10, v11
	v_mov_b32_e32 v230, v16
	v_mov_b32_e32 v231, v17
	v_cvt_pk_bf16_f32 v16, v28, v29
	v_cvt_pk_bf16_f32 v17, v30, v31
	v_mov_b32_e32 v234, v0
	v_mov_b32_e32 v235, v1
	v_cvt_pk_bf16_f32 v0, v12, v13
	v_cvt_pk_bf16_f32 v1, v14, v15
	v_mov_b32_e32 v232, v16
	v_mov_b32_e32 v233, v17
	s_nop 1
	v_permlane32_swap_b32_e32 v230, v232
	v_permlane32_swap_b32_e32 v231, v233
	global_store_dwordx4 v[238:239], v[230:233], off offset:32
	v_mov_b32_e32 v236, v0
	v_mov_b32_e32 v237, v1
	s_nop 1
	v_permlane32_swap_b32_e32 v234, v236
	v_permlane32_swap_b32_e32 v235, v237
	global_store_dwordx4 v[238:239], v[234:237], off offset:96
	s_branch .LBB0_527
